# back-edge rotation: K-loop counter/address SALU spread into the last MFMA cluster of 12 GEMM mainloops (on top of vt_pair2)
# speedup vs baseline: 1.0040x; 1.0040x over previous
; #define PG8_STAGE(bufoff, gbase, voff) do { _Pragma("unroll") for (int _i = 0; _i < 2; ++_i) \
;         __builtin_amdgcn_global_load_lds((const unsigned*)((const char*)(gbase) + (voff)[_i]), (PG8_LAS unsigned*)(lds + (bufoff) + ldsw + _i * 8192), 16, 0, 0); } while (0)
; #define PG8_LDA(dst, b, h) do { _Pragma("unroll") for (int m = 0; m < 4; ++m) _Pragma("unroll") for (int k = 0; k < 2; ++k) dst[m][k] = *(const PG8_LAS bf16x8*)(lds + PG8_SA(b, h) + aoff + m * 2048 + k * 1024); } while (0)
; #define PG8_LDB(dst, b, h) do { _Pragma("unroll") for (int n = 0; n < 2; ++n) _Pragma("unroll") for (int k = 0; k < 2; ++k) dst[n][k] = *(const PG8_LAS bf16x8*)(lds + PG8_SB(b, h) + boff + n * 2048 + k * 1024); } while (0)
; #define PG8_MMA(ai, bj, At, Bt) do { __builtin_amdgcn_s_setprio(1); _Pragma("unroll") for (int m = 0; m < 4; ++m) _Pragma("unroll") for (int n = 0; n < 2; ++n) _Pragma("unroll") for (int k = 0; k < 2; ++k) \
;         acc[ai][bj][m][n] = __builtin_amdgcn_mfma_f32_16x16x32_bf16(Bt[n][k], At[m][k], acc[ai][bj][m][n], 0, 0, 0); __builtin_amdgcn_s_setprio(0); } while (0)
; #define PG8_WAIT_V(n) asm volatile("s_waitcnt vmcnt(" #n ")" ::: "memory")
; #define PG8_WAIT_L(n) asm volatile("s_waitcnt lgkmcnt(" #n ")" ::: "memory")
; #define PG8_BAR __builtin_amdgcn_s_barrier()
; #define PG8_SCHED __builtin_amdgcn_sched_barrier(0)
; template <class Epi, class Sched>
; __device__ __forceinline__ void gemm_phase(int wid_s, PG8_LAS unsigned char* lds, const Gemm g, const Sched& S, const Epi& E) {
;     ...
;             PG8_LDB(B0, 0, 0); PG8_LDB(B1, 0, 1); PG8_SCHED; PG8_LDA(At, 0, 0); PG8_STAGE(PG8_SA(1, 1), a1 + hstepA, voffA);
;             PG8_WAIT_V(8); PG8_WAIT_L(0); PG8_BAR; PG8_MMA(0, 0, At, B0); PG8_MMA(0, 1, At, B1); PG8_BAR; PG8_SCHED;
;             PG8_LDA(At, 0, 1); PG8_STAGE(PG8_SB(0, 0), b2, voffB); PG8_STAGE(PG8_SB(0, 1), b2 + hstepB, voffB); PG8_STAGE(PG8_SA(0, 0), a2, voffA);
;             PG8_WAIT_V(8); PG8_WAIT_L(0); PG8_BAR; PG8_MMA(1, 0, At, B0); PG8_MMA(1, 1, At, B1); PG8_BAR; PG8_SCHED;
.Lmy_kh0:
	ds_read_b128 v[138:141], v142
	ds_read_b128 v[154:157], v142 offset:1024
	ds_read_b128 v[164:167], v142 offset:2048
	ds_read_b128 v[186:189], v142 offset:3072
	v_add_u32_e32 v142, s35, v158
	ds_read_b128 v[190:193], v142
	ds_read_b128 v[194:197], v142 offset:1024
	ds_read_b128 v[198:201], v142 offset:2048
	ds_read_b128 v[202:205], v142 offset:3072
	v_lshl_add_u64 v[238:239], s[6:7], 0, v[136:137]
	s_add_i32 m0, s18, 0xc000
	ds_read_b128 v[206:209], v162
	ds_read_b128 v[210:213], v162 offset:1024
	ds_read_b128 v[214:217], v162 offset:2048
	ds_read_b128 v[218:221], v162 offset:3072
	ds_read_b128 v[222:225], v162 offset:4096
	ds_read_b128 v[226:229], v162 offset:5120
	ds_read_b128 v[230:233], v162 offset:6144
	ds_read_b128 v[234:237], v162 offset:7168
	global_load_lds_dwordx4 v[238:239], off
	v_lshl_add_u64 v[238:239], s[6:7], 0, v[134:135]
	s_add_i32 m0, s18, 0xe000
	s_nop 0
	global_load_lds_dwordx4 v[238:239], off
	s_waitcnt vmcnt(8)
	s_waitcnt lgkmcnt(0)
	s_barrier
	s_setprio 1
	s_waitcnt lgkmcnt(0)
	v_mfma_f32_16x16x32_bf16 v[120:123], v[138:141], v[206:209], v[120:123]
	v_mfma_f32_16x16x32_bf16 v[124:127], v[164:167], v[206:209], v[124:127]
	v_mfma_f32_16x16x32_bf16 v[108:111], v[138:141], v[214:217], v[108:111]
	v_mfma_f32_16x16x32_bf16 v[104:107], v[164:167], v[214:217], v[104:107]
	v_mfma_f32_16x16x32_bf16 v[92:95], v[138:141], v[222:225], v[92:95]
	v_mfma_f32_16x16x32_bf16 v[88:91], v[164:167], v[222:225], v[88:91]
	v_mfma_f32_16x16x32_bf16 v[76:79], v[138:141], v[230:233], v[76:79]
	v_mfma_f32_16x16x32_bf16 v[72:75], v[164:167], v[230:233], v[72:75]
	v_mfma_f32_16x16x32_bf16 v[120:123], v[154:157], v[210:213], v[120:123]
	v_mfma_f32_16x16x32_bf16 v[124:127], v[186:189], v[210:213], v[124:127]
	v_mfma_f32_16x16x32_bf16 v[108:111], v[154:157], v[218:221], v[108:111]
	v_mfma_f32_16x16x32_bf16 v[104:107], v[186:189], v[218:221], v[104:107]
	v_mfma_f32_16x16x32_bf16 v[92:95], v[154:157], v[226:229], v[92:95]
	v_mfma_f32_16x16x32_bf16 v[88:91], v[186:189], v[226:229], v[88:91]
	v_mfma_f32_16x16x32_bf16 v[76:79], v[154:157], v[234:237], v[76:79]
	v_mfma_f32_16x16x32_bf16 v[72:75], v[186:189], v[234:237], v[72:75]
	s_setprio 0
	s_setprio 1
	v_mfma_f32_16x16x32_bf16 v[116:119], v[190:193], v[206:209], v[116:119]
	v_mfma_f32_16x16x32_bf16 v[112:115], v[198:201], v[206:209], v[112:115]
	v_mfma_f32_16x16x32_bf16 v[100:103], v[190:193], v[214:217], v[100:103]
	v_mfma_f32_16x16x32_bf16 v[96:99], v[198:201], v[214:217], v[96:99]
	v_mfma_f32_16x16x32_bf16 v[84:87], v[190:193], v[222:225], v[84:87]
	v_mfma_f32_16x16x32_bf16 v[80:83], v[198:201], v[222:225], v[80:83]
	v_mfma_f32_16x16x32_bf16 v[68:71], v[190:193], v[230:233], v[68:71]
	v_mfma_f32_16x16x32_bf16 v[64:67], v[198:201], v[230:233], v[64:67]
	v_mfma_f32_16x16x32_bf16 v[116:119], v[194:197], v[210:213], v[116:119]
	v_mfma_f32_16x16x32_bf16 v[112:115], v[202:205], v[210:213], v[112:115]
	v_mfma_f32_16x16x32_bf16 v[100:103], v[194:197], v[218:221], v[100:103]
	v_mfma_f32_16x16x32_bf16 v[96:99], v[202:205], v[218:221], v[96:99]
	v_mfma_f32_16x16x32_bf16 v[84:87], v[194:197], v[226:229], v[84:87]
	v_mfma_f32_16x16x32_bf16 v[80:83], v[202:205], v[226:229], v[80:83]
	v_mfma_f32_16x16x32_bf16 v[68:71], v[194:197], v[234:237], v[68:71]
	v_mfma_f32_16x16x32_bf16 v[64:67], v[202:205], v[234:237], v[64:67]
	s_setprio 0
	s_barrier
	s_add_i32 s50, s50, s53
	v_lshl_add_u64 v[238:239], s[48:49], 0, v[144:145]
	s_mov_b32 m0, s50
	ds_read_b128 v[206:209], v162 offset:16384
	ds_read_b128 v[210:213], v162 offset:17408
	ds_read_b128 v[214:217], v162 offset:18432
	ds_read_b128 v[218:221], v162 offset:19456
	ds_read_b128 v[222:225], v162 offset:20480
	ds_read_b128 v[226:229], v162 offset:21504
	ds_read_b128 v[230:233], v162 offset:22528
	ds_read_b128 v[234:237], v162 offset:23552
	global_load_lds_dwordx4 v[238:239], off
	s_add_i32 m0, s50, 0x2000
	v_lshl_add_u64 v[240:241], s[48:49], 0, v[132:133]
	s_add_u32 s48, s48, s12
	s_addc_u32 s49, s49, s13
	s_add_i32 s35, s35, s53
	global_load_lds_dwordx4 v[240:241], off
	v_lshl_add_u64 v[242:243], s[48:49], 0, v[144:145]
	s_mov_b32 m0, s35
	v_lshl_add_u64 v[244:245], s[48:49], 0, v[132:133]
	global_load_lds_dwordx4 v[242:243], off
	s_add_i32 m0, s35, 0x2000
	v_lshl_add_u64 v[246:247], s[8:9], 0, v[128:129]
	global_load_lds_dwordx4 v[244:245], off
	s_mov_b32 m0, s18
	v_lshl_add_u64 v[248:249], s[8:9], 0, v[130:131]
	global_load_lds_dwordx4 v[246:247], off
	s_mov_b32 m0, s19
	s_nop 0
	global_load_lds_dwordx4 v[248:249], off
	s_waitcnt vmcnt(8)
	s_waitcnt lgkmcnt(0)
	s_barrier
; #define PG8_STAGE(bufoff, gbase, voff) do { _Pragma("unroll") for (int _i = 0; _i < 2; ++_i) \
;         __builtin_amdgcn_global_load_lds((const unsigned*)((const char*)(gbase) + (voff)[_i]), (PG8_LAS unsigned*)(lds + (bufoff) + ldsw + _i * 8192), 16, 0, 0); } while (0)
; #define PG8_LDA(dst, b, h) do { _Pragma("unroll") for (int m = 0; m < 4; ++m) _Pragma("unroll") for (int k = 0; k < 2; ++k) dst[m][k] = *(const PG8_LAS bf16x8*)(lds + PG8_SA(b, h) + aoff + m * 2048 + k * 1024); } while (0)
; #define PG8_LDB(dst, b, h) do { _Pragma("unroll") for (int n = 0; n < 2; ++n) _Pragma("unroll") for (int k = 0; k < 2; ++k) dst[n][k] = *(const PG8_LAS bf16x8*)(lds + PG8_SB(b, h) + boff + n * 2048 + k * 1024); } while (0)
; #define PG8_MMA(ai, bj, At, Bt) do { __builtin_amdgcn_s_setprio(1); _Pragma("unroll") for (int m = 0; m < 4; ++m) _Pragma("unroll") for (int n = 0; n < 2; ++n) _Pragma("unroll") for (int k = 0; k < 2; ++k) \
;         acc[ai][bj][m][n] = __builtin_amdgcn_mfma_f32_16x16x32_bf16(Bt[n][k], At[m][k], acc[ai][bj][m][n], 0, 0, 0); __builtin_amdgcn_s_setprio(0); } while (0)
; #define PG8_WAIT_V(n) asm volatile("s_waitcnt vmcnt(" #n ")" ::: "memory")
; #define PG8_WAIT_L(n) asm volatile("s_waitcnt lgkmcnt(" #n ")" ::: "memory")
; #define PG8_BAR __builtin_amdgcn_s_barrier()
; #define PG8_SCHED __builtin_amdgcn_sched_barrier(0)
; template <class Epi, class Sched>
; __device__ __forceinline__ void gemm_phase(int wid_s, PG8_LAS unsigned char* lds, const Gemm g, const Sched& S, const Epi& E) {
;     ...
;             PG8_WAIT_V(8); PG8_WAIT_L(0); PG8_BAR; PG8_MMA(1, 0, At, B0); PG8_MMA(1, 1, At, B1); PG8_BAR; PG8_SCHED;
;             PG8_LDB(B0, 1, 0); PG8_LDB(B1, 1, 1); PG8_SCHED; PG8_LDA(At, 1, 0); PG8_STAGE(PG8_SA(0, 1), a2 + hstepA, voffA);
;             PG8_WAIT_V(8); PG8_WAIT_L(0); PG8_BAR; PG8_MMA(0, 0, At, B0); PG8_MMA(0, 1, At, B1); PG8_BAR; PG8_SCHED;
	s_setprio 1
	s_waitcnt lgkmcnt(0)
	v_mfma_f32_16x16x32_bf16 v[60:63], v[138:141], v[206:209], v[60:63]
	v_mfma_f32_16x16x32_bf16 v[56:59], v[164:167], v[206:209], v[56:59]
	v_mfma_f32_16x16x32_bf16 v[44:47], v[138:141], v[214:217], v[44:47]
	v_mfma_f32_16x16x32_bf16 v[40:43], v[164:167], v[214:217], v[40:43]
	v_mfma_f32_16x16x32_bf16 v[28:31], v[138:141], v[222:225], v[28:31]
	v_mfma_f32_16x16x32_bf16 v[24:27], v[164:167], v[222:225], v[24:27]
	v_mfma_f32_16x16x32_bf16 v[12:15], v[138:141], v[230:233], v[12:15]
	v_mfma_f32_16x16x32_bf16 v[8:11], v[164:167], v[230:233], v[8:11]
	v_mfma_f32_16x16x32_bf16 v[60:63], v[154:157], v[210:213], v[60:63]
	v_mfma_f32_16x16x32_bf16 v[56:59], v[186:189], v[210:213], v[56:59]
	v_mfma_f32_16x16x32_bf16 v[44:47], v[154:157], v[218:221], v[44:47]
	v_mfma_f32_16x16x32_bf16 v[40:43], v[186:189], v[218:221], v[40:43]
	v_mfma_f32_16x16x32_bf16 v[28:31], v[154:157], v[226:229], v[28:31]
	v_mfma_f32_16x16x32_bf16 v[24:27], v[186:189], v[226:229], v[24:27]
	v_mfma_f32_16x16x32_bf16 v[12:15], v[154:157], v[234:237], v[12:15]
	v_mfma_f32_16x16x32_bf16 v[8:11], v[186:189], v[234:237], v[8:11]
	s_setprio 0
	s_setprio 1
	v_mfma_f32_16x16x32_bf16 v[52:55], v[190:193], v[206:209], v[52:55]
	v_mfma_f32_16x16x32_bf16 v[48:51], v[198:201], v[206:209], v[48:51]
	v_mfma_f32_16x16x32_bf16 v[36:39], v[190:193], v[214:217], v[36:39]
	v_mfma_f32_16x16x32_bf16 v[32:35], v[198:201], v[214:217], v[32:35]
	v_mfma_f32_16x16x32_bf16 v[20:23], v[190:193], v[222:225], v[20:23]
	v_mfma_f32_16x16x32_bf16 v[16:19], v[198:201], v[222:225], v[16:19]
	v_mfma_f32_16x16x32_bf16 v[4:7], v[190:193], v[230:233], v[4:7]
	v_mfma_f32_16x16x32_bf16 v[0:3], v[198:201], v[230:233], v[0:3]
	v_mfma_f32_16x16x32_bf16 v[52:55], v[194:197], v[210:213], v[52:55]
	v_mfma_f32_16x16x32_bf16 v[48:51], v[202:205], v[210:213], v[48:51]
	v_mfma_f32_16x16x32_bf16 v[36:39], v[194:197], v[218:221], v[36:39]
	v_mfma_f32_16x16x32_bf16 v[32:35], v[202:205], v[218:221], v[32:35]
	v_mfma_f32_16x16x32_bf16 v[20:23], v[194:197], v[226:229], v[20:23]
	v_mfma_f32_16x16x32_bf16 v[16:19], v[202:205], v[226:229], v[16:19]
	v_mfma_f32_16x16x32_bf16 v[4:7], v[194:197], v[234:237], v[4:7]
	v_mfma_f32_16x16x32_bf16 v[0:3], v[202:205], v[234:237], v[0:3]
	s_setprio 0
	s_barrier
	s_add_i32 s35, 0, 0x18000
	v_add_u32_e32 v142, s35, v158
	s_add_i32 s48, 0, 0x1c000
	ds_read_b128 v[138:141], v142
	ds_read_b128 v[154:157], v142 offset:1024
	ds_read_b128 v[164:167], v142 offset:2048
	ds_read_b128 v[186:189], v142 offset:3072
	v_add_u32_e32 v142, s48, v158
	ds_read_b128 v[190:193], v142
	ds_read_b128 v[194:197], v142 offset:1024
	ds_read_b128 v[198:201], v142 offset:2048
	ds_read_b128 v[202:205], v142 offset:3072
	s_add_u32 s8, s8, s10
	s_addc_u32 s9, s9, s11
	s_mov_b32 m0, s94
	v_lshl_add_u64 v[250:251], s[8:9], 0, v[128:129]
	ds_read_b128 v[206:209], v162 offset:32768
	ds_read_b128 v[210:213], v162 offset:33792
	ds_read_b128 v[214:217], v162 offset:34816
	ds_read_b128 v[218:221], v162 offset:35840
	ds_read_b128 v[222:225], v162 offset:36864
	ds_read_b128 v[226:229], v162 offset:37888
	ds_read_b128 v[230:233], v162 offset:38912
	ds_read_b128 v[234:237], v162 offset:39936
	global_load_lds_dwordx4 v[250:251], off
	v_lshl_add_u64 v[250:251], s[8:9], 0, v[130:131]
	s_mov_b32 m0, s95
	s_nop 0
	global_load_lds_dwordx4 v[250:251], off
	s_waitcnt vmcnt(8)
	s_waitcnt lgkmcnt(0)
	s_barrier
	s_setprio 1
	s_waitcnt lgkmcnt(0)
	v_mfma_f32_16x16x32_bf16 v[120:123], v[138:141], v[206:209], v[120:123]
	v_mfma_f32_16x16x32_bf16 v[124:127], v[164:167], v[206:209], v[124:127]
	v_mfma_f32_16x16x32_bf16 v[108:111], v[138:141], v[214:217], v[108:111]
	v_mfma_f32_16x16x32_bf16 v[104:107], v[164:167], v[214:217], v[104:107]
	v_mfma_f32_16x16x32_bf16 v[92:95], v[138:141], v[222:225], v[92:95]
	v_mfma_f32_16x16x32_bf16 v[88:91], v[164:167], v[222:225], v[88:91]
	v_mfma_f32_16x16x32_bf16 v[76:79], v[138:141], v[230:233], v[76:79]
	v_mfma_f32_16x16x32_bf16 v[72:75], v[164:167], v[230:233], v[72:75]
	v_mfma_f32_16x16x32_bf16 v[120:123], v[154:157], v[210:213], v[120:123]
	v_mfma_f32_16x16x32_bf16 v[124:127], v[186:189], v[210:213], v[124:127]
	v_mfma_f32_16x16x32_bf16 v[108:111], v[154:157], v[218:221], v[108:111]
	v_mfma_f32_16x16x32_bf16 v[104:107], v[186:189], v[218:221], v[104:107]
	v_mfma_f32_16x16x32_bf16 v[92:95], v[154:157], v[226:229], v[92:95]
	v_mfma_f32_16x16x32_bf16 v[88:91], v[186:189], v[226:229], v[88:91]
	v_mfma_f32_16x16x32_bf16 v[76:79], v[154:157], v[234:237], v[76:79]
	v_mfma_f32_16x16x32_bf16 v[72:75], v[186:189], v[234:237], v[72:75]
	s_setprio 0
	s_setprio 1
	v_mfma_f32_16x16x32_bf16 v[116:119], v[190:193], v[206:209], v[116:119]
	v_mfma_f32_16x16x32_bf16 v[112:115], v[198:201], v[206:209], v[112:115]
	v_mfma_f32_16x16x32_bf16 v[100:103], v[190:193], v[214:217], v[100:103]
	v_mfma_f32_16x16x32_bf16 v[96:99], v[198:201], v[214:217], v[96:99]
	v_mfma_f32_16x16x32_bf16 v[84:87], v[190:193], v[222:225], v[84:87]
	v_mfma_f32_16x16x32_bf16 v[80:83], v[198:201], v[222:225], v[80:83]
	v_mfma_f32_16x16x32_bf16 v[68:71], v[190:193], v[230:233], v[68:71]
	v_mfma_f32_16x16x32_bf16 v[64:67], v[198:201], v[230:233], v[64:67]
	v_mfma_f32_16x16x32_bf16 v[116:119], v[194:197], v[210:213], v[116:119]
	v_mfma_f32_16x16x32_bf16 v[112:115], v[202:205], v[210:213], v[112:115]
	v_mfma_f32_16x16x32_bf16 v[100:103], v[194:197], v[218:221], v[100:103]
	v_mfma_f32_16x16x32_bf16 v[96:99], v[202:205], v[218:221], v[96:99]
	v_mfma_f32_16x16x32_bf16 v[84:87], v[194:197], v[226:229], v[84:87]
	v_mfma_f32_16x16x32_bf16 v[80:83], v[202:205], v[226:229], v[80:83]
	v_mfma_f32_16x16x32_bf16 v[68:71], v[194:197], v[234:237], v[68:71]
	v_mfma_f32_16x16x32_bf16 v[64:67], v[202:205], v[234:237], v[64:67]
	s_setprio 0
	s_barrier
; #define PG8_STAGE(bufoff, gbase, voff) do { _Pragma("unroll") for (int _i = 0; _i < 2; ++_i) \
;         __builtin_amdgcn_global_load_lds((const unsigned*)((const char*)(gbase) + (voff)[_i]), (PG8_LAS unsigned*)(lds + (bufoff) + ldsw + _i * 8192), 16, 0, 0); } while (0)
; #define PG8_LDA(dst, b, h) do { _Pragma("unroll") for (int m = 0; m < 4; ++m) _Pragma("unroll") for (int k = 0; k < 2; ++k) dst[m][k] = *(const PG8_LAS bf16x8*)(lds + PG8_SA(b, h) + aoff + m * 2048 + k * 1024); } while (0)
; #define PG8_MMA(ai, bj, At, Bt) do { __builtin_amdgcn_s_setprio(1); _Pragma("unroll") for (int m = 0; m < 4; ++m) _Pragma("unroll") for (int n = 0; n < 2; ++n) _Pragma("unroll") for (int k = 0; k < 2; ++k) \
;         acc[ai][bj][m][n] = __builtin_amdgcn_mfma_f32_16x16x32_bf16(Bt[n][k], At[m][k], acc[ai][bj][m][n], 0, 0, 0); __builtin_amdgcn_s_setprio(0); } while (0)
; #define PG8_WAIT_V(n) asm volatile("s_waitcnt vmcnt(" #n ")" ::: "memory")
; #define PG8_WAIT_L(n) asm volatile("s_waitcnt lgkmcnt(" #n ")" ::: "memory")
; #define PG8_BAR __builtin_amdgcn_s_barrier()
; #define PG8_SCHED __builtin_amdgcn_sched_barrier(0)
; template <class Epi, class Sched>
; __device__ __forceinline__ void gemm_phase(int wid_s, PG8_LAS unsigned char* lds, const Gemm g, const Sched& S, const Epi& E) {
;     ...
;         for (int t = 0; t < nt; t += 2) {
;             const bool last = (t == nt - 2);
;             const char* a1 = cA + (size_t)(t + 1) * kstep;
;             const char* a2 = last ? nA : cA + (size_t)(t + 2) * kstep; const char* b2 = last ? nB : cB + (size_t)(t + 2) * kstep;
;     ...
;             PG8_LDA(At, 1, 1); PG8_STAGE(PG8_SB(1, 0), b3, voffB); PG8_STAGE(PG8_SB(1, 1), b3 + hstepB, voffB); PG8_STAGE(PG8_SA(1, 0), a3, voffA);
;             PG8_WAIT_V(8); PG8_WAIT_L(0); PG8_BAR; PG8_MMA(1, 0, At, B0); PG8_MMA(1, 1, At, B1); PG8_BAR; PG8_SCHED;
;         }
	s_add_i32 s8, s35, s53
	v_lshl_add_u64 v[238:239], v[238:239], 0, s[96:97]
	s_mov_b32 m0, s8
	ds_read_b128 v[206:209], v162 offset:49152
	ds_read_b128 v[210:213], v162 offset:50176
	ds_read_b128 v[214:217], v162 offset:51200
	ds_read_b128 v[218:221], v162 offset:52224
	ds_read_b128 v[222:225], v162 offset:53248
	ds_read_b128 v[226:229], v162 offset:54272
	ds_read_b128 v[230:233], v162 offset:55296
	ds_read_b128 v[234:237], v162 offset:56320
	global_load_lds_dwordx4 v[238:239], off
	v_lshl_add_u64 v[238:239], v[240:241], 0, s[96:97]
	s_add_i32 m0, s8, 0x2000
	s_add_i32 s8, s48, s53
	global_load_lds_dwordx4 v[238:239], off
	v_lshl_add_u64 v[238:239], v[242:243], 0, s[96:97]
	s_mov_b32 m0, s8
	s_nop 0
	global_load_lds_dwordx4 v[238:239], off
	v_lshl_add_u64 v[238:239], v[244:245], 0, s[96:97]
	s_add_i32 m0, s8, 0x2000
	s_nop 0
	global_load_lds_dwordx4 v[238:239], off
	v_lshl_add_u64 v[238:239], v[246:247], 0, s[96:97]
	s_mov_b32 m0, s40
	s_nop 0
	global_load_lds_dwordx4 v[238:239], off
	v_lshl_add_u64 v[238:239], v[248:249], 0, s[96:97]
	s_mov_b32 m0, s41
	s_nop 0
	global_load_lds_dwordx4 v[238:239], off
	s_waitcnt vmcnt(8)
	s_waitcnt lgkmcnt(0)
	s_barrier
	s_setprio 1
	s_waitcnt lgkmcnt(0)
	v_mfma_f32_16x16x32_bf16 v[60:63], v[138:141], v[206:209], v[60:63]
	v_mfma_f32_16x16x32_bf16 v[56:59], v[164:167], v[206:209], v[56:59]
	v_mfma_f32_16x16x32_bf16 v[44:47], v[138:141], v[214:217], v[44:47]
	v_mfma_f32_16x16x32_bf16 v[40:43], v[164:167], v[214:217], v[40:43]
	v_mfma_f32_16x16x32_bf16 v[28:31], v[138:141], v[222:225], v[28:31]
	v_mfma_f32_16x16x32_bf16 v[24:27], v[164:167], v[222:225], v[24:27]
	v_mfma_f32_16x16x32_bf16 v[12:15], v[138:141], v[230:233], v[12:15]
	v_mfma_f32_16x16x32_bf16 v[8:11], v[164:167], v[230:233], v[8:11]
	v_mfma_f32_16x16x32_bf16 v[60:63], v[154:157], v[210:213], v[60:63]
	v_mfma_f32_16x16x32_bf16 v[56:59], v[186:189], v[210:213], v[56:59]
	v_mfma_f32_16x16x32_bf16 v[44:47], v[154:157], v[218:221], v[44:47]
	v_mfma_f32_16x16x32_bf16 v[40:43], v[186:189], v[218:221], v[40:43]
	v_mfma_f32_16x16x32_bf16 v[28:31], v[154:157], v[226:229], v[28:31]
	v_mfma_f32_16x16x32_bf16 v[24:27], v[186:189], v[226:229], v[24:27]
	v_mfma_f32_16x16x32_bf16 v[12:15], v[154:157], v[234:237], v[12:15]
	v_mfma_f32_16x16x32_bf16 v[8:11], v[186:189], v[234:237], v[8:11]
	s_setprio 0
	s_setprio 1
	v_mfma_f32_16x16x32_bf16 v[52:55], v[190:193], v[206:209], v[52:55]
	s_add_u32 s33, s33, 0x100
	s_addc_u32 s47, s47, 0
	v_mfma_f32_16x16x32_bf16 v[48:51], v[198:201], v[206:209], v[48:51]
	s_add_u32 s6, s6, 0x100
	s_addc_u32 s7, s7, 0
	v_mfma_f32_16x16x32_bf16 v[36:39], v[190:193], v[214:217], v[36:39]
	s_cmp_ge_i32 s34, s37
	s_mov_b32 s8, s34
	s_cbranch_scc1 .Lmy_kx0
	v_mfma_f32_16x16x32_bf16 v[32:35], v[198:201], v[214:217], v[32:35]
	s_add_i32 s34, s8, 2
	v_mfma_f32_16x16x32_bf16 v[20:23], v[190:193], v[222:225], v[20:23]
	s_add_u32 s35, s6, 0x80
	v_mfma_f32_16x16x32_bf16 v[16:19], v[198:201], v[222:225], v[16:19]
	s_addc_u32 s9, s7, 0
	v_mfma_f32_16x16x32_bf16 v[4:7], v[190:193], v[230:233], v[4:7]
	s_add_i32 s50, 0, 0x10000
	v_mfma_f32_16x16x32_bf16 v[0:3], v[198:201], v[230:233], v[0:3]
	s_cmp_eq_u32 s92, s8
	v_mfma_f32_16x16x32_bf16 v[52:55], v[194:197], v[210:213], v[52:55]
	s_cselect_b32 s9, s29, s9
	v_mfma_f32_16x16x32_bf16 v[48:51], v[202:205], v[210:213], v[48:51]
	s_cselect_b32 s8, s28, s35
	v_mfma_f32_16x16x32_bf16 v[36:39], v[194:197], v[218:221], v[36:39]
	v_add_u32_e32 v142, s50, v158
	v_mfma_f32_16x16x32_bf16 v[32:35], v[202:205], v[218:221], v[32:35]
	s_cselect_b32 s49, s31, s47
	v_mfma_f32_16x16x32_bf16 v[20:23], v[194:197], v[226:229], v[20:23]
	s_cselect_b32 s48, s30, s33
	v_mfma_f32_16x16x32_bf16 v[16:19], v[202:205], v[226:229], v[16:19]
	s_add_i32 s35, 0, 0x14000
	v_mfma_f32_16x16x32_bf16 v[4:7], v[194:197], v[234:237], v[4:7]
	v_mfma_f32_16x16x32_bf16 v[0:3], v[202:205], v[234:237], v[0:3]
	s_setprio 0
	s_barrier
	s_branch .Lmy_kh0
.Lmy_kx0:
	v_mfma_f32_16x16x32_bf16 v[32:35], v[198:201], v[214:217], v[32:35]
	v_mfma_f32_16x16x32_bf16 v[20:23], v[190:193], v[222:225], v[20:23]
	v_mfma_f32_16x16x32_bf16 v[16:19], v[198:201], v[222:225], v[16:19]
	v_mfma_f32_16x16x32_bf16 v[4:7], v[190:193], v[230:233], v[4:7]
	v_mfma_f32_16x16x32_bf16 v[0:3], v[198:201], v[230:233], v[0:3]
	v_mfma_f32_16x16x32_bf16 v[52:55], v[194:197], v[210:213], v[52:55]
	v_mfma_f32_16x16x32_bf16 v[48:51], v[202:205], v[210:213], v[48:51]
	v_mfma_f32_16x16x32_bf16 v[36:39], v[194:197], v[218:221], v[36:39]
	v_mfma_f32_16x16x32_bf16 v[32:35], v[202:205], v[218:221], v[32:35]
	v_mfma_f32_16x16x32_bf16 v[20:23], v[194:197], v[226:229], v[20:23]
	v_mfma_f32_16x16x32_bf16 v[16:19], v[202:205], v[226:229], v[16:19]
	v_mfma_f32_16x16x32_bf16 v[4:7], v[194:197], v[234:237], v[4:7]
	v_mfma_f32_16x16x32_bf16 v[0:3], v[202:205], v[234:237], v[0:3]
	s_setprio 0
	s_barrier
	s_movk_i32 s33, 0x300

; #define PG8_STAGE(bufoff, gbase, voff) do { _Pragma("unroll") for (int _i = 0; _i < 2; ++_i) \
;         __builtin_amdgcn_global_load_lds((const unsigned*)((const char*)(gbase) + (voff)[_i]), (PG8_LAS unsigned*)(lds + (bufoff) + ldsw + _i * 8192), 16, 0, 0); } while (0)
; #define PG8_LDA(dst, b, h) do { _Pragma("unroll") for (int m = 0; m < 4; ++m) _Pragma("unroll") for (int k = 0; k < 2; ++k) dst[m][k] = *(const PG8_LAS bf16x8*)(lds + PG8_SA(b, h) + aoff + m * 2048 + k * 1024); } while (0)
; #define PG8_LDB(dst, b, h) do { _Pragma("unroll") for (int n = 0; n < 2; ++n) _Pragma("unroll") for (int k = 0; k < 2; ++k) dst[n][k] = *(const PG8_LAS bf16x8*)(lds + PG8_SB(b, h) + boff + n * 2048 + k * 1024); } while (0)
; #define PG8_MMA(ai, bj, At, Bt) do { __builtin_amdgcn_s_setprio(1); _Pragma("unroll") for (int m = 0; m < 4; ++m) _Pragma("unroll") for (int n = 0; n < 2; ++n) _Pragma("unroll") for (int k = 0; k < 2; ++k) \
;         acc[ai][bj][m][n] = __builtin_amdgcn_mfma_f32_16x16x32_bf16(Bt[n][k], At[m][k], acc[ai][bj][m][n], 0, 0, 0); __builtin_amdgcn_s_setprio(0); } while (0)
; #define PG8_WAIT_V(n) asm volatile("s_waitcnt vmcnt(" #n ")" ::: "memory")
; #define PG8_WAIT_L(n) asm volatile("s_waitcnt lgkmcnt(" #n ")" ::: "memory")
; #define PG8_BAR __builtin_amdgcn_s_barrier()
; #define PG8_SCHED __builtin_amdgcn_sched_barrier(0)
; template <class Epi, class Sched>
; __device__ __forceinline__ void gemm_phase(int wid_s, PG8_LAS unsigned char* lds, const Gemm g, const Sched& S, const Epi& E) {
;     ...
;             PG8_LDB(B0, 0, 0); PG8_LDB(B1, 0, 1); PG8_SCHED; PG8_LDA(At, 0, 0); PG8_STAGE(PG8_SA(1, 1), a1 + hstepA, voffA);
;             PG8_WAIT_V(8); PG8_WAIT_L(0); PG8_BAR; PG8_MMA(0, 0, At, B0); PG8_MMA(0, 1, At, B1); PG8_BAR; PG8_SCHED;
;             PG8_LDA(At, 0, 1); PG8_STAGE(PG8_SB(0, 0), b2, voffB); PG8_STAGE(PG8_SB(0, 1), b2 + hstepB, voffB); PG8_STAGE(PG8_SA(0, 0), a2, voffA);
;             PG8_WAIT_V(8); PG8_WAIT_L(0); PG8_BAR; PG8_MMA(1, 0, At, B0); PG8_MMA(1, 1, At, B1); PG8_BAR; PG8_SCHED;
.Lmy_kh1:
	ds_read_b128 v[154:157], v138
	ds_read_b128 v[158:161], v138 offset:1024
	ds_read_b128 v[162:165], v138 offset:2048
	ds_read_b128 v[186:189], v138 offset:3072
	v_add_u32_e32 v138, s94, v141
	ds_read_b128 v[190:193], v138
	ds_read_b128 v[194:197], v138 offset:1024
	ds_read_b128 v[198:201], v138 offset:2048
	ds_read_b128 v[202:205], v138 offset:3072
	v_lshl_add_u64 v[138:139], s[26:27], 0, v[136:137]
	s_add_i32 m0, s37, 0xc000
	ds_read_b128 v[206:209], v143
	ds_read_b128 v[210:213], v143 offset:1024
	ds_read_b128 v[214:217], v143 offset:2048
	ds_read_b128 v[218:221], v143 offset:3072
	ds_read_b128 v[222:225], v143 offset:4096
	ds_read_b128 v[226:229], v143 offset:5120
	ds_read_b128 v[230:233], v143 offset:6144
	ds_read_b128 v[234:237], v143 offset:7168
	global_load_lds_dwordx4 v[138:139], off
	v_lshl_add_u64 v[138:139], s[26:27], 0, v[134:135]
	s_add_i32 m0, s37, 0xe000
	s_nop 0
	global_load_lds_dwordx4 v[138:139], off
	s_waitcnt vmcnt(8)
	s_waitcnt lgkmcnt(0)
	s_barrier
	s_setprio 1
	s_waitcnt lgkmcnt(0)
	v_mfma_f32_16x16x32_bf16 v[120:123], v[154:157], v[206:209], v[120:123]
	v_mfma_f32_16x16x32_bf16 v[124:127], v[162:165], v[206:209], v[124:127]
	v_mfma_f32_16x16x32_bf16 v[108:111], v[154:157], v[214:217], v[108:111]
	v_mfma_f32_16x16x32_bf16 v[104:107], v[162:165], v[214:217], v[104:107]
	v_mfma_f32_16x16x32_bf16 v[92:95], v[154:157], v[222:225], v[92:95]
	v_mfma_f32_16x16x32_bf16 v[88:91], v[162:165], v[222:225], v[88:91]
	v_mfma_f32_16x16x32_bf16 v[76:79], v[154:157], v[230:233], v[76:79]
	v_mfma_f32_16x16x32_bf16 v[72:75], v[162:165], v[230:233], v[72:75]
	v_mfma_f32_16x16x32_bf16 v[120:123], v[158:161], v[210:213], v[120:123]
	v_mfma_f32_16x16x32_bf16 v[124:127], v[186:189], v[210:213], v[124:127]
	v_mfma_f32_16x16x32_bf16 v[108:111], v[158:161], v[218:221], v[108:111]
	v_mfma_f32_16x16x32_bf16 v[104:107], v[186:189], v[218:221], v[104:107]
	v_mfma_f32_16x16x32_bf16 v[92:95], v[158:161], v[226:229], v[92:95]
	v_mfma_f32_16x16x32_bf16 v[88:91], v[186:189], v[226:229], v[88:91]
	v_mfma_f32_16x16x32_bf16 v[76:79], v[158:161], v[234:237], v[76:79]
	v_mfma_f32_16x16x32_bf16 v[72:75], v[186:189], v[234:237], v[72:75]
	s_setprio 0
	s_setprio 1
	v_mfma_f32_16x16x32_bf16 v[116:119], v[190:193], v[206:209], v[116:119]
	v_mfma_f32_16x16x32_bf16 v[112:115], v[198:201], v[206:209], v[112:115]
	v_mfma_f32_16x16x32_bf16 v[100:103], v[190:193], v[214:217], v[100:103]
	v_mfma_f32_16x16x32_bf16 v[96:99], v[198:201], v[214:217], v[96:99]
	v_mfma_f32_16x16x32_bf16 v[84:87], v[190:193], v[222:225], v[84:87]
	v_mfma_f32_16x16x32_bf16 v[80:83], v[198:201], v[222:225], v[80:83]
	v_mfma_f32_16x16x32_bf16 v[68:71], v[190:193], v[230:233], v[68:71]
	v_mfma_f32_16x16x32_bf16 v[64:67], v[198:201], v[230:233], v[64:67]
	v_mfma_f32_16x16x32_bf16 v[116:119], v[194:197], v[210:213], v[116:119]
	v_mfma_f32_16x16x32_bf16 v[112:115], v[202:205], v[210:213], v[112:115]
	v_mfma_f32_16x16x32_bf16 v[100:103], v[194:197], v[218:221], v[100:103]
	v_mfma_f32_16x16x32_bf16 v[96:99], v[202:205], v[218:221], v[96:99]
	v_mfma_f32_16x16x32_bf16 v[84:87], v[194:197], v[226:229], v[84:87]
	v_mfma_f32_16x16x32_bf16 v[80:83], v[202:205], v[226:229], v[80:83]
	v_mfma_f32_16x16x32_bf16 v[68:71], v[194:197], v[234:237], v[68:71]
	v_mfma_f32_16x16x32_bf16 v[64:67], v[202:205], v[234:237], v[64:67]
	s_setprio 0
	s_barrier
	s_add_i32 s92, s92, s35
	v_lshl_add_u64 v[138:139], s[56:57], 0, v[144:145]
	s_mov_b32 m0, s92
	ds_read_b128 v[206:209], v143 offset:16384
	ds_read_b128 v[210:213], v143 offset:17408
	ds_read_b128 v[214:217], v143 offset:18432
	ds_read_b128 v[218:221], v143 offset:19456
	ds_read_b128 v[222:225], v143 offset:20480
	ds_read_b128 v[226:229], v143 offset:21504
	ds_read_b128 v[230:233], v143 offset:22528
	ds_read_b128 v[234:237], v143 offset:23552
	global_load_lds_dwordx4 v[138:139], off
	s_add_i32 m0, s92, 0x2000
	v_lshl_add_u64 v[166:167], s[56:57], 0, v[128:129]
	s_add_u32 s56, s56, s8
	s_addc_u32 s57, s57, s9
	s_add_i32 s92, s94, s35
	global_load_lds_dwordx4 v[166:167], off
	v_lshl_add_u64 v[238:239], s[56:57], 0, v[144:145]
	s_mov_b32 m0, s92
	v_lshl_add_u64 v[240:241], s[56:57], 0, v[128:129]
	global_load_lds_dwordx4 v[238:239], off
	s_add_i32 m0, s92, 0x2000
	v_lshl_add_u64 v[242:243], s[28:29], 0, v[132:133]
	global_load_lds_dwordx4 v[240:241], off
	s_mov_b32 m0, s37
	v_lshl_add_u64 v[244:245], s[28:29], 0, v[130:131]
	global_load_lds_dwordx4 v[242:243], off
	s_mov_b32 m0, s39
	s_nop 0
	global_load_lds_dwordx4 v[244:245], off
	s_waitcnt vmcnt(8)
	s_waitcnt lgkmcnt(0)
	s_barrier
; #define PG8_STAGE(bufoff, gbase, voff) do { _Pragma("unroll") for (int _i = 0; _i < 2; ++_i) \
;         __builtin_amdgcn_global_load_lds((const unsigned*)((const char*)(gbase) + (voff)[_i]), (PG8_LAS unsigned*)(lds + (bufoff) + ldsw + _i * 8192), 16, 0, 0); } while (0)
; #define PG8_LDA(dst, b, h) do { _Pragma("unroll") for (int m = 0; m < 4; ++m) _Pragma("unroll") for (int k = 0; k < 2; ++k) dst[m][k] = *(const PG8_LAS bf16x8*)(lds + PG8_SA(b, h) + aoff + m * 2048 + k * 1024); } while (0)
; #define PG8_LDB(dst, b, h) do { _Pragma("unroll") for (int n = 0; n < 2; ++n) _Pragma("unroll") for (int k = 0; k < 2; ++k) dst[n][k] = *(const PG8_LAS bf16x8*)(lds + PG8_SB(b, h) + boff + n * 2048 + k * 1024); } while (0)
; #define PG8_MMA(ai, bj, At, Bt) do { __builtin_amdgcn_s_setprio(1); _Pragma("unroll") for (int m = 0; m < 4; ++m) _Pragma("unroll") for (int n = 0; n < 2; ++n) _Pragma("unroll") for (int k = 0; k < 2; ++k) \
;         acc[ai][bj][m][n] = __builtin_amdgcn_mfma_f32_16x16x32_bf16(Bt[n][k], At[m][k], acc[ai][bj][m][n], 0, 0, 0); __builtin_amdgcn_s_setprio(0); } while (0)
; #define PG8_WAIT_V(n) asm volatile("s_waitcnt vmcnt(" #n ")" ::: "memory")
; #define PG8_WAIT_L(n) asm volatile("s_waitcnt lgkmcnt(" #n ")" ::: "memory")
; #define PG8_BAR __builtin_amdgcn_s_barrier()
; #define PG8_SCHED __builtin_amdgcn_sched_barrier(0)
; template <class Epi, class Sched>
; __device__ __forceinline__ void gemm_phase(int wid_s, PG8_LAS unsigned char* lds, const Gemm g, const Sched& S, const Epi& E) {
;     ...
;             PG8_WAIT_V(8); PG8_WAIT_L(0); PG8_BAR; PG8_MMA(1, 0, At, B0); PG8_MMA(1, 1, At, B1); PG8_BAR; PG8_SCHED;
;             PG8_LDB(B0, 1, 0); PG8_LDB(B1, 1, 1); PG8_SCHED; PG8_LDA(At, 1, 0); PG8_STAGE(PG8_SA(0, 1), a2 + hstepA, voffA);
;             PG8_WAIT_V(8); PG8_WAIT_L(0); PG8_BAR; PG8_MMA(0, 0, At, B0); PG8_MMA(0, 1, At, B1); PG8_BAR; PG8_SCHED;
	s_setprio 1
	s_waitcnt lgkmcnt(0)
	v_mfma_f32_16x16x32_bf16 v[60:63], v[154:157], v[206:209], v[60:63]
	v_mfma_f32_16x16x32_bf16 v[56:59], v[162:165], v[206:209], v[56:59]
	v_mfma_f32_16x16x32_bf16 v[44:47], v[154:157], v[214:217], v[44:47]
	v_mfma_f32_16x16x32_bf16 v[40:43], v[162:165], v[214:217], v[40:43]
	v_mfma_f32_16x16x32_bf16 v[28:31], v[154:157], v[222:225], v[28:31]
	v_mfma_f32_16x16x32_bf16 v[24:27], v[162:165], v[222:225], v[24:27]
	v_mfma_f32_16x16x32_bf16 v[12:15], v[154:157], v[230:233], v[12:15]
	v_mfma_f32_16x16x32_bf16 v[8:11], v[162:165], v[230:233], v[8:11]
	v_mfma_f32_16x16x32_bf16 v[60:63], v[158:161], v[210:213], v[60:63]
	v_mfma_f32_16x16x32_bf16 v[56:59], v[186:189], v[210:213], v[56:59]
	v_mfma_f32_16x16x32_bf16 v[44:47], v[158:161], v[218:221], v[44:47]
	v_mfma_f32_16x16x32_bf16 v[40:43], v[186:189], v[218:221], v[40:43]
	v_mfma_f32_16x16x32_bf16 v[28:31], v[158:161], v[226:229], v[28:31]
	v_mfma_f32_16x16x32_bf16 v[24:27], v[186:189], v[226:229], v[24:27]
	v_mfma_f32_16x16x32_bf16 v[12:15], v[158:161], v[234:237], v[12:15]
	v_mfma_f32_16x16x32_bf16 v[8:11], v[186:189], v[234:237], v[8:11]
	s_setprio 0
	s_setprio 1
	v_mfma_f32_16x16x32_bf16 v[52:55], v[190:193], v[206:209], v[52:55]
	v_mfma_f32_16x16x32_bf16 v[48:51], v[198:201], v[206:209], v[48:51]
	v_mfma_f32_16x16x32_bf16 v[36:39], v[190:193], v[214:217], v[36:39]
	v_mfma_f32_16x16x32_bf16 v[32:35], v[198:201], v[214:217], v[32:35]
	v_mfma_f32_16x16x32_bf16 v[20:23], v[190:193], v[222:225], v[20:23]
	v_mfma_f32_16x16x32_bf16 v[16:19], v[198:201], v[222:225], v[16:19]
	v_mfma_f32_16x16x32_bf16 v[4:7], v[190:193], v[230:233], v[4:7]
	v_mfma_f32_16x16x32_bf16 v[0:3], v[198:201], v[230:233], v[0:3]
	v_mfma_f32_16x16x32_bf16 v[52:55], v[194:197], v[210:213], v[52:55]
	v_mfma_f32_16x16x32_bf16 v[48:51], v[202:205], v[210:213], v[48:51]
	v_mfma_f32_16x16x32_bf16 v[36:39], v[194:197], v[218:221], v[36:39]
	v_mfma_f32_16x16x32_bf16 v[32:35], v[202:205], v[218:221], v[32:35]
	v_mfma_f32_16x16x32_bf16 v[20:23], v[194:197], v[226:229], v[20:23]
	v_mfma_f32_16x16x32_bf16 v[16:19], v[202:205], v[226:229], v[16:19]
	v_mfma_f32_16x16x32_bf16 v[4:7], v[194:197], v[234:237], v[4:7]
	v_mfma_f32_16x16x32_bf16 v[0:3], v[202:205], v[234:237], v[0:3]
	s_setprio 0
	s_barrier
	s_add_i32 s56, 0, 0x18000
	v_add_u32_e32 v185, s56, v141
	s_add_i32 s57, 0, 0x1c000
	ds_read_b128 v[154:157], v185
	ds_read_b128 v[158:161], v185 offset:1024
	ds_read_b128 v[162:165], v185 offset:2048
	ds_read_b128 v[186:189], v185 offset:3072
	v_add_u32_e32 v185, s57, v141
	ds_read_b128 v[190:193], v185
	ds_read_b128 v[194:197], v185 offset:1024
	ds_read_b128 v[198:201], v185 offset:2048
	ds_read_b128 v[202:205], v185 offset:3072
	s_add_u32 s28, s28, s6
	s_addc_u32 s29, s29, s7
	s_mov_b32 m0, s40
	v_lshl_add_u64 v[246:247], s[28:29], 0, v[132:133]
	ds_read_b128 v[206:209], v143 offset:32768
	ds_read_b128 v[210:213], v143 offset:33792
	ds_read_b128 v[214:217], v143 offset:34816
	ds_read_b128 v[218:221], v143 offset:35840
	ds_read_b128 v[222:225], v143 offset:36864
	ds_read_b128 v[226:229], v143 offset:37888
	ds_read_b128 v[230:233], v143 offset:38912
	ds_read_b128 v[234:237], v143 offset:39936
	global_load_lds_dwordx4 v[246:247], off
	v_lshl_add_u64 v[246:247], s[28:29], 0, v[130:131]
	s_mov_b32 m0, s41
	s_nop 0
	global_load_lds_dwordx4 v[246:247], off
	s_waitcnt vmcnt(8)
	s_waitcnt lgkmcnt(0)
	s_barrier
	s_setprio 1
	s_waitcnt lgkmcnt(0)
	v_mfma_f32_16x16x32_bf16 v[120:123], v[154:157], v[206:209], v[120:123]
	v_mfma_f32_16x16x32_bf16 v[124:127], v[162:165], v[206:209], v[124:127]
	v_mfma_f32_16x16x32_bf16 v[108:111], v[154:157], v[214:217], v[108:111]
	v_mfma_f32_16x16x32_bf16 v[104:107], v[162:165], v[214:217], v[104:107]
	v_mfma_f32_16x16x32_bf16 v[92:95], v[154:157], v[222:225], v[92:95]
	v_mfma_f32_16x16x32_bf16 v[88:91], v[162:165], v[222:225], v[88:91]
	v_mfma_f32_16x16x32_bf16 v[76:79], v[154:157], v[230:233], v[76:79]
	v_mfma_f32_16x16x32_bf16 v[72:75], v[162:165], v[230:233], v[72:75]
	v_mfma_f32_16x16x32_bf16 v[120:123], v[158:161], v[210:213], v[120:123]
	v_mfma_f32_16x16x32_bf16 v[124:127], v[186:189], v[210:213], v[124:127]
	v_mfma_f32_16x16x32_bf16 v[108:111], v[158:161], v[218:221], v[108:111]
	v_mfma_f32_16x16x32_bf16 v[104:107], v[186:189], v[218:221], v[104:107]
	v_mfma_f32_16x16x32_bf16 v[92:95], v[158:161], v[226:229], v[92:95]
	v_mfma_f32_16x16x32_bf16 v[88:91], v[186:189], v[226:229], v[88:91]
	v_mfma_f32_16x16x32_bf16 v[76:79], v[158:161], v[234:237], v[76:79]
	v_mfma_f32_16x16x32_bf16 v[72:75], v[186:189], v[234:237], v[72:75]
	s_setprio 0
	s_setprio 1
	v_mfma_f32_16x16x32_bf16 v[116:119], v[190:193], v[206:209], v[116:119]
	v_mfma_f32_16x16x32_bf16 v[112:115], v[198:201], v[206:209], v[112:115]
	v_mfma_f32_16x16x32_bf16 v[100:103], v[190:193], v[214:217], v[100:103]
	v_mfma_f32_16x16x32_bf16 v[96:99], v[198:201], v[214:217], v[96:99]
	v_mfma_f32_16x16x32_bf16 v[84:87], v[190:193], v[222:225], v[84:87]
	v_mfma_f32_16x16x32_bf16 v[80:83], v[198:201], v[222:225], v[80:83]
	v_mfma_f32_16x16x32_bf16 v[68:71], v[190:193], v[230:233], v[68:71]
	v_mfma_f32_16x16x32_bf16 v[64:67], v[198:201], v[230:233], v[64:67]
	v_mfma_f32_16x16x32_bf16 v[116:119], v[194:197], v[210:213], v[116:119]
	v_mfma_f32_16x16x32_bf16 v[112:115], v[202:205], v[210:213], v[112:115]
	v_mfma_f32_16x16x32_bf16 v[100:103], v[194:197], v[218:221], v[100:103]
	v_mfma_f32_16x16x32_bf16 v[96:99], v[202:205], v[218:221], v[96:99]
	v_mfma_f32_16x16x32_bf16 v[84:87], v[194:197], v[226:229], v[84:87]
	v_mfma_f32_16x16x32_bf16 v[80:83], v[202:205], v[226:229], v[80:83]
	v_mfma_f32_16x16x32_bf16 v[68:71], v[194:197], v[234:237], v[68:71]
	v_mfma_f32_16x16x32_bf16 v[64:67], v[202:205], v[234:237], v[64:67]
	s_setprio 0
	s_barrier
; #define PG8_STAGE(bufoff, gbase, voff) do { _Pragma("unroll") for (int _i = 0; _i < 2; ++_i) \
;         __builtin_amdgcn_global_load_lds((const unsigned*)((const char*)(gbase) + (voff)[_i]), (PG8_LAS unsigned*)(lds + (bufoff) + ldsw + _i * 8192), 16, 0, 0); } while (0)
; #define PG8_LDA(dst, b, h) do { _Pragma("unroll") for (int m = 0; m < 4; ++m) _Pragma("unroll") for (int k = 0; k < 2; ++k) dst[m][k] = *(const PG8_LAS bf16x8*)(lds + PG8_SA(b, h) + aoff + m * 2048 + k * 1024); } while (0)
; #define PG8_MMA(ai, bj, At, Bt) do { __builtin_amdgcn_s_setprio(1); _Pragma("unroll") for (int m = 0; m < 4; ++m) _Pragma("unroll") for (int n = 0; n < 2; ++n) _Pragma("unroll") for (int k = 0; k < 2; ++k) \
;         acc[ai][bj][m][n] = __builtin_amdgcn_mfma_f32_16x16x32_bf16(Bt[n][k], At[m][k], acc[ai][bj][m][n], 0, 0, 0); __builtin_amdgcn_s_setprio(0); } while (0)
; #define PG8_WAIT_V(n) asm volatile("s_waitcnt vmcnt(" #n ")" ::: "memory")
; #define PG8_WAIT_L(n) asm volatile("s_waitcnt lgkmcnt(" #n ")" ::: "memory")
; #define PG8_BAR __builtin_amdgcn_s_barrier()
; #define PG8_SCHED __builtin_amdgcn_sched_barrier(0)
; template <class Epi, class Sched>
; __device__ __forceinline__ void gemm_phase(int wid_s, PG8_LAS unsigned char* lds, const Gemm g, const Sched& S, const Epi& E) {
;     ...
;         for (int t = 0; t < nt; t += 2) {
;             const bool last = (t == nt - 2);
;             const char* a1 = cA + (size_t)(t + 1) * kstep;
;             const char* a2 = last ? nA : cA + (size_t)(t + 2) * kstep; const char* b2 = last ? nB : cB + (size_t)(t + 2) * kstep;
;     ...
;             PG8_LDA(At, 1, 1); PG8_STAGE(PG8_SB(1, 0), b3, voffB); PG8_STAGE(PG8_SB(1, 1), b3 + hstepB, voffB); PG8_STAGE(PG8_SA(1, 0), a3, voffA);
;             PG8_WAIT_V(8); PG8_WAIT_L(0); PG8_BAR; PG8_MMA(1, 0, At, B0); PG8_MMA(1, 1, At, B1); PG8_BAR; PG8_SCHED;
;         }
	s_add_i32 s28, s56, s35
	v_lshl_add_u64 v[138:139], v[138:139], 0, s[96:97]
	s_mov_b32 m0, s28
	ds_read_b128 v[206:209], v143 offset:49152
	ds_read_b128 v[210:213], v143 offset:50176
	ds_read_b128 v[214:217], v143 offset:51200
	ds_read_b128 v[218:221], v143 offset:52224
	ds_read_b128 v[222:225], v143 offset:53248
	ds_read_b128 v[226:229], v143 offset:54272
	ds_read_b128 v[230:233], v143 offset:55296
	ds_read_b128 v[234:237], v143 offset:56320
	global_load_lds_dwordx4 v[138:139], off
	v_lshl_add_u64 v[138:139], v[166:167], 0, s[96:97]
	s_add_i32 m0, s28, 0x2000
	s_add_i32 s28, s57, s35
	global_load_lds_dwordx4 v[138:139], off
	v_lshl_add_u64 v[138:139], v[238:239], 0, s[96:97]
	s_mov_b32 m0, s28
	s_nop 0
	global_load_lds_dwordx4 v[138:139], off
	v_lshl_add_u64 v[138:139], v[240:241], 0, s[96:97]
	s_add_i32 m0, s28, 0x2000
	s_nop 0
	global_load_lds_dwordx4 v[138:139], off
	v_lshl_add_u64 v[138:139], v[242:243], 0, s[96:97]
	s_mov_b32 m0, s44
	s_nop 0
	global_load_lds_dwordx4 v[138:139], off
	v_lshl_add_u64 v[138:139], v[244:245], 0, s[96:97]
	s_mov_b32 m0, s45
	s_nop 0
	global_load_lds_dwordx4 v[138:139], off
	s_waitcnt vmcnt(8)
	s_waitcnt lgkmcnt(0)
	s_barrier
	s_setprio 1
	s_waitcnt lgkmcnt(0)
	v_mfma_f32_16x16x32_bf16 v[60:63], v[154:157], v[206:209], v[60:63]
	v_mfma_f32_16x16x32_bf16 v[56:59], v[162:165], v[206:209], v[56:59]
	v_mfma_f32_16x16x32_bf16 v[44:47], v[154:157], v[214:217], v[44:47]
	v_mfma_f32_16x16x32_bf16 v[40:43], v[162:165], v[214:217], v[40:43]
	v_mfma_f32_16x16x32_bf16 v[28:31], v[154:157], v[222:225], v[28:31]
	v_mfma_f32_16x16x32_bf16 v[24:27], v[162:165], v[222:225], v[24:27]
	v_mfma_f32_16x16x32_bf16 v[12:15], v[154:157], v[230:233], v[12:15]
	v_mfma_f32_16x16x32_bf16 v[8:11], v[162:165], v[230:233], v[8:11]
	v_mfma_f32_16x16x32_bf16 v[60:63], v[158:161], v[210:213], v[60:63]
	v_mfma_f32_16x16x32_bf16 v[56:59], v[186:189], v[210:213], v[56:59]
	v_mfma_f32_16x16x32_bf16 v[44:47], v[158:161], v[218:221], v[44:47]
	v_mfma_f32_16x16x32_bf16 v[40:43], v[186:189], v[218:221], v[40:43]
	v_mfma_f32_16x16x32_bf16 v[28:31], v[158:161], v[226:229], v[28:31]
	v_mfma_f32_16x16x32_bf16 v[24:27], v[186:189], v[226:229], v[24:27]
	v_mfma_f32_16x16x32_bf16 v[12:15], v[158:161], v[234:237], v[12:15]
	v_mfma_f32_16x16x32_bf16 v[8:11], v[186:189], v[234:237], v[8:11]
	s_setprio 0
	s_setprio 1
	v_mfma_f32_16x16x32_bf16 v[52:55], v[190:193], v[206:209], v[52:55]
	s_add_u32 s33, s33, 0x100
	s_addc_u32 s54, s54, 0
	v_mfma_f32_16x16x32_bf16 v[48:51], v[198:201], v[206:209], v[48:51]
	s_add_u32 s26, s26, 0x100
	s_addc_u32 s27, s27, 0
	v_mfma_f32_16x16x32_bf16 v[36:39], v[190:193], v[214:217], v[36:39]
	s_cmp_ge_i32 s55, s42
	s_mov_b32 s28, s55
	s_cbranch_scc1 .Lmy_kx1
	v_mfma_f32_16x16x32_bf16 v[32:35], v[198:201], v[214:217], v[32:35]
	s_add_i32 s55, s28, 2
	v_mfma_f32_16x16x32_bf16 v[20:23], v[190:193], v[222:225], v[20:23]
	s_add_u32 s56, s26, 0x80
	v_mfma_f32_16x16x32_bf16 v[16:19], v[198:201], v[222:225], v[16:19]
	s_addc_u32 s29, s27, 0
	v_mfma_f32_16x16x32_bf16 v[4:7], v[190:193], v[230:233], v[4:7]
	s_add_i32 s92, 0, 0x10000
	v_mfma_f32_16x16x32_bf16 v[0:3], v[198:201], v[230:233], v[0:3]
	s_cmp_eq_u32 s46, s28
	v_mfma_f32_16x16x32_bf16 v[52:55], v[194:197], v[210:213], v[52:55]
	s_cselect_b32 s29, s5, s29
	v_mfma_f32_16x16x32_bf16 v[48:51], v[202:205], v[210:213], v[48:51]
	s_cselect_b32 s28, s4, s56
	v_mfma_f32_16x16x32_bf16 v[36:39], v[194:197], v[218:221], v[36:39]
	v_add_u32_e32 v138, s92, v141
	v_mfma_f32_16x16x32_bf16 v[32:35], v[202:205], v[218:221], v[32:35]
	s_cselect_b32 s57, s25, s54
	v_mfma_f32_16x16x32_bf16 v[20:23], v[194:197], v[226:229], v[20:23]
	s_cselect_b32 s56, s24, s33
	v_mfma_f32_16x16x32_bf16 v[16:19], v[202:205], v[226:229], v[16:19]
	s_add_i32 s94, 0, 0x14000
	v_mfma_f32_16x16x32_bf16 v[4:7], v[194:197], v[234:237], v[4:7]
	v_mfma_f32_16x16x32_bf16 v[0:3], v[202:205], v[234:237], v[0:3]
	s_setprio 0
	s_barrier
	s_branch .Lmy_kh1
.Lmy_kx1:
	v_mfma_f32_16x16x32_bf16 v[32:35], v[198:201], v[214:217], v[32:35]
	v_mfma_f32_16x16x32_bf16 v[20:23], v[190:193], v[222:225], v[20:23]
	v_mfma_f32_16x16x32_bf16 v[16:19], v[198:201], v[222:225], v[16:19]
	v_mfma_f32_16x16x32_bf16 v[4:7], v[190:193], v[230:233], v[4:7]
	v_mfma_f32_16x16x32_bf16 v[0:3], v[198:201], v[230:233], v[0:3]
	v_mfma_f32_16x16x32_bf16 v[52:55], v[194:197], v[210:213], v[52:55]
	v_mfma_f32_16x16x32_bf16 v[48:51], v[202:205], v[210:213], v[48:51]
	v_mfma_f32_16x16x32_bf16 v[36:39], v[194:197], v[218:221], v[36:39]
	v_mfma_f32_16x16x32_bf16 v[32:35], v[202:205], v[218:221], v[32:35]
	v_mfma_f32_16x16x32_bf16 v[20:23], v[194:197], v[226:229], v[20:23]
	v_mfma_f32_16x16x32_bf16 v[16:19], v[202:205], v[226:229], v[16:19]
	v_mfma_f32_16x16x32_bf16 v[4:7], v[194:197], v[234:237], v[4:7]
	v_mfma_f32_16x16x32_bf16 v[0:3], v[202:205], v[234:237], v[0:3]
	s_setprio 0
	s_barrier
	v_readlane_b32 s54, v254, 52
	v_readlane_b32 s55, v254, 53
	v_readlane_b32 s92, v254, 54
	v_readlane_b32 s94, v254, 55
	s_movk_i32 s33, 0x300

; #define PG8_STAGE(bufoff, gbase, voff) do { _Pragma("unroll") for (int _i = 0; _i < 2; ++_i) \
;         __builtin_amdgcn_global_load_lds((const unsigned*)((const char*)(gbase) + (voff)[_i]), (PG8_LAS unsigned*)(lds + (bufoff) + ldsw + _i * 8192), 16, 0, 0); } while (0)
; #define PG8_LDA(dst, b, h) do { _Pragma("unroll") for (int m = 0; m < 4; ++m) _Pragma("unroll") for (int k = 0; k < 2; ++k) dst[m][k] = *(const PG8_LAS bf16x8*)(lds + PG8_SA(b, h) + aoff + m * 2048 + k * 1024); } while (0)
; #define PG8_LDB(dst, b, h) do { _Pragma("unroll") for (int n = 0; n < 2; ++n) _Pragma("unroll") for (int k = 0; k < 2; ++k) dst[n][k] = *(const PG8_LAS bf16x8*)(lds + PG8_SB(b, h) + boff + n * 2048 + k * 1024); } while (0)
; #define PG8_MMA(ai, bj, At, Bt) do { __builtin_amdgcn_s_setprio(1); _Pragma("unroll") for (int m = 0; m < 4; ++m) _Pragma("unroll") for (int n = 0; n < 2; ++n) _Pragma("unroll") for (int k = 0; k < 2; ++k) \
;         acc[ai][bj][m][n] = __builtin_amdgcn_mfma_f32_16x16x32_bf16(Bt[n][k], At[m][k], acc[ai][bj][m][n], 0, 0, 0); __builtin_amdgcn_s_setprio(0); } while (0)
; #define PG8_WAIT_V(n) asm volatile("s_waitcnt vmcnt(" #n ")" ::: "memory")
; #define PG8_WAIT_L(n) asm volatile("s_waitcnt lgkmcnt(" #n ")" ::: "memory")
; #define PG8_BAR __builtin_amdgcn_s_barrier()
; #define PG8_SCHED __builtin_amdgcn_sched_barrier(0)
; template <class Epi, class Sched>
; __device__ __forceinline__ void gemm_phase(int wid_s, PG8_LAS unsigned char* lds, const Gemm g, const Sched& S, const Epi& E) {
;     ...
;             PG8_LDB(B0, 0, 0); PG8_LDB(B1, 0, 1); PG8_SCHED; PG8_LDA(At, 0, 0); PG8_STAGE(PG8_SA(1, 1), a1 + hstepA, voffA);
;             PG8_WAIT_V(8); PG8_WAIT_L(0); PG8_BAR; PG8_MMA(0, 0, At, B0); PG8_MMA(0, 1, At, B1); PG8_BAR; PG8_SCHED;
;             PG8_LDA(At, 0, 1); PG8_STAGE(PG8_SB(0, 0), b2, voffB); PG8_STAGE(PG8_SB(0, 1), b2 + hstepB, voffB); PG8_STAGE(PG8_SA(0, 0), a2, voffA);
;             PG8_WAIT_V(8); PG8_WAIT_L(0); PG8_BAR; PG8_MMA(1, 0, At, B0); PG8_MMA(1, 1, At, B1); PG8_BAR; PG8_SCHED;
.Lmy_kh2:
	ds_read_b128 v[154:157], v144
	ds_read_b128 v[158:161], v144 offset:1024
	ds_read_b128 v[164:167], v144 offset:2048
	ds_read_b128 v[186:189], v144 offset:3072
	v_add_u32_e32 v144, s51, v162
	ds_read_b128 v[190:193], v144
	ds_read_b128 v[194:197], v144 offset:1024
	ds_read_b128 v[198:201], v144 offset:2048
	ds_read_b128 v[202:205], v144 offset:3072
	v_lshl_add_u64 v[238:239], s[4:5], 0, v[142:143]
	s_add_i32 m0, s46, 0xc000
	ds_read_b128 v[206:209], v163
	ds_read_b128 v[210:213], v163 offset:1024
	ds_read_b128 v[214:217], v163 offset:2048
	ds_read_b128 v[218:221], v163 offset:3072
	ds_read_b128 v[222:225], v163 offset:4096
	ds_read_b128 v[226:229], v163 offset:5120
	ds_read_b128 v[230:233], v163 offset:6144
	ds_read_b128 v[234:237], v163 offset:7168
	global_load_lds_dwordx4 v[238:239], off
	v_lshl_add_u64 v[238:239], s[4:5], 0, v[140:141]
	s_add_i32 m0, s46, 0xe000
	s_nop 0
	global_load_lds_dwordx4 v[238:239], off
	s_waitcnt vmcnt(8)
	s_waitcnt lgkmcnt(0)
	s_barrier
	s_setprio 1
	s_waitcnt lgkmcnt(0)
	v_mfma_f32_16x16x32_bf16 v[120:123], v[154:157], v[206:209], v[120:123]
	v_mfma_f32_16x16x32_bf16 v[124:127], v[164:167], v[206:209], v[124:127]
	v_mfma_f32_16x16x32_bf16 v[108:111], v[154:157], v[214:217], v[108:111]
	v_mfma_f32_16x16x32_bf16 v[104:107], v[164:167], v[214:217], v[104:107]
	v_mfma_f32_16x16x32_bf16 v[92:95], v[154:157], v[222:225], v[92:95]
	v_mfma_f32_16x16x32_bf16 v[88:91], v[164:167], v[222:225], v[88:91]
	v_mfma_f32_16x16x32_bf16 v[76:79], v[154:157], v[230:233], v[76:79]
	v_mfma_f32_16x16x32_bf16 v[72:75], v[164:167], v[230:233], v[72:75]
	v_mfma_f32_16x16x32_bf16 v[120:123], v[158:161], v[210:213], v[120:123]
	v_mfma_f32_16x16x32_bf16 v[124:127], v[186:189], v[210:213], v[124:127]
	v_mfma_f32_16x16x32_bf16 v[108:111], v[158:161], v[218:221], v[108:111]
	v_mfma_f32_16x16x32_bf16 v[104:107], v[186:189], v[218:221], v[104:107]
	v_mfma_f32_16x16x32_bf16 v[92:95], v[158:161], v[226:229], v[92:95]
	v_mfma_f32_16x16x32_bf16 v[88:91], v[186:189], v[226:229], v[88:91]
	v_mfma_f32_16x16x32_bf16 v[76:79], v[158:161], v[234:237], v[76:79]
	v_mfma_f32_16x16x32_bf16 v[72:75], v[186:189], v[234:237], v[72:75]
	s_setprio 0
	s_setprio 1
	v_mfma_f32_16x16x32_bf16 v[116:119], v[190:193], v[206:209], v[116:119]
	v_mfma_f32_16x16x32_bf16 v[112:115], v[198:201], v[206:209], v[112:115]
	v_mfma_f32_16x16x32_bf16 v[100:103], v[190:193], v[214:217], v[100:103]
	v_mfma_f32_16x16x32_bf16 v[96:99], v[198:201], v[214:217], v[96:99]
	v_mfma_f32_16x16x32_bf16 v[84:87], v[190:193], v[222:225], v[84:87]
	v_mfma_f32_16x16x32_bf16 v[80:83], v[198:201], v[222:225], v[80:83]
	v_mfma_f32_16x16x32_bf16 v[68:71], v[190:193], v[230:233], v[68:71]
	v_mfma_f32_16x16x32_bf16 v[64:67], v[198:201], v[230:233], v[64:67]
	v_mfma_f32_16x16x32_bf16 v[116:119], v[194:197], v[210:213], v[116:119]
	v_mfma_f32_16x16x32_bf16 v[112:115], v[202:205], v[210:213], v[112:115]
	v_mfma_f32_16x16x32_bf16 v[100:103], v[194:197], v[218:221], v[100:103]
	v_mfma_f32_16x16x32_bf16 v[96:99], v[202:205], v[218:221], v[96:99]
	v_mfma_f32_16x16x32_bf16 v[84:87], v[194:197], v[226:229], v[84:87]
	v_mfma_f32_16x16x32_bf16 v[80:83], v[202:205], v[226:229], v[80:83]
	v_mfma_f32_16x16x32_bf16 v[68:71], v[194:197], v[234:237], v[68:71]
	v_mfma_f32_16x16x32_bf16 v[64:67], v[202:205], v[234:237], v[64:67]
	s_setprio 0
	s_barrier
	s_add_i32 s50, s50, s41
	v_lshl_add_u64 v[238:239], s[34:35], 0, v[130:131]
	s_mov_b32 m0, s50
	ds_read_b128 v[206:209], v163 offset:16384
	ds_read_b128 v[210:213], v163 offset:17408
	ds_read_b128 v[214:217], v163 offset:18432
	ds_read_b128 v[218:221], v163 offset:19456
	ds_read_b128 v[222:225], v163 offset:20480
	ds_read_b128 v[226:229], v163 offset:21504
	ds_read_b128 v[230:233], v163 offset:22528
	ds_read_b128 v[234:237], v163 offset:23552
	global_load_lds_dwordx4 v[238:239], off
	s_add_i32 m0, s50, 0x2000
	v_lshl_add_u64 v[240:241], s[34:35], 0, v[134:135]
	s_add_u32 s34, s34, s8
	s_addc_u32 s35, s35, s9
	s_add_i32 s50, s51, s41
	global_load_lds_dwordx4 v[240:241], off
	v_lshl_add_u64 v[242:243], s[34:35], 0, v[130:131]
	s_mov_b32 m0, s50
	v_lshl_add_u64 v[244:245], s[34:35], 0, v[134:135]
	global_load_lds_dwordx4 v[242:243], off
	s_add_i32 m0, s50, 0x2000
	v_lshl_add_u64 v[246:247], s[30:31], 0, v[128:129]
	global_load_lds_dwordx4 v[244:245], off
	s_mov_b32 m0, s46
	v_lshl_add_u64 v[248:249], s[30:31], 0, v[132:133]
	global_load_lds_dwordx4 v[246:247], off
	s_mov_b32 m0, s47
	s_nop 0
	global_load_lds_dwordx4 v[248:249], off
	s_waitcnt vmcnt(8)
	s_waitcnt lgkmcnt(0)
	s_barrier
; #define PG8_STAGE(bufoff, gbase, voff) do { _Pragma("unroll") for (int _i = 0; _i < 2; ++_i) \
;         __builtin_amdgcn_global_load_lds((const unsigned*)((const char*)(gbase) + (voff)[_i]), (PG8_LAS unsigned*)(lds + (bufoff) + ldsw + _i * 8192), 16, 0, 0); } while (0)
; #define PG8_LDA(dst, b, h) do { _Pragma("unroll") for (int m = 0; m < 4; ++m) _Pragma("unroll") for (int k = 0; k < 2; ++k) dst[m][k] = *(const PG8_LAS bf16x8*)(lds + PG8_SA(b, h) + aoff + m * 2048 + k * 1024); } while (0)
; #define PG8_LDB(dst, b, h) do { _Pragma("unroll") for (int n = 0; n < 2; ++n) _Pragma("unroll") for (int k = 0; k < 2; ++k) dst[n][k] = *(const PG8_LAS bf16x8*)(lds + PG8_SB(b, h) + boff + n * 2048 + k * 1024); } while (0)
; #define PG8_MMA(ai, bj, At, Bt) do { __builtin_amdgcn_s_setprio(1); _Pragma("unroll") for (int m = 0; m < 4; ++m) _Pragma("unroll") for (int n = 0; n < 2; ++n) _Pragma("unroll") for (int k = 0; k < 2; ++k) \
;         acc[ai][bj][m][n] = __builtin_amdgcn_mfma_f32_16x16x32_bf16(Bt[n][k], At[m][k], acc[ai][bj][m][n], 0, 0, 0); __builtin_amdgcn_s_setprio(0); } while (0)
; #define PG8_WAIT_V(n) asm volatile("s_waitcnt vmcnt(" #n ")" ::: "memory")
; #define PG8_WAIT_L(n) asm volatile("s_waitcnt lgkmcnt(" #n ")" ::: "memory")
; #define PG8_BAR __builtin_amdgcn_s_barrier()
; #define PG8_SCHED __builtin_amdgcn_sched_barrier(0)
; template <class Epi, class Sched>
; __device__ __forceinline__ void gemm_phase(int wid_s, PG8_LAS unsigned char* lds, const Gemm g, const Sched& S, const Epi& E) {
;     ...
;             PG8_WAIT_V(8); PG8_WAIT_L(0); PG8_BAR; PG8_MMA(1, 0, At, B0); PG8_MMA(1, 1, At, B1); PG8_BAR; PG8_SCHED;
;             PG8_LDB(B0, 1, 0); PG8_LDB(B1, 1, 1); PG8_SCHED; PG8_LDA(At, 1, 0); PG8_STAGE(PG8_SA(0, 1), a2 + hstepA, voffA);
;             PG8_WAIT_V(8); PG8_WAIT_L(0); PG8_BAR; PG8_MMA(0, 0, At, B0); PG8_MMA(0, 1, At, B1); PG8_BAR; PG8_SCHED;
	s_setprio 1
	s_waitcnt lgkmcnt(0)
	v_mfma_f32_16x16x32_bf16 v[60:63], v[154:157], v[206:209], v[60:63]
	v_mfma_f32_16x16x32_bf16 v[56:59], v[164:167], v[206:209], v[56:59]
	v_mfma_f32_16x16x32_bf16 v[44:47], v[154:157], v[214:217], v[44:47]
	v_mfma_f32_16x16x32_bf16 v[40:43], v[164:167], v[214:217], v[40:43]
	v_mfma_f32_16x16x32_bf16 v[28:31], v[154:157], v[222:225], v[28:31]
	v_mfma_f32_16x16x32_bf16 v[24:27], v[164:167], v[222:225], v[24:27]
	v_mfma_f32_16x16x32_bf16 v[12:15], v[154:157], v[230:233], v[12:15]
	v_mfma_f32_16x16x32_bf16 v[8:11], v[164:167], v[230:233], v[8:11]
	v_mfma_f32_16x16x32_bf16 v[60:63], v[158:161], v[210:213], v[60:63]
	v_mfma_f32_16x16x32_bf16 v[56:59], v[186:189], v[210:213], v[56:59]
	v_mfma_f32_16x16x32_bf16 v[44:47], v[158:161], v[218:221], v[44:47]
	v_mfma_f32_16x16x32_bf16 v[40:43], v[186:189], v[218:221], v[40:43]
	v_mfma_f32_16x16x32_bf16 v[28:31], v[158:161], v[226:229], v[28:31]
	v_mfma_f32_16x16x32_bf16 v[24:27], v[186:189], v[226:229], v[24:27]
	v_mfma_f32_16x16x32_bf16 v[12:15], v[158:161], v[234:237], v[12:15]
	v_mfma_f32_16x16x32_bf16 v[8:11], v[186:189], v[234:237], v[8:11]
	s_setprio 0
	s_setprio 1
	v_mfma_f32_16x16x32_bf16 v[52:55], v[190:193], v[206:209], v[52:55]
	v_mfma_f32_16x16x32_bf16 v[48:51], v[198:201], v[206:209], v[48:51]
	v_mfma_f32_16x16x32_bf16 v[36:39], v[190:193], v[214:217], v[36:39]
	v_mfma_f32_16x16x32_bf16 v[32:35], v[198:201], v[214:217], v[32:35]
	v_mfma_f32_16x16x32_bf16 v[20:23], v[190:193], v[222:225], v[20:23]
	v_mfma_f32_16x16x32_bf16 v[16:19], v[198:201], v[222:225], v[16:19]
	v_mfma_f32_16x16x32_bf16 v[4:7], v[190:193], v[230:233], v[4:7]
	v_mfma_f32_16x16x32_bf16 v[0:3], v[198:201], v[230:233], v[0:3]
	v_mfma_f32_16x16x32_bf16 v[52:55], v[194:197], v[210:213], v[52:55]
	v_mfma_f32_16x16x32_bf16 v[48:51], v[202:205], v[210:213], v[48:51]
	v_mfma_f32_16x16x32_bf16 v[36:39], v[194:197], v[218:221], v[36:39]
	v_mfma_f32_16x16x32_bf16 v[32:35], v[202:205], v[218:221], v[32:35]
	v_mfma_f32_16x16x32_bf16 v[20:23], v[194:197], v[226:229], v[20:23]
	v_mfma_f32_16x16x32_bf16 v[16:19], v[202:205], v[226:229], v[16:19]
	v_mfma_f32_16x16x32_bf16 v[4:7], v[194:197], v[234:237], v[4:7]
	v_mfma_f32_16x16x32_bf16 v[0:3], v[202:205], v[234:237], v[0:3]
	s_setprio 0
	s_barrier
	s_add_i32 s34, 0, 0x18000
	v_add_u32_e32 v144, s34, v162
	s_add_i32 s35, 0, 0x1c000
	ds_read_b128 v[154:157], v144
	ds_read_b128 v[158:161], v144 offset:1024
	ds_read_b128 v[164:167], v144 offset:2048
	ds_read_b128 v[186:189], v144 offset:3072
	v_add_u32_e32 v144, s35, v162
	ds_read_b128 v[190:193], v144
	ds_read_b128 v[194:197], v144 offset:1024
	ds_read_b128 v[198:201], v144 offset:2048
	ds_read_b128 v[202:205], v144 offset:3072
	s_add_u32 s30, s30, s6
	s_addc_u32 s31, s31, s7
	s_mov_b32 m0, s53
	v_lshl_add_u64 v[250:251], s[30:31], 0, v[128:129]
	ds_read_b128 v[206:209], v163 offset:32768
	ds_read_b128 v[210:213], v163 offset:33792
	ds_read_b128 v[214:217], v163 offset:34816
	ds_read_b128 v[218:221], v163 offset:35840
	ds_read_b128 v[222:225], v163 offset:36864
	ds_read_b128 v[226:229], v163 offset:37888
	ds_read_b128 v[230:233], v163 offset:38912
	ds_read_b128 v[234:237], v163 offset:39936
	global_load_lds_dwordx4 v[250:251], off
	v_lshl_add_u64 v[250:251], s[30:31], 0, v[132:133]
	s_mov_b32 m0, s54
	s_nop 0
	global_load_lds_dwordx4 v[250:251], off
	s_waitcnt vmcnt(8)
	s_waitcnt lgkmcnt(0)
	s_barrier
	s_setprio 1
	s_waitcnt lgkmcnt(0)
	v_mfma_f32_16x16x32_bf16 v[120:123], v[154:157], v[206:209], v[120:123]
	v_mfma_f32_16x16x32_bf16 v[124:127], v[164:167], v[206:209], v[124:127]
	v_mfma_f32_16x16x32_bf16 v[108:111], v[154:157], v[214:217], v[108:111]
	v_mfma_f32_16x16x32_bf16 v[104:107], v[164:167], v[214:217], v[104:107]
	v_mfma_f32_16x16x32_bf16 v[92:95], v[154:157], v[222:225], v[92:95]
	v_mfma_f32_16x16x32_bf16 v[88:91], v[164:167], v[222:225], v[88:91]
	v_mfma_f32_16x16x32_bf16 v[76:79], v[154:157], v[230:233], v[76:79]
	v_mfma_f32_16x16x32_bf16 v[72:75], v[164:167], v[230:233], v[72:75]
	v_mfma_f32_16x16x32_bf16 v[120:123], v[158:161], v[210:213], v[120:123]
	v_mfma_f32_16x16x32_bf16 v[124:127], v[186:189], v[210:213], v[124:127]
	v_mfma_f32_16x16x32_bf16 v[108:111], v[158:161], v[218:221], v[108:111]
	v_mfma_f32_16x16x32_bf16 v[104:107], v[186:189], v[218:221], v[104:107]
	v_mfma_f32_16x16x32_bf16 v[92:95], v[158:161], v[226:229], v[92:95]
	v_mfma_f32_16x16x32_bf16 v[88:91], v[186:189], v[226:229], v[88:91]
	v_mfma_f32_16x16x32_bf16 v[76:79], v[158:161], v[234:237], v[76:79]
	v_mfma_f32_16x16x32_bf16 v[72:75], v[186:189], v[234:237], v[72:75]
	s_setprio 0
	s_setprio 1
	v_mfma_f32_16x16x32_bf16 v[116:119], v[190:193], v[206:209], v[116:119]
	v_mfma_f32_16x16x32_bf16 v[112:115], v[198:201], v[206:209], v[112:115]
	v_mfma_f32_16x16x32_bf16 v[100:103], v[190:193], v[214:217], v[100:103]
	v_mfma_f32_16x16x32_bf16 v[96:99], v[198:201], v[214:217], v[96:99]
	v_mfma_f32_16x16x32_bf16 v[84:87], v[190:193], v[222:225], v[84:87]
	v_mfma_f32_16x16x32_bf16 v[80:83], v[198:201], v[222:225], v[80:83]
	v_mfma_f32_16x16x32_bf16 v[68:71], v[190:193], v[230:233], v[68:71]
	v_mfma_f32_16x16x32_bf16 v[64:67], v[198:201], v[230:233], v[64:67]
	v_mfma_f32_16x16x32_bf16 v[116:119], v[194:197], v[210:213], v[116:119]
	v_mfma_f32_16x16x32_bf16 v[112:115], v[202:205], v[210:213], v[112:115]
	v_mfma_f32_16x16x32_bf16 v[100:103], v[194:197], v[218:221], v[100:103]
	v_mfma_f32_16x16x32_bf16 v[96:99], v[202:205], v[218:221], v[96:99]
	v_mfma_f32_16x16x32_bf16 v[84:87], v[194:197], v[226:229], v[84:87]
	v_mfma_f32_16x16x32_bf16 v[80:83], v[202:205], v[226:229], v[80:83]
	v_mfma_f32_16x16x32_bf16 v[68:71], v[194:197], v[234:237], v[68:71]
	v_mfma_f32_16x16x32_bf16 v[64:67], v[202:205], v[234:237], v[64:67]
	s_setprio 0
	s_barrier
; #define PG8_STAGE(bufoff, gbase, voff) do { _Pragma("unroll") for (int _i = 0; _i < 2; ++_i) \
;         __builtin_amdgcn_global_load_lds((const unsigned*)((const char*)(gbase) + (voff)[_i]), (PG8_LAS unsigned*)(lds + (bufoff) + ldsw + _i * 8192), 16, 0, 0); } while (0)
; #define PG8_LDA(dst, b, h) do { _Pragma("unroll") for (int m = 0; m < 4; ++m) _Pragma("unroll") for (int k = 0; k < 2; ++k) dst[m][k] = *(const PG8_LAS bf16x8*)(lds + PG8_SA(b, h) + aoff + m * 2048 + k * 1024); } while (0)
; #define PG8_MMA(ai, bj, At, Bt) do { __builtin_amdgcn_s_setprio(1); _Pragma("unroll") for (int m = 0; m < 4; ++m) _Pragma("unroll") for (int n = 0; n < 2; ++n) _Pragma("unroll") for (int k = 0; k < 2; ++k) \
;         acc[ai][bj][m][n] = __builtin_amdgcn_mfma_f32_16x16x32_bf16(Bt[n][k], At[m][k], acc[ai][bj][m][n], 0, 0, 0); __builtin_amdgcn_s_setprio(0); } while (0)
; #define PG8_WAIT_V(n) asm volatile("s_waitcnt vmcnt(" #n ")" ::: "memory")
; #define PG8_WAIT_L(n) asm volatile("s_waitcnt lgkmcnt(" #n ")" ::: "memory")
; #define PG8_BAR __builtin_amdgcn_s_barrier()
; #define PG8_SCHED __builtin_amdgcn_sched_barrier(0)
; template <class Epi, class Sched>
; __device__ __forceinline__ void gemm_phase(int wid_s, PG8_LAS unsigned char* lds, const Gemm g, const Sched& S, const Epi& E) {
;     ...
;         for (int t = 0; t < nt; t += 2) {
;             const bool last = (t == nt - 2);
;             const char* a1 = cA + (size_t)(t + 1) * kstep;
;             const char* a2 = last ? nA : cA + (size_t)(t + 2) * kstep; const char* b2 = last ? nB : cB + (size_t)(t + 2) * kstep;
;     ...
;             PG8_LDA(At, 1, 1); PG8_STAGE(PG8_SB(1, 0), b3, voffB); PG8_STAGE(PG8_SB(1, 1), b3 + hstepB, voffB); PG8_STAGE(PG8_SA(1, 0), a3, voffA);
;             PG8_WAIT_V(8); PG8_WAIT_L(0); PG8_BAR; PG8_MMA(1, 0, At, B0); PG8_MMA(1, 1, At, B1); PG8_BAR; PG8_SCHED;
;         }
	s_add_i32 s30, s34, s41
	v_lshl_add_u64 v[238:239], v[238:239], 0, s[96:97]
	s_mov_b32 m0, s30
	ds_read_b128 v[206:209], v163 offset:49152
	ds_read_b128 v[210:213], v163 offset:50176
	ds_read_b128 v[214:217], v163 offset:51200
	ds_read_b128 v[218:221], v163 offset:52224
	ds_read_b128 v[222:225], v163 offset:53248
	ds_read_b128 v[226:229], v163 offset:54272
	ds_read_b128 v[230:233], v163 offset:55296
	ds_read_b128 v[234:237], v163 offset:56320
	global_load_lds_dwordx4 v[238:239], off
	v_lshl_add_u64 v[238:239], v[240:241], 0, s[96:97]
	s_add_i32 m0, s30, 0x2000
	s_add_i32 s30, s35, s41
	global_load_lds_dwordx4 v[238:239], off
	v_lshl_add_u64 v[238:239], v[242:243], 0, s[96:97]
	s_mov_b32 m0, s30
	s_nop 0
	global_load_lds_dwordx4 v[238:239], off
	v_lshl_add_u64 v[238:239], v[244:245], 0, s[96:97]
	s_add_i32 m0, s30, 0x2000
	s_nop 0
	global_load_lds_dwordx4 v[238:239], off
	v_lshl_add_u64 v[238:239], v[246:247], 0, s[96:97]
	s_mov_b32 m0, s55
	s_nop 0
	global_load_lds_dwordx4 v[238:239], off
	v_lshl_add_u64 v[238:239], v[248:249], 0, s[96:97]
	s_mov_b32 m0, s56
	s_nop 0
	global_load_lds_dwordx4 v[238:239], off
	s_waitcnt vmcnt(8)
	s_waitcnt lgkmcnt(0)
	s_barrier
	s_setprio 1
	s_waitcnt lgkmcnt(0)
	v_mfma_f32_16x16x32_bf16 v[60:63], v[154:157], v[206:209], v[60:63]
	v_mfma_f32_16x16x32_bf16 v[56:59], v[164:167], v[206:209], v[56:59]
	v_mfma_f32_16x16x32_bf16 v[44:47], v[154:157], v[214:217], v[44:47]
	v_mfma_f32_16x16x32_bf16 v[40:43], v[164:167], v[214:217], v[40:43]
	v_mfma_f32_16x16x32_bf16 v[28:31], v[154:157], v[222:225], v[28:31]
	v_mfma_f32_16x16x32_bf16 v[24:27], v[164:167], v[222:225], v[24:27]
	v_mfma_f32_16x16x32_bf16 v[12:15], v[154:157], v[230:233], v[12:15]
	v_mfma_f32_16x16x32_bf16 v[8:11], v[164:167], v[230:233], v[8:11]
	v_mfma_f32_16x16x32_bf16 v[60:63], v[158:161], v[210:213], v[60:63]
	v_mfma_f32_16x16x32_bf16 v[56:59], v[186:189], v[210:213], v[56:59]
	v_mfma_f32_16x16x32_bf16 v[44:47], v[158:161], v[218:221], v[44:47]
	v_mfma_f32_16x16x32_bf16 v[40:43], v[186:189], v[218:221], v[40:43]
	v_mfma_f32_16x16x32_bf16 v[28:31], v[158:161], v[226:229], v[28:31]
	v_mfma_f32_16x16x32_bf16 v[24:27], v[186:189], v[226:229], v[24:27]
	v_mfma_f32_16x16x32_bf16 v[12:15], v[158:161], v[234:237], v[12:15]
	v_mfma_f32_16x16x32_bf16 v[8:11], v[186:189], v[234:237], v[8:11]
	s_setprio 0
	s_setprio 1
	v_mfma_f32_16x16x32_bf16 v[52:55], v[190:193], v[206:209], v[52:55]
	s_add_u32 s14, s14, 0x100
	s_addc_u32 s15, s15, 0
	v_mfma_f32_16x16x32_bf16 v[48:51], v[198:201], v[206:209], v[48:51]
	s_add_u32 s4, s4, 0x100
	s_addc_u32 s5, s5, 0
	v_mfma_f32_16x16x32_bf16 v[36:39], v[190:193], v[214:217], v[36:39]
	s_cmp_ge_i32 s33, s57
	s_mov_b32 s30, s33
	s_cbranch_scc1 .Lmy_kx2
	v_mfma_f32_16x16x32_bf16 v[32:35], v[198:201], v[214:217], v[32:35]
	s_add_i32 s33, s30, 2
	v_mfma_f32_16x16x32_bf16 v[20:23], v[190:193], v[222:225], v[20:23]
	s_add_u32 s34, s4, 0x80
	v_mfma_f32_16x16x32_bf16 v[16:19], v[198:201], v[222:225], v[16:19]
	s_addc_u32 s31, s5, 0
	v_mfma_f32_16x16x32_bf16 v[4:7], v[190:193], v[230:233], v[4:7]
	s_add_i32 s50, 0, 0x10000
	v_mfma_f32_16x16x32_bf16 v[0:3], v[198:201], v[230:233], v[0:3]
	s_cmp_eq_u32 s94, s30
	v_mfma_f32_16x16x32_bf16 v[52:55], v[194:197], v[210:213], v[52:55]
	s_cselect_b32 s31, s27, s31
	v_mfma_f32_16x16x32_bf16 v[48:51], v[202:205], v[210:213], v[48:51]
	s_cselect_b32 s30, s26, s34
	v_mfma_f32_16x16x32_bf16 v[36:39], v[194:197], v[218:221], v[36:39]
	v_add_u32_e32 v144, s50, v162
	v_mfma_f32_16x16x32_bf16 v[32:35], v[202:205], v[218:221], v[32:35]
	s_cselect_b32 s35, s29, s15
	v_mfma_f32_16x16x32_bf16 v[20:23], v[194:197], v[226:229], v[20:23]
	s_cselect_b32 s34, s28, s14
	v_mfma_f32_16x16x32_bf16 v[16:19], v[202:205], v[226:229], v[16:19]
	s_add_i32 s51, 0, 0x14000
	v_mfma_f32_16x16x32_bf16 v[4:7], v[194:197], v[234:237], v[4:7]
	v_mfma_f32_16x16x32_bf16 v[0:3], v[202:205], v[234:237], v[0:3]
	s_setprio 0
	s_barrier
	s_branch .Lmy_kh2
.Lmy_kx2:
	v_mfma_f32_16x16x32_bf16 v[32:35], v[198:201], v[214:217], v[32:35]
	v_mfma_f32_16x16x32_bf16 v[20:23], v[190:193], v[222:225], v[20:23]
	v_mfma_f32_16x16x32_bf16 v[16:19], v[198:201], v[222:225], v[16:19]
	v_mfma_f32_16x16x32_bf16 v[4:7], v[190:193], v[230:233], v[4:7]
	v_mfma_f32_16x16x32_bf16 v[0:3], v[198:201], v[230:233], v[0:3]
	v_mfma_f32_16x16x32_bf16 v[52:55], v[194:197], v[210:213], v[52:55]
	v_mfma_f32_16x16x32_bf16 v[48:51], v[202:205], v[210:213], v[48:51]
	v_mfma_f32_16x16x32_bf16 v[36:39], v[194:197], v[218:221], v[36:39]
	v_mfma_f32_16x16x32_bf16 v[32:35], v[202:205], v[218:221], v[32:35]
	v_mfma_f32_16x16x32_bf16 v[20:23], v[194:197], v[226:229], v[20:23]
	v_mfma_f32_16x16x32_bf16 v[16:19], v[202:205], v[226:229], v[16:19]
	v_mfma_f32_16x16x32_bf16 v[4:7], v[194:197], v[234:237], v[4:7]
	v_mfma_f32_16x16x32_bf16 v[0:3], v[202:205], v[234:237], v[0:3]
	s_setprio 0
	s_barrier
	s_movk_i32 s51, 0x1000

; #define PG8_STAGE(bufoff, gbase, voff) do { _Pragma("unroll") for (int _i = 0; _i < 2; ++_i) \
;         __builtin_amdgcn_global_load_lds((const unsigned*)((const char*)(gbase) + (voff)[_i]), (PG8_LAS unsigned*)(lds + (bufoff) + ldsw + _i * 8192), 16, 0, 0); } while (0)
; #define PG8_LDA(dst, b, h) do { _Pragma("unroll") for (int m = 0; m < 4; ++m) _Pragma("unroll") for (int k = 0; k < 2; ++k) dst[m][k] = *(const PG8_LAS bf16x8*)(lds + PG8_SA(b, h) + aoff + m * 2048 + k * 1024); } while (0)
; #define PG8_LDB(dst, b, h) do { _Pragma("unroll") for (int n = 0; n < 2; ++n) _Pragma("unroll") for (int k = 0; k < 2; ++k) dst[n][k] = *(const PG8_LAS bf16x8*)(lds + PG8_SB(b, h) + boff + n * 2048 + k * 1024); } while (0)
; #define PG8_MMA(ai, bj, At, Bt) do { __builtin_amdgcn_s_setprio(1); _Pragma("unroll") for (int m = 0; m < 4; ++m) _Pragma("unroll") for (int n = 0; n < 2; ++n) _Pragma("unroll") for (int k = 0; k < 2; ++k) \
;         acc[ai][bj][m][n] = __builtin_amdgcn_mfma_f32_16x16x32_bf16(Bt[n][k], At[m][k], acc[ai][bj][m][n], 0, 0, 0); __builtin_amdgcn_s_setprio(0); } while (0)
; #define PG8_WAIT_V(n) asm volatile("s_waitcnt vmcnt(" #n ")" ::: "memory")
; #define PG8_WAIT_L(n) asm volatile("s_waitcnt lgkmcnt(" #n ")" ::: "memory")
; #define PG8_BAR __builtin_amdgcn_s_barrier()
; #define PG8_SCHED __builtin_amdgcn_sched_barrier(0)
; template <class Epi, class Sched>
; __device__ __forceinline__ void gemm_phase(int wid_s, PG8_LAS unsigned char* lds, const Gemm g, const Sched& S, const Epi& E) {
;     ...
;             PG8_LDB(B0, 0, 0); PG8_LDB(B1, 0, 1); PG8_SCHED; PG8_LDA(At, 0, 0); PG8_STAGE(PG8_SA(1, 1), a1 + hstepA, voffA);
;             PG8_WAIT_V(8); PG8_WAIT_L(0); PG8_BAR; PG8_MMA(0, 0, At, B0); PG8_MMA(0, 1, At, B1); PG8_BAR; PG8_SCHED;
;             PG8_LDA(At, 0, 1); PG8_STAGE(PG8_SB(0, 0), b2, voffB); PG8_STAGE(PG8_SB(0, 1), b2 + hstepB, voffB); PG8_STAGE(PG8_SA(0, 0), a2, voffA);
;             PG8_WAIT_V(8); PG8_WAIT_L(0); PG8_BAR; PG8_MMA(1, 0, At, B0); PG8_MMA(1, 1, At, B1); PG8_BAR; PG8_SCHED;
.Lmy_kh3:
	ds_read_b128 v[154:157], v142
	ds_read_b128 v[158:161], v142 offset:1024
	ds_read_b128 v[162:165], v142 offset:2048
	ds_read_b128 v[186:189], v142 offset:3072
	v_add_u32_e32 v142, s94, v139
	ds_read_b128 v[190:193], v142
	ds_read_b128 v[194:197], v142 offset:1024
	ds_read_b128 v[198:201], v142 offset:2048
	ds_read_b128 v[202:205], v142 offset:3072
	v_lshl_add_u64 v[142:143], s[24:25], 0, v[136:137]
	s_add_i32 m0, s36, 0xc000
	ds_read_b128 v[206:209], v141
	ds_read_b128 v[210:213], v141 offset:1024
	ds_read_b128 v[214:217], v141 offset:2048
	ds_read_b128 v[218:221], v141 offset:3072
	ds_read_b128 v[222:225], v141 offset:4096
	ds_read_b128 v[226:229], v141 offset:5120
	ds_read_b128 v[230:233], v141 offset:6144
	ds_read_b128 v[234:237], v141 offset:7168
	global_load_lds_dwordx4 v[142:143], off
	v_lshl_add_u64 v[142:143], s[24:25], 0, v[134:135]
	s_add_i32 m0, s36, 0xe000
	s_nop 0
	global_load_lds_dwordx4 v[142:143], off
	s_waitcnt vmcnt(8)
	s_waitcnt lgkmcnt(0)
	s_barrier
	s_setprio 1
	s_waitcnt lgkmcnt(0)
	v_mfma_f32_16x16x32_bf16 v[120:123], v[154:157], v[206:209], v[120:123]
	v_mfma_f32_16x16x32_bf16 v[124:127], v[162:165], v[206:209], v[124:127]
	v_mfma_f32_16x16x32_bf16 v[108:111], v[154:157], v[214:217], v[108:111]
	v_mfma_f32_16x16x32_bf16 v[104:107], v[162:165], v[214:217], v[104:107]
	v_mfma_f32_16x16x32_bf16 v[92:95], v[154:157], v[222:225], v[92:95]
	v_mfma_f32_16x16x32_bf16 v[88:91], v[162:165], v[222:225], v[88:91]
	v_mfma_f32_16x16x32_bf16 v[76:79], v[154:157], v[230:233], v[76:79]
	v_mfma_f32_16x16x32_bf16 v[72:75], v[162:165], v[230:233], v[72:75]
	v_mfma_f32_16x16x32_bf16 v[120:123], v[158:161], v[210:213], v[120:123]
	v_mfma_f32_16x16x32_bf16 v[124:127], v[186:189], v[210:213], v[124:127]
	v_mfma_f32_16x16x32_bf16 v[108:111], v[158:161], v[218:221], v[108:111]
	v_mfma_f32_16x16x32_bf16 v[104:107], v[186:189], v[218:221], v[104:107]
	v_mfma_f32_16x16x32_bf16 v[92:95], v[158:161], v[226:229], v[92:95]
	v_mfma_f32_16x16x32_bf16 v[88:91], v[186:189], v[226:229], v[88:91]
	v_mfma_f32_16x16x32_bf16 v[76:79], v[158:161], v[234:237], v[76:79]
	v_mfma_f32_16x16x32_bf16 v[72:75], v[186:189], v[234:237], v[72:75]
	s_setprio 0
	s_setprio 1
	v_mfma_f32_16x16x32_bf16 v[116:119], v[190:193], v[206:209], v[116:119]
	v_mfma_f32_16x16x32_bf16 v[112:115], v[198:201], v[206:209], v[112:115]
	v_mfma_f32_16x16x32_bf16 v[100:103], v[190:193], v[214:217], v[100:103]
	v_mfma_f32_16x16x32_bf16 v[96:99], v[198:201], v[214:217], v[96:99]
	v_mfma_f32_16x16x32_bf16 v[84:87], v[190:193], v[222:225], v[84:87]
	v_mfma_f32_16x16x32_bf16 v[80:83], v[198:201], v[222:225], v[80:83]
	v_mfma_f32_16x16x32_bf16 v[68:71], v[190:193], v[230:233], v[68:71]
	v_mfma_f32_16x16x32_bf16 v[64:67], v[198:201], v[230:233], v[64:67]
	v_mfma_f32_16x16x32_bf16 v[116:119], v[194:197], v[210:213], v[116:119]
	v_mfma_f32_16x16x32_bf16 v[112:115], v[202:205], v[210:213], v[112:115]
	v_mfma_f32_16x16x32_bf16 v[100:103], v[194:197], v[218:221], v[100:103]
	v_mfma_f32_16x16x32_bf16 v[96:99], v[202:205], v[218:221], v[96:99]
	v_mfma_f32_16x16x32_bf16 v[84:87], v[194:197], v[226:229], v[84:87]
	v_mfma_f32_16x16x32_bf16 v[80:83], v[202:205], v[226:229], v[80:83]
	v_mfma_f32_16x16x32_bf16 v[68:71], v[194:197], v[234:237], v[68:71]
	v_mfma_f32_16x16x32_bf16 v[64:67], v[202:205], v[234:237], v[64:67]
	s_setprio 0
	s_barrier
	s_add_i32 s92, s92, s34
	v_lshl_add_u64 v[142:143], s[56:57], 0, v[144:145]
	s_mov_b32 m0, s92
	ds_read_b128 v[206:209], v141 offset:16384
	ds_read_b128 v[210:213], v141 offset:17408
	ds_read_b128 v[214:217], v141 offset:18432
	ds_read_b128 v[218:221], v141 offset:19456
	ds_read_b128 v[222:225], v141 offset:20480
	ds_read_b128 v[226:229], v141 offset:21504
	ds_read_b128 v[230:233], v141 offset:22528
	ds_read_b128 v[234:237], v141 offset:23552
	global_load_lds_dwordx4 v[142:143], off
	s_add_i32 m0, s92, 0x2000
	v_lshl_add_u64 v[166:167], s[56:57], 0, v[128:129]
	s_add_u32 s56, s56, s8
	s_addc_u32 s57, s57, s9
	s_add_i32 s92, s94, s34
	global_load_lds_dwordx4 v[166:167], off
	v_lshl_add_u64 v[238:239], s[56:57], 0, v[144:145]
	s_mov_b32 m0, s92
	v_lshl_add_u64 v[240:241], s[56:57], 0, v[128:129]
	global_load_lds_dwordx4 v[238:239], off
	s_add_i32 m0, s92, 0x2000
	v_lshl_add_u64 v[242:243], s[26:27], 0, v[132:133]
	global_load_lds_dwordx4 v[240:241], off
	s_mov_b32 m0, s36
	v_lshl_add_u64 v[244:245], s[26:27], 0, v[130:131]
	global_load_lds_dwordx4 v[242:243], off
	s_mov_b32 m0, s37
	s_nop 0
	global_load_lds_dwordx4 v[244:245], off
	s_waitcnt vmcnt(8)
	s_waitcnt lgkmcnt(0)
	s_barrier
; #define PG8_STAGE(bufoff, gbase, voff) do { _Pragma("unroll") for (int _i = 0; _i < 2; ++_i) \
;         __builtin_amdgcn_global_load_lds((const unsigned*)((const char*)(gbase) + (voff)[_i]), (PG8_LAS unsigned*)(lds + (bufoff) + ldsw + _i * 8192), 16, 0, 0); } while (0)
; #define PG8_LDA(dst, b, h) do { _Pragma("unroll") for (int m = 0; m < 4; ++m) _Pragma("unroll") for (int k = 0; k < 2; ++k) dst[m][k] = *(const PG8_LAS bf16x8*)(lds + PG8_SA(b, h) + aoff + m * 2048 + k * 1024); } while (0)
; #define PG8_LDB(dst, b, h) do { _Pragma("unroll") for (int n = 0; n < 2; ++n) _Pragma("unroll") for (int k = 0; k < 2; ++k) dst[n][k] = *(const PG8_LAS bf16x8*)(lds + PG8_SB(b, h) + boff + n * 2048 + k * 1024); } while (0)
; #define PG8_MMA(ai, bj, At, Bt) do { __builtin_amdgcn_s_setprio(1); _Pragma("unroll") for (int m = 0; m < 4; ++m) _Pragma("unroll") for (int n = 0; n < 2; ++n) _Pragma("unroll") for (int k = 0; k < 2; ++k) \
;         acc[ai][bj][m][n] = __builtin_amdgcn_mfma_f32_16x16x32_bf16(Bt[n][k], At[m][k], acc[ai][bj][m][n], 0, 0, 0); __builtin_amdgcn_s_setprio(0); } while (0)
; #define PG8_WAIT_V(n) asm volatile("s_waitcnt vmcnt(" #n ")" ::: "memory")
; #define PG8_WAIT_L(n) asm volatile("s_waitcnt lgkmcnt(" #n ")" ::: "memory")
; #define PG8_BAR __builtin_amdgcn_s_barrier()
; #define PG8_SCHED __builtin_amdgcn_sched_barrier(0)
; template <class Epi, class Sched>
; __device__ __forceinline__ void gemm_phase(int wid_s, PG8_LAS unsigned char* lds, const Gemm g, const Sched& S, const Epi& E) {
;     ...
;             PG8_WAIT_V(8); PG8_WAIT_L(0); PG8_BAR; PG8_MMA(1, 0, At, B0); PG8_MMA(1, 1, At, B1); PG8_BAR; PG8_SCHED;
;             PG8_LDB(B0, 1, 0); PG8_LDB(B1, 1, 1); PG8_SCHED; PG8_LDA(At, 1, 0); PG8_STAGE(PG8_SA(0, 1), a2 + hstepA, voffA);
;             PG8_WAIT_V(8); PG8_WAIT_L(0); PG8_BAR; PG8_MMA(0, 0, At, B0); PG8_MMA(0, 1, At, B1); PG8_BAR; PG8_SCHED;
	s_setprio 1
	s_waitcnt lgkmcnt(0)
	v_mfma_f32_16x16x32_bf16 v[60:63], v[154:157], v[206:209], v[60:63]
	v_mfma_f32_16x16x32_bf16 v[56:59], v[162:165], v[206:209], v[56:59]
	v_mfma_f32_16x16x32_bf16 v[44:47], v[154:157], v[214:217], v[44:47]
	v_mfma_f32_16x16x32_bf16 v[40:43], v[162:165], v[214:217], v[40:43]
	v_mfma_f32_16x16x32_bf16 v[28:31], v[154:157], v[222:225], v[28:31]
	v_mfma_f32_16x16x32_bf16 v[24:27], v[162:165], v[222:225], v[24:27]
	v_mfma_f32_16x16x32_bf16 v[12:15], v[154:157], v[230:233], v[12:15]
	v_mfma_f32_16x16x32_bf16 v[8:11], v[162:165], v[230:233], v[8:11]
	v_mfma_f32_16x16x32_bf16 v[60:63], v[158:161], v[210:213], v[60:63]
	v_mfma_f32_16x16x32_bf16 v[56:59], v[186:189], v[210:213], v[56:59]
	v_mfma_f32_16x16x32_bf16 v[44:47], v[158:161], v[218:221], v[44:47]
	v_mfma_f32_16x16x32_bf16 v[40:43], v[186:189], v[218:221], v[40:43]
	v_mfma_f32_16x16x32_bf16 v[28:31], v[158:161], v[226:229], v[28:31]
	v_mfma_f32_16x16x32_bf16 v[24:27], v[186:189], v[226:229], v[24:27]
	v_mfma_f32_16x16x32_bf16 v[12:15], v[158:161], v[234:237], v[12:15]
	v_mfma_f32_16x16x32_bf16 v[8:11], v[186:189], v[234:237], v[8:11]
	s_setprio 0
	s_setprio 1
	v_mfma_f32_16x16x32_bf16 v[52:55], v[190:193], v[206:209], v[52:55]
	v_mfma_f32_16x16x32_bf16 v[48:51], v[198:201], v[206:209], v[48:51]
	v_mfma_f32_16x16x32_bf16 v[36:39], v[190:193], v[214:217], v[36:39]
	v_mfma_f32_16x16x32_bf16 v[32:35], v[198:201], v[214:217], v[32:35]
	v_mfma_f32_16x16x32_bf16 v[20:23], v[190:193], v[222:225], v[20:23]
	v_mfma_f32_16x16x32_bf16 v[16:19], v[198:201], v[222:225], v[16:19]
	v_mfma_f32_16x16x32_bf16 v[4:7], v[190:193], v[230:233], v[4:7]
	v_mfma_f32_16x16x32_bf16 v[0:3], v[198:201], v[230:233], v[0:3]
	v_mfma_f32_16x16x32_bf16 v[52:55], v[194:197], v[210:213], v[52:55]
	v_mfma_f32_16x16x32_bf16 v[48:51], v[202:205], v[210:213], v[48:51]
	v_mfma_f32_16x16x32_bf16 v[36:39], v[194:197], v[218:221], v[36:39]
	v_mfma_f32_16x16x32_bf16 v[32:35], v[202:205], v[218:221], v[32:35]
	v_mfma_f32_16x16x32_bf16 v[20:23], v[194:197], v[226:229], v[20:23]
	v_mfma_f32_16x16x32_bf16 v[16:19], v[202:205], v[226:229], v[16:19]
	v_mfma_f32_16x16x32_bf16 v[4:7], v[194:197], v[234:237], v[4:7]
	v_mfma_f32_16x16x32_bf16 v[0:3], v[202:205], v[234:237], v[0:3]
	s_setprio 0
	s_barrier
	s_add_i32 s56, 0, 0x18000
	v_add_u32_e32 v185, s56, v139
	s_add_i32 s57, 0, 0x1c000
	ds_read_b128 v[154:157], v185
	ds_read_b128 v[158:161], v185 offset:1024
	ds_read_b128 v[162:165], v185 offset:2048
	ds_read_b128 v[186:189], v185 offset:3072
	v_add_u32_e32 v185, s57, v139
	ds_read_b128 v[190:193], v185
	ds_read_b128 v[194:197], v185 offset:1024
	ds_read_b128 v[198:201], v185 offset:2048
	ds_read_b128 v[202:205], v185 offset:3072
	s_add_u32 s26, s26, s6
	s_addc_u32 s27, s27, s7
	s_mov_b32 m0, s39
	v_lshl_add_u64 v[246:247], s[26:27], 0, v[132:133]
	ds_read_b128 v[206:209], v141 offset:32768
	ds_read_b128 v[210:213], v141 offset:33792
	ds_read_b128 v[214:217], v141 offset:34816
	ds_read_b128 v[218:221], v141 offset:35840
	ds_read_b128 v[222:225], v141 offset:36864
	ds_read_b128 v[226:229], v141 offset:37888
	ds_read_b128 v[230:233], v141 offset:38912
	ds_read_b128 v[234:237], v141 offset:39936
	global_load_lds_dwordx4 v[246:247], off
	v_lshl_add_u64 v[246:247], s[26:27], 0, v[130:131]
	s_mov_b32 m0, s40
	s_nop 0
	global_load_lds_dwordx4 v[246:247], off
	s_waitcnt vmcnt(8)
	s_waitcnt lgkmcnt(0)
	s_barrier
	s_setprio 1
	s_waitcnt lgkmcnt(0)
	v_mfma_f32_16x16x32_bf16 v[120:123], v[154:157], v[206:209], v[120:123]
	v_mfma_f32_16x16x32_bf16 v[124:127], v[162:165], v[206:209], v[124:127]
	v_mfma_f32_16x16x32_bf16 v[108:111], v[154:157], v[214:217], v[108:111]
	v_mfma_f32_16x16x32_bf16 v[104:107], v[162:165], v[214:217], v[104:107]
	v_mfma_f32_16x16x32_bf16 v[92:95], v[154:157], v[222:225], v[92:95]
	v_mfma_f32_16x16x32_bf16 v[88:91], v[162:165], v[222:225], v[88:91]
	v_mfma_f32_16x16x32_bf16 v[76:79], v[154:157], v[230:233], v[76:79]
	v_mfma_f32_16x16x32_bf16 v[72:75], v[162:165], v[230:233], v[72:75]
	v_mfma_f32_16x16x32_bf16 v[120:123], v[158:161], v[210:213], v[120:123]
	v_mfma_f32_16x16x32_bf16 v[124:127], v[186:189], v[210:213], v[124:127]
	v_mfma_f32_16x16x32_bf16 v[108:111], v[158:161], v[218:221], v[108:111]
	v_mfma_f32_16x16x32_bf16 v[104:107], v[186:189], v[218:221], v[104:107]
	v_mfma_f32_16x16x32_bf16 v[92:95], v[158:161], v[226:229], v[92:95]
	v_mfma_f32_16x16x32_bf16 v[88:91], v[186:189], v[226:229], v[88:91]
	v_mfma_f32_16x16x32_bf16 v[76:79], v[158:161], v[234:237], v[76:79]
	v_mfma_f32_16x16x32_bf16 v[72:75], v[186:189], v[234:237], v[72:75]
	s_setprio 0
	s_setprio 1
	v_mfma_f32_16x16x32_bf16 v[116:119], v[190:193], v[206:209], v[116:119]
	v_mfma_f32_16x16x32_bf16 v[112:115], v[198:201], v[206:209], v[112:115]
	v_mfma_f32_16x16x32_bf16 v[100:103], v[190:193], v[214:217], v[100:103]
	v_mfma_f32_16x16x32_bf16 v[96:99], v[198:201], v[214:217], v[96:99]
	v_mfma_f32_16x16x32_bf16 v[84:87], v[190:193], v[222:225], v[84:87]
	v_mfma_f32_16x16x32_bf16 v[80:83], v[198:201], v[222:225], v[80:83]
	v_mfma_f32_16x16x32_bf16 v[68:71], v[190:193], v[230:233], v[68:71]
	v_mfma_f32_16x16x32_bf16 v[64:67], v[198:201], v[230:233], v[64:67]
	v_mfma_f32_16x16x32_bf16 v[116:119], v[194:197], v[210:213], v[116:119]
	v_mfma_f32_16x16x32_bf16 v[112:115], v[202:205], v[210:213], v[112:115]
	v_mfma_f32_16x16x32_bf16 v[100:103], v[194:197], v[218:221], v[100:103]
	v_mfma_f32_16x16x32_bf16 v[96:99], v[202:205], v[218:221], v[96:99]
	v_mfma_f32_16x16x32_bf16 v[84:87], v[194:197], v[226:229], v[84:87]
	v_mfma_f32_16x16x32_bf16 v[80:83], v[202:205], v[226:229], v[80:83]
	v_mfma_f32_16x16x32_bf16 v[68:71], v[194:197], v[234:237], v[68:71]
	v_mfma_f32_16x16x32_bf16 v[64:67], v[202:205], v[234:237], v[64:67]
	s_setprio 0
	s_barrier
; #define PG8_STAGE(bufoff, gbase, voff) do { _Pragma("unroll") for (int _i = 0; _i < 2; ++_i) \
;         __builtin_amdgcn_global_load_lds((const unsigned*)((const char*)(gbase) + (voff)[_i]), (PG8_LAS unsigned*)(lds + (bufoff) + ldsw + _i * 8192), 16, 0, 0); } while (0)
; #define PG8_LDA(dst, b, h) do { _Pragma("unroll") for (int m = 0; m < 4; ++m) _Pragma("unroll") for (int k = 0; k < 2; ++k) dst[m][k] = *(const PG8_LAS bf16x8*)(lds + PG8_SA(b, h) + aoff + m * 2048 + k * 1024); } while (0)
; #define PG8_MMA(ai, bj, At, Bt) do { __builtin_amdgcn_s_setprio(1); _Pragma("unroll") for (int m = 0; m < 4; ++m) _Pragma("unroll") for (int n = 0; n < 2; ++n) _Pragma("unroll") for (int k = 0; k < 2; ++k) \
;         acc[ai][bj][m][n] = __builtin_amdgcn_mfma_f32_16x16x32_bf16(Bt[n][k], At[m][k], acc[ai][bj][m][n], 0, 0, 0); __builtin_amdgcn_s_setprio(0); } while (0)
; #define PG8_WAIT_V(n) asm volatile("s_waitcnt vmcnt(" #n ")" ::: "memory")
; #define PG8_WAIT_L(n) asm volatile("s_waitcnt lgkmcnt(" #n ")" ::: "memory")
; #define PG8_BAR __builtin_amdgcn_s_barrier()
; #define PG8_SCHED __builtin_amdgcn_sched_barrier(0)
; template <class Epi, class Sched>
; __device__ __forceinline__ void gemm_phase(int wid_s, PG8_LAS unsigned char* lds, const Gemm g, const Sched& S, const Epi& E) {
;     ...
;         for (int t = 0; t < nt; t += 2) {
;             const bool last = (t == nt - 2);
;             const char* a1 = cA + (size_t)(t + 1) * kstep;
;             const char* a2 = last ? nA : cA + (size_t)(t + 2) * kstep; const char* b2 = last ? nB : cB + (size_t)(t + 2) * kstep;
;     ...
;             PG8_LDA(At, 1, 1); PG8_STAGE(PG8_SB(1, 0), b3, voffB); PG8_STAGE(PG8_SB(1, 1), b3 + hstepB, voffB); PG8_STAGE(PG8_SA(1, 0), a3, voffA);
;             PG8_WAIT_V(8); PG8_WAIT_L(0); PG8_BAR; PG8_MMA(1, 0, At, B0); PG8_MMA(1, 1, At, B1); PG8_BAR; PG8_SCHED;
;         }
	s_add_i32 s26, s56, s34
	v_lshl_add_u64 v[142:143], v[142:143], 0, s[96:97]
	s_mov_b32 m0, s26
	ds_read_b128 v[206:209], v141 offset:49152
	ds_read_b128 v[210:213], v141 offset:50176
	ds_read_b128 v[214:217], v141 offset:51200
	ds_read_b128 v[218:221], v141 offset:52224
	ds_read_b128 v[222:225], v141 offset:53248
	ds_read_b128 v[226:229], v141 offset:54272
	ds_read_b128 v[230:233], v141 offset:55296
	ds_read_b128 v[234:237], v141 offset:56320
	global_load_lds_dwordx4 v[142:143], off
	v_lshl_add_u64 v[142:143], v[166:167], 0, s[96:97]
	s_add_i32 m0, s26, 0x2000
	s_add_i32 s26, s57, s34
	global_load_lds_dwordx4 v[142:143], off
	v_lshl_add_u64 v[142:143], v[238:239], 0, s[96:97]
	s_mov_b32 m0, s26
	s_nop 0
	global_load_lds_dwordx4 v[142:143], off
	v_lshl_add_u64 v[142:143], v[240:241], 0, s[96:97]
	s_add_i32 m0, s26, 0x2000
	s_nop 0
	global_load_lds_dwordx4 v[142:143], off
	v_lshl_add_u64 v[142:143], v[242:243], 0, s[96:97]
	s_mov_b32 m0, s46
	s_nop 0
	global_load_lds_dwordx4 v[142:143], off
	v_lshl_add_u64 v[142:143], v[244:245], 0, s[96:97]
	s_mov_b32 m0, s47
	s_nop 0
	global_load_lds_dwordx4 v[142:143], off
	s_waitcnt vmcnt(8)
	s_waitcnt lgkmcnt(0)
	s_barrier
	s_setprio 1
	s_waitcnt lgkmcnt(0)
	v_mfma_f32_16x16x32_bf16 v[60:63], v[154:157], v[206:209], v[60:63]
	v_mfma_f32_16x16x32_bf16 v[56:59], v[162:165], v[206:209], v[56:59]
	v_mfma_f32_16x16x32_bf16 v[44:47], v[154:157], v[214:217], v[44:47]
	v_mfma_f32_16x16x32_bf16 v[40:43], v[162:165], v[214:217], v[40:43]
	v_mfma_f32_16x16x32_bf16 v[28:31], v[154:157], v[222:225], v[28:31]
	v_mfma_f32_16x16x32_bf16 v[24:27], v[162:165], v[222:225], v[24:27]
	v_mfma_f32_16x16x32_bf16 v[12:15], v[154:157], v[230:233], v[12:15]
	v_mfma_f32_16x16x32_bf16 v[8:11], v[162:165], v[230:233], v[8:11]
	v_mfma_f32_16x16x32_bf16 v[60:63], v[158:161], v[210:213], v[60:63]
	v_mfma_f32_16x16x32_bf16 v[56:59], v[186:189], v[210:213], v[56:59]
	v_mfma_f32_16x16x32_bf16 v[44:47], v[158:161], v[218:221], v[44:47]
	v_mfma_f32_16x16x32_bf16 v[40:43], v[186:189], v[218:221], v[40:43]
	v_mfma_f32_16x16x32_bf16 v[28:31], v[158:161], v[226:229], v[28:31]
	v_mfma_f32_16x16x32_bf16 v[24:27], v[186:189], v[226:229], v[24:27]
	v_mfma_f32_16x16x32_bf16 v[12:15], v[158:161], v[234:237], v[12:15]
	v_mfma_f32_16x16x32_bf16 v[8:11], v[186:189], v[234:237], v[8:11]
	s_setprio 0
	s_setprio 1
	v_mfma_f32_16x16x32_bf16 v[52:55], v[190:193], v[206:209], v[52:55]
	s_add_u32 s33, s33, 0x100
	s_addc_u32 s54, s54, 0
	v_mfma_f32_16x16x32_bf16 v[48:51], v[198:201], v[206:209], v[48:51]
	s_add_u32 s24, s24, 0x100
	s_addc_u32 s25, s25, 0
	v_mfma_f32_16x16x32_bf16 v[36:39], v[190:193], v[214:217], v[36:39]
	s_cmp_ge_i32 s55, s41
	s_mov_b32 s26, s55
	s_cbranch_scc1 .Lmy_kx3
	v_mfma_f32_16x16x32_bf16 v[32:35], v[198:201], v[214:217], v[32:35]
	s_add_i32 s55, s26, 2
	v_mfma_f32_16x16x32_bf16 v[20:23], v[190:193], v[222:225], v[20:23]
	s_add_u32 s56, s24, 0x80
	v_mfma_f32_16x16x32_bf16 v[16:19], v[198:201], v[222:225], v[16:19]
	s_addc_u32 s27, s25, 0
	v_mfma_f32_16x16x32_bf16 v[4:7], v[190:193], v[230:233], v[4:7]
	s_add_i32 s92, 0, 0x10000
	v_mfma_f32_16x16x32_bf16 v[0:3], v[198:201], v[230:233], v[0:3]
	s_cmp_eq_u32 s48, s26
	v_mfma_f32_16x16x32_bf16 v[52:55], v[194:197], v[210:213], v[52:55]
	s_cselect_b32 s27, s5, s27
	v_mfma_f32_16x16x32_bf16 v[48:51], v[202:205], v[210:213], v[48:51]
	s_cselect_b32 s26, s4, s56
	v_mfma_f32_16x16x32_bf16 v[36:39], v[194:197], v[218:221], v[36:39]
	v_add_u32_e32 v142, s92, v139
	v_mfma_f32_16x16x32_bf16 v[32:35], v[202:205], v[218:221], v[32:35]
	s_cselect_b32 s57, s23, s54
	v_mfma_f32_16x16x32_bf16 v[20:23], v[194:197], v[226:229], v[20:23]
	s_cselect_b32 s56, s22, s33
	v_mfma_f32_16x16x32_bf16 v[16:19], v[202:205], v[226:229], v[16:19]
	s_add_i32 s94, 0, 0x14000
	v_mfma_f32_16x16x32_bf16 v[4:7], v[194:197], v[234:237], v[4:7]
	v_mfma_f32_16x16x32_bf16 v[0:3], v[202:205], v[234:237], v[0:3]
	s_setprio 0
	s_barrier
	s_branch .Lmy_kh3
.Lmy_kx3:
	v_mfma_f32_16x16x32_bf16 v[32:35], v[198:201], v[214:217], v[32:35]
	v_mfma_f32_16x16x32_bf16 v[20:23], v[190:193], v[222:225], v[20:23]
	v_mfma_f32_16x16x32_bf16 v[16:19], v[198:201], v[222:225], v[16:19]
	v_mfma_f32_16x16x32_bf16 v[4:7], v[190:193], v[230:233], v[4:7]
	v_mfma_f32_16x16x32_bf16 v[0:3], v[198:201], v[230:233], v[0:3]
	v_mfma_f32_16x16x32_bf16 v[52:55], v[194:197], v[210:213], v[52:55]
	v_mfma_f32_16x16x32_bf16 v[48:51], v[202:205], v[210:213], v[48:51]
	v_mfma_f32_16x16x32_bf16 v[36:39], v[194:197], v[218:221], v[36:39]
	v_mfma_f32_16x16x32_bf16 v[32:35], v[202:205], v[218:221], v[32:35]
	v_mfma_f32_16x16x32_bf16 v[20:23], v[194:197], v[226:229], v[20:23]
	v_mfma_f32_16x16x32_bf16 v[16:19], v[202:205], v[226:229], v[16:19]
	v_mfma_f32_16x16x32_bf16 v[4:7], v[194:197], v[234:237], v[4:7]
	v_mfma_f32_16x16x32_bf16 v[0:3], v[202:205], v[234:237], v[0:3]
	s_setprio 0
	s_barrier
	v_readlane_b32 s54, v254, 52
	v_readlane_b32 s55, v254, 53
	v_readlane_b32 s92, v254, 54
	v_readlane_b32 s94, v254, 55
	s_movk_i32 s33, 0xc00

; #define PG8_STAGE(bufoff, gbase, voff) do { _Pragma("unroll") for (int _i = 0; _i < 2; ++_i) \
;         __builtin_amdgcn_global_load_lds((const unsigned*)((const char*)(gbase) + (voff)[_i]), (PG8_LAS unsigned*)(lds + (bufoff) + ldsw + _i * 8192), 16, 0, 0); } while (0)
; #define PG8_LDA(dst, b, h) do { _Pragma("unroll") for (int m = 0; m < 4; ++m) _Pragma("unroll") for (int k = 0; k < 2; ++k) dst[m][k] = *(const PG8_LAS bf16x8*)(lds + PG8_SA(b, h) + aoff + m * 2048 + k * 1024); } while (0)
; #define PG8_LDB(dst, b, h) do { _Pragma("unroll") for (int n = 0; n < 2; ++n) _Pragma("unroll") for (int k = 0; k < 2; ++k) dst[n][k] = *(const PG8_LAS bf16x8*)(lds + PG8_SB(b, h) + boff + n * 2048 + k * 1024); } while (0)
; #define PG8_MMA(ai, bj, At, Bt) do { __builtin_amdgcn_s_setprio(1); _Pragma("unroll") for (int m = 0; m < 4; ++m) _Pragma("unroll") for (int n = 0; n < 2; ++n) _Pragma("unroll") for (int k = 0; k < 2; ++k) \
;         acc[ai][bj][m][n] = __builtin_amdgcn_mfma_f32_16x16x32_bf16(Bt[n][k], At[m][k], acc[ai][bj][m][n], 0, 0, 0); __builtin_amdgcn_s_setprio(0); } while (0)
; #define PG8_WAIT_V(n) asm volatile("s_waitcnt vmcnt(" #n ")" ::: "memory")
; #define PG8_WAIT_L(n) asm volatile("s_waitcnt lgkmcnt(" #n ")" ::: "memory")
; #define PG8_BAR __builtin_amdgcn_s_barrier()
; #define PG8_SCHED __builtin_amdgcn_sched_barrier(0)
; template <class Epi, class Sched>
; __device__ __forceinline__ void gemm_phase(int wid_s, PG8_LAS unsigned char* lds, const Gemm g, const Sched& S, const Epi& E) {
;     ...
;             PG8_LDB(B0, 0, 0); PG8_LDB(B1, 0, 1); PG8_SCHED; PG8_LDA(At, 0, 0); PG8_STAGE(PG8_SA(1, 1), a1 + hstepA, voffA);
;             PG8_WAIT_V(8); PG8_WAIT_L(0); PG8_BAR; PG8_MMA(0, 0, At, B0); PG8_MMA(0, 1, At, B1); PG8_BAR; PG8_SCHED;
;             PG8_LDA(At, 0, 1); PG8_STAGE(PG8_SB(0, 0), b2, voffB); PG8_STAGE(PG8_SB(0, 1), b2 + hstepB, voffB); PG8_STAGE(PG8_SA(0, 0), a2, voffA);
;             PG8_WAIT_V(8); PG8_WAIT_L(0); PG8_BAR; PG8_MMA(1, 0, At, B0); PG8_MMA(1, 1, At, B1); PG8_BAR; PG8_SCHED;
.Lmy_kh4:
	ds_read_b128 v[154:157], v166
	ds_read_b128 v[158:161], v166 offset:1024
	ds_read_b128 v[162:165], v166 offset:2048
	ds_read_b128 v[186:189], v166 offset:3072
	v_add_u32_e32 v166, s92, v141
	ds_read_b128 v[190:193], v166
	ds_read_b128 v[194:197], v166 offset:1024
	ds_read_b128 v[198:201], v166 offset:2048
	ds_read_b128 v[202:205], v166 offset:3072
	v_lshl_add_u64 v[166:167], s[26:27], 0, v[136:137]
	s_add_i32 m0, s37, 0xc000
	ds_read_b128 v[206:209], v143
	ds_read_b128 v[210:213], v143 offset:1024
	ds_read_b128 v[214:217], v143 offset:2048
	ds_read_b128 v[218:221], v143 offset:3072
	ds_read_b128 v[222:225], v143 offset:4096
	ds_read_b128 v[226:229], v143 offset:5120
	ds_read_b128 v[230:233], v143 offset:6144
	ds_read_b128 v[234:237], v143 offset:7168
	global_load_lds_dwordx4 v[166:167], off
	v_lshl_add_u64 v[166:167], s[26:27], 0, v[134:135]
	s_add_i32 m0, s37, 0xe000
	s_nop 0
	global_load_lds_dwordx4 v[166:167], off
	s_waitcnt vmcnt(8)
	s_waitcnt lgkmcnt(0)
	s_barrier
	s_setprio 1
	s_waitcnt lgkmcnt(0)
	v_mfma_f32_16x16x32_bf16 v[120:123], v[154:157], v[206:209], v[120:123]
	v_mfma_f32_16x16x32_bf16 v[124:127], v[162:165], v[206:209], v[124:127]
	v_mfma_f32_16x16x32_bf16 v[108:111], v[154:157], v[214:217], v[108:111]
	v_mfma_f32_16x16x32_bf16 v[104:107], v[162:165], v[214:217], v[104:107]
	v_mfma_f32_16x16x32_bf16 v[92:95], v[154:157], v[222:225], v[92:95]
	v_mfma_f32_16x16x32_bf16 v[88:91], v[162:165], v[222:225], v[88:91]
	v_mfma_f32_16x16x32_bf16 v[76:79], v[154:157], v[230:233], v[76:79]
	v_mfma_f32_16x16x32_bf16 v[72:75], v[162:165], v[230:233], v[72:75]
	v_mfma_f32_16x16x32_bf16 v[120:123], v[158:161], v[210:213], v[120:123]
	v_mfma_f32_16x16x32_bf16 v[124:127], v[186:189], v[210:213], v[124:127]
	v_mfma_f32_16x16x32_bf16 v[108:111], v[158:161], v[218:221], v[108:111]
	v_mfma_f32_16x16x32_bf16 v[104:107], v[186:189], v[218:221], v[104:107]
	v_mfma_f32_16x16x32_bf16 v[92:95], v[158:161], v[226:229], v[92:95]
	v_mfma_f32_16x16x32_bf16 v[88:91], v[186:189], v[226:229], v[88:91]
	v_mfma_f32_16x16x32_bf16 v[76:79], v[158:161], v[234:237], v[76:79]
	v_mfma_f32_16x16x32_bf16 v[72:75], v[186:189], v[234:237], v[72:75]
	s_setprio 0
	s_setprio 1
	v_mfma_f32_16x16x32_bf16 v[116:119], v[190:193], v[206:209], v[116:119]
	v_mfma_f32_16x16x32_bf16 v[112:115], v[198:201], v[206:209], v[112:115]
	v_mfma_f32_16x16x32_bf16 v[100:103], v[190:193], v[214:217], v[100:103]
	v_mfma_f32_16x16x32_bf16 v[96:99], v[198:201], v[214:217], v[96:99]
	v_mfma_f32_16x16x32_bf16 v[84:87], v[190:193], v[222:225], v[84:87]
	v_mfma_f32_16x16x32_bf16 v[80:83], v[198:201], v[222:225], v[80:83]
	v_mfma_f32_16x16x32_bf16 v[68:71], v[190:193], v[230:233], v[68:71]
	v_mfma_f32_16x16x32_bf16 v[64:67], v[198:201], v[230:233], v[64:67]
	v_mfma_f32_16x16x32_bf16 v[116:119], v[194:197], v[210:213], v[116:119]
	v_mfma_f32_16x16x32_bf16 v[112:115], v[202:205], v[210:213], v[112:115]
	v_mfma_f32_16x16x32_bf16 v[100:103], v[194:197], v[218:221], v[100:103]
	v_mfma_f32_16x16x32_bf16 v[96:99], v[202:205], v[218:221], v[96:99]
	v_mfma_f32_16x16x32_bf16 v[84:87], v[194:197], v[226:229], v[84:87]
	v_mfma_f32_16x16x32_bf16 v[80:83], v[202:205], v[226:229], v[80:83]
	v_mfma_f32_16x16x32_bf16 v[68:71], v[194:197], v[234:237], v[68:71]
	v_mfma_f32_16x16x32_bf16 v[64:67], v[202:205], v[234:237], v[64:67]
	s_setprio 0
	s_barrier
	s_add_i32 vcc_lo, vcc_lo, s35
	v_lshl_add_u64 v[166:167], s[94:95], 0, v[144:145]
	s_mov_b32 m0, vcc_lo
	ds_read_b128 v[206:209], v143 offset:16384
	ds_read_b128 v[210:213], v143 offset:17408
	ds_read_b128 v[214:217], v143 offset:18432
	ds_read_b128 v[218:221], v143 offset:19456
	ds_read_b128 v[222:225], v143 offset:20480
	ds_read_b128 v[226:229], v143 offset:21504
	ds_read_b128 v[230:233], v143 offset:22528
	ds_read_b128 v[234:237], v143 offset:23552
	global_load_lds_dwordx4 v[166:167], off
	s_add_i32 m0, vcc_lo, 0x2000
	v_lshl_add_u64 v[238:239], s[94:95], 0, v[128:129]
	s_add_u32 s94, s94, s6
	s_addc_u32 s95, s95, s7
	s_add_i32 s92, s92, s35
	global_load_lds_dwordx4 v[238:239], off
	v_lshl_add_u64 v[240:241], s[94:95], 0, v[144:145]
	s_mov_b32 m0, s92
	v_lshl_add_u64 v[242:243], s[94:95], 0, v[128:129]
	global_load_lds_dwordx4 v[240:241], off
	s_add_i32 m0, s92, 0x2000
	v_lshl_add_u64 v[244:245], s[28:29], 0, v[132:133]
	global_load_lds_dwordx4 v[242:243], off
	s_mov_b32 m0, s37
	v_lshl_add_u64 v[246:247], s[28:29], 0, v[130:131]
	global_load_lds_dwordx4 v[244:245], off
	s_mov_b32 m0, s39
	s_nop 0
	global_load_lds_dwordx4 v[246:247], off
	s_waitcnt vmcnt(8)
	s_waitcnt lgkmcnt(0)
	s_barrier
; #define PG8_STAGE(bufoff, gbase, voff) do { _Pragma("unroll") for (int _i = 0; _i < 2; ++_i) \
;         __builtin_amdgcn_global_load_lds((const unsigned*)((const char*)(gbase) + (voff)[_i]), (PG8_LAS unsigned*)(lds + (bufoff) + ldsw + _i * 8192), 16, 0, 0); } while (0)
; #define PG8_LDA(dst, b, h) do { _Pragma("unroll") for (int m = 0; m < 4; ++m) _Pragma("unroll") for (int k = 0; k < 2; ++k) dst[m][k] = *(const PG8_LAS bf16x8*)(lds + PG8_SA(b, h) + aoff + m * 2048 + k * 1024); } while (0)
; #define PG8_LDB(dst, b, h) do { _Pragma("unroll") for (int n = 0; n < 2; ++n) _Pragma("unroll") for (int k = 0; k < 2; ++k) dst[n][k] = *(const PG8_LAS bf16x8*)(lds + PG8_SB(b, h) + boff + n * 2048 + k * 1024); } while (0)
; #define PG8_MMA(ai, bj, At, Bt) do { __builtin_amdgcn_s_setprio(1); _Pragma("unroll") for (int m = 0; m < 4; ++m) _Pragma("unroll") for (int n = 0; n < 2; ++n) _Pragma("unroll") for (int k = 0; k < 2; ++k) \
;         acc[ai][bj][m][n] = __builtin_amdgcn_mfma_f32_16x16x32_bf16(Bt[n][k], At[m][k], acc[ai][bj][m][n], 0, 0, 0); __builtin_amdgcn_s_setprio(0); } while (0)
; #define PG8_WAIT_V(n) asm volatile("s_waitcnt vmcnt(" #n ")" ::: "memory")
; #define PG8_WAIT_L(n) asm volatile("s_waitcnt lgkmcnt(" #n ")" ::: "memory")
; #define PG8_BAR __builtin_amdgcn_s_barrier()
; #define PG8_SCHED __builtin_amdgcn_sched_barrier(0)
; template <class Epi, class Sched>
; __device__ __forceinline__ void gemm_phase(int wid_s, PG8_LAS unsigned char* lds, const Gemm g, const Sched& S, const Epi& E) {
;     ...
;             PG8_WAIT_V(8); PG8_WAIT_L(0); PG8_BAR; PG8_MMA(1, 0, At, B0); PG8_MMA(1, 1, At, B1); PG8_BAR; PG8_SCHED;
;             PG8_LDB(B0, 1, 0); PG8_LDB(B1, 1, 1); PG8_SCHED; PG8_LDA(At, 1, 0); PG8_STAGE(PG8_SA(0, 1), a2 + hstepA, voffA);
;             PG8_WAIT_V(8); PG8_WAIT_L(0); PG8_BAR; PG8_MMA(0, 0, At, B0); PG8_MMA(0, 1, At, B1); PG8_BAR; PG8_SCHED;
	s_setprio 1
	s_waitcnt lgkmcnt(0)
	v_mfma_f32_16x16x32_bf16 v[60:63], v[154:157], v[206:209], v[60:63]
	v_mfma_f32_16x16x32_bf16 v[56:59], v[162:165], v[206:209], v[56:59]
	v_mfma_f32_16x16x32_bf16 v[44:47], v[154:157], v[214:217], v[44:47]
	v_mfma_f32_16x16x32_bf16 v[40:43], v[162:165], v[214:217], v[40:43]
	v_mfma_f32_16x16x32_bf16 v[28:31], v[154:157], v[222:225], v[28:31]
	v_mfma_f32_16x16x32_bf16 v[24:27], v[162:165], v[222:225], v[24:27]
	v_mfma_f32_16x16x32_bf16 v[12:15], v[154:157], v[230:233], v[12:15]
	v_mfma_f32_16x16x32_bf16 v[8:11], v[162:165], v[230:233], v[8:11]
	v_mfma_f32_16x16x32_bf16 v[60:63], v[158:161], v[210:213], v[60:63]
	v_mfma_f32_16x16x32_bf16 v[56:59], v[186:189], v[210:213], v[56:59]
	v_mfma_f32_16x16x32_bf16 v[44:47], v[158:161], v[218:221], v[44:47]
	v_mfma_f32_16x16x32_bf16 v[40:43], v[186:189], v[218:221], v[40:43]
	v_mfma_f32_16x16x32_bf16 v[28:31], v[158:161], v[226:229], v[28:31]
	v_mfma_f32_16x16x32_bf16 v[24:27], v[186:189], v[226:229], v[24:27]
	v_mfma_f32_16x16x32_bf16 v[12:15], v[158:161], v[234:237], v[12:15]
	v_mfma_f32_16x16x32_bf16 v[8:11], v[186:189], v[234:237], v[8:11]
	s_setprio 0
	s_setprio 1
	v_mfma_f32_16x16x32_bf16 v[52:55], v[190:193], v[206:209], v[52:55]
	v_mfma_f32_16x16x32_bf16 v[48:51], v[198:201], v[206:209], v[48:51]
	v_mfma_f32_16x16x32_bf16 v[36:39], v[190:193], v[214:217], v[36:39]
	v_mfma_f32_16x16x32_bf16 v[32:35], v[198:201], v[214:217], v[32:35]
	v_mfma_f32_16x16x32_bf16 v[20:23], v[190:193], v[222:225], v[20:23]
	v_mfma_f32_16x16x32_bf16 v[16:19], v[198:201], v[222:225], v[16:19]
	v_mfma_f32_16x16x32_bf16 v[4:7], v[190:193], v[230:233], v[4:7]
	v_mfma_f32_16x16x32_bf16 v[0:3], v[198:201], v[230:233], v[0:3]
	v_mfma_f32_16x16x32_bf16 v[52:55], v[194:197], v[210:213], v[52:55]
	v_mfma_f32_16x16x32_bf16 v[48:51], v[202:205], v[210:213], v[48:51]
	v_mfma_f32_16x16x32_bf16 v[36:39], v[194:197], v[218:221], v[36:39]
	v_mfma_f32_16x16x32_bf16 v[32:35], v[202:205], v[218:221], v[32:35]
	v_mfma_f32_16x16x32_bf16 v[20:23], v[194:197], v[226:229], v[20:23]
	v_mfma_f32_16x16x32_bf16 v[16:19], v[202:205], v[226:229], v[16:19]
	v_mfma_f32_16x16x32_bf16 v[4:7], v[194:197], v[234:237], v[4:7]
	v_mfma_f32_16x16x32_bf16 v[0:3], v[202:205], v[234:237], v[0:3]
	s_setprio 0
	s_barrier
	s_add_i32 s92, 0, 0x18000
	v_add_u32_e32 v185, s92, v141
	s_add_i32 s94, 0, 0x1c000
	ds_read_b128 v[154:157], v185
	ds_read_b128 v[158:161], v185 offset:1024
	ds_read_b128 v[162:165], v185 offset:2048
	ds_read_b128 v[186:189], v185 offset:3072
	v_add_u32_e32 v185, s94, v141
	ds_read_b128 v[190:193], v185
	ds_read_b128 v[194:197], v185 offset:1024
	ds_read_b128 v[198:201], v185 offset:2048
	ds_read_b128 v[202:205], v185 offset:3072
	s_add_u32 s28, s28, s4
	s_addc_u32 s29, s29, s5
	s_mov_b32 m0, s40
	v_lshl_add_u64 v[248:249], s[28:29], 0, v[132:133]
	ds_read_b128 v[206:209], v143 offset:32768
	ds_read_b128 v[210:213], v143 offset:33792
	ds_read_b128 v[214:217], v143 offset:34816
	ds_read_b128 v[218:221], v143 offset:35840
	ds_read_b128 v[222:225], v143 offset:36864
	ds_read_b128 v[226:229], v143 offset:37888
	ds_read_b128 v[230:233], v143 offset:38912
	ds_read_b128 v[234:237], v143 offset:39936
	global_load_lds_dwordx4 v[248:249], off
	v_lshl_add_u64 v[248:249], s[28:29], 0, v[130:131]
	s_mov_b32 m0, s41
	s_nop 0
	global_load_lds_dwordx4 v[248:249], off
	s_waitcnt vmcnt(8)
	s_waitcnt lgkmcnt(0)
	s_barrier
	s_setprio 1
	s_waitcnt lgkmcnt(0)
	v_mfma_f32_16x16x32_bf16 v[120:123], v[154:157], v[206:209], v[120:123]
	v_mfma_f32_16x16x32_bf16 v[124:127], v[162:165], v[206:209], v[124:127]
	v_mfma_f32_16x16x32_bf16 v[108:111], v[154:157], v[214:217], v[108:111]
	v_mfma_f32_16x16x32_bf16 v[104:107], v[162:165], v[214:217], v[104:107]
	v_mfma_f32_16x16x32_bf16 v[92:95], v[154:157], v[222:225], v[92:95]
	v_mfma_f32_16x16x32_bf16 v[88:91], v[162:165], v[222:225], v[88:91]
	v_mfma_f32_16x16x32_bf16 v[76:79], v[154:157], v[230:233], v[76:79]
	v_mfma_f32_16x16x32_bf16 v[72:75], v[162:165], v[230:233], v[72:75]
	v_mfma_f32_16x16x32_bf16 v[120:123], v[158:161], v[210:213], v[120:123]
	v_mfma_f32_16x16x32_bf16 v[124:127], v[186:189], v[210:213], v[124:127]
	v_mfma_f32_16x16x32_bf16 v[108:111], v[158:161], v[218:221], v[108:111]
	v_mfma_f32_16x16x32_bf16 v[104:107], v[186:189], v[218:221], v[104:107]
	v_mfma_f32_16x16x32_bf16 v[92:95], v[158:161], v[226:229], v[92:95]
	v_mfma_f32_16x16x32_bf16 v[88:91], v[186:189], v[226:229], v[88:91]
	v_mfma_f32_16x16x32_bf16 v[76:79], v[158:161], v[234:237], v[76:79]
	v_mfma_f32_16x16x32_bf16 v[72:75], v[186:189], v[234:237], v[72:75]
	s_setprio 0
	s_setprio 1
	v_mfma_f32_16x16x32_bf16 v[116:119], v[190:193], v[206:209], v[116:119]
	v_mfma_f32_16x16x32_bf16 v[112:115], v[198:201], v[206:209], v[112:115]
	v_mfma_f32_16x16x32_bf16 v[100:103], v[190:193], v[214:217], v[100:103]
	v_mfma_f32_16x16x32_bf16 v[96:99], v[198:201], v[214:217], v[96:99]
	v_mfma_f32_16x16x32_bf16 v[84:87], v[190:193], v[222:225], v[84:87]
	v_mfma_f32_16x16x32_bf16 v[80:83], v[198:201], v[222:225], v[80:83]
	v_mfma_f32_16x16x32_bf16 v[68:71], v[190:193], v[230:233], v[68:71]
	v_mfma_f32_16x16x32_bf16 v[64:67], v[198:201], v[230:233], v[64:67]
	v_mfma_f32_16x16x32_bf16 v[116:119], v[194:197], v[210:213], v[116:119]
	v_mfma_f32_16x16x32_bf16 v[112:115], v[202:205], v[210:213], v[112:115]
	v_mfma_f32_16x16x32_bf16 v[100:103], v[194:197], v[218:221], v[100:103]
	v_mfma_f32_16x16x32_bf16 v[96:99], v[202:205], v[218:221], v[96:99]
	v_mfma_f32_16x16x32_bf16 v[84:87], v[194:197], v[226:229], v[84:87]
	v_mfma_f32_16x16x32_bf16 v[80:83], v[202:205], v[226:229], v[80:83]
	v_mfma_f32_16x16x32_bf16 v[68:71], v[194:197], v[234:237], v[68:71]
	v_mfma_f32_16x16x32_bf16 v[64:67], v[202:205], v[234:237], v[64:67]
	s_setprio 0
	s_barrier
; #define PG8_STAGE(bufoff, gbase, voff) do { _Pragma("unroll") for (int _i = 0; _i < 2; ++_i) \
;         __builtin_amdgcn_global_load_lds((const unsigned*)((const char*)(gbase) + (voff)[_i]), (PG8_LAS unsigned*)(lds + (bufoff) + ldsw + _i * 8192), 16, 0, 0); } while (0)
; #define PG8_LDA(dst, b, h) do { _Pragma("unroll") for (int m = 0; m < 4; ++m) _Pragma("unroll") for (int k = 0; k < 2; ++k) dst[m][k] = *(const PG8_LAS bf16x8*)(lds + PG8_SA(b, h) + aoff + m * 2048 + k * 1024); } while (0)
; #define PG8_MMA(ai, bj, At, Bt) do { __builtin_amdgcn_s_setprio(1); _Pragma("unroll") for (int m = 0; m < 4; ++m) _Pragma("unroll") for (int n = 0; n < 2; ++n) _Pragma("unroll") for (int k = 0; k < 2; ++k) \
;         acc[ai][bj][m][n] = __builtin_amdgcn_mfma_f32_16x16x32_bf16(Bt[n][k], At[m][k], acc[ai][bj][m][n], 0, 0, 0); __builtin_amdgcn_s_setprio(0); } while (0)
; #define PG8_WAIT_V(n) asm volatile("s_waitcnt vmcnt(" #n ")" ::: "memory")
; #define PG8_WAIT_L(n) asm volatile("s_waitcnt lgkmcnt(" #n ")" ::: "memory")
; #define PG8_BAR __builtin_amdgcn_s_barrier()
; #define PG8_SCHED __builtin_amdgcn_sched_barrier(0)
; template <class Epi, class Sched>
; __device__ __forceinline__ void gemm_phase(int wid_s, PG8_LAS unsigned char* lds, const Gemm g, const Sched& S, const Epi& E) {
;     ...
;         for (int t = 0; t < nt; t += 2) {
;             const bool last = (t == nt - 2);
;             const char* a1 = cA + (size_t)(t + 1) * kstep;
;             const char* a2 = last ? nA : cA + (size_t)(t + 2) * kstep; const char* b2 = last ? nB : cB + (size_t)(t + 2) * kstep;
;     ...
;             PG8_LDA(At, 1, 1); PG8_STAGE(PG8_SB(1, 0), b3, voffB); PG8_STAGE(PG8_SB(1, 1), b3 + hstepB, voffB); PG8_STAGE(PG8_SA(1, 0), a3, voffA);
;             PG8_WAIT_V(8); PG8_WAIT_L(0); PG8_BAR; PG8_MMA(1, 0, At, B0); PG8_MMA(1, 1, At, B1); PG8_BAR; PG8_SCHED;
;         }
	s_add_i32 s28, s92, s35
	v_lshl_add_u64 v[166:167], v[166:167], 0, s[96:97]
	s_mov_b32 m0, s28
	ds_read_b128 v[206:209], v143 offset:49152
	ds_read_b128 v[210:213], v143 offset:50176
	ds_read_b128 v[214:217], v143 offset:51200
	ds_read_b128 v[218:221], v143 offset:52224
	ds_read_b128 v[222:225], v143 offset:53248
	ds_read_b128 v[226:229], v143 offset:54272
	ds_read_b128 v[230:233], v143 offset:55296
	ds_read_b128 v[234:237], v143 offset:56320
	global_load_lds_dwordx4 v[166:167], off
	v_lshl_add_u64 v[166:167], v[238:239], 0, s[96:97]
	s_add_i32 m0, s28, 0x2000
	s_add_i32 s28, s94, s35
	global_load_lds_dwordx4 v[166:167], off
	v_lshl_add_u64 v[166:167], v[240:241], 0, s[96:97]
	s_mov_b32 m0, s28
	s_nop 0
	global_load_lds_dwordx4 v[166:167], off
	v_lshl_add_u64 v[166:167], v[242:243], 0, s[96:97]
	s_add_i32 m0, s28, 0x2000
	s_nop 0
	global_load_lds_dwordx4 v[166:167], off
	v_lshl_add_u64 v[166:167], v[244:245], 0, s[96:97]
	s_mov_b32 m0, s45
	s_nop 0
	global_load_lds_dwordx4 v[166:167], off
	v_lshl_add_u64 v[166:167], v[246:247], 0, s[96:97]
	s_mov_b32 m0, s46
	s_nop 0
	global_load_lds_dwordx4 v[166:167], off
	s_waitcnt vmcnt(8)
	s_waitcnt lgkmcnt(0)
	s_barrier
	s_setprio 1
	s_waitcnt lgkmcnt(0)
	v_mfma_f32_16x16x32_bf16 v[60:63], v[154:157], v[206:209], v[60:63]
	v_mfma_f32_16x16x32_bf16 v[56:59], v[162:165], v[206:209], v[56:59]
	v_mfma_f32_16x16x32_bf16 v[44:47], v[154:157], v[214:217], v[44:47]
	v_mfma_f32_16x16x32_bf16 v[40:43], v[162:165], v[214:217], v[40:43]
	v_mfma_f32_16x16x32_bf16 v[28:31], v[154:157], v[222:225], v[28:31]
	v_mfma_f32_16x16x32_bf16 v[24:27], v[162:165], v[222:225], v[24:27]
	v_mfma_f32_16x16x32_bf16 v[12:15], v[154:157], v[230:233], v[12:15]
	v_mfma_f32_16x16x32_bf16 v[8:11], v[162:165], v[230:233], v[8:11]
	v_mfma_f32_16x16x32_bf16 v[60:63], v[158:161], v[210:213], v[60:63]
	v_mfma_f32_16x16x32_bf16 v[56:59], v[186:189], v[210:213], v[56:59]
	v_mfma_f32_16x16x32_bf16 v[44:47], v[158:161], v[218:221], v[44:47]
	v_mfma_f32_16x16x32_bf16 v[40:43], v[186:189], v[218:221], v[40:43]
	v_mfma_f32_16x16x32_bf16 v[28:31], v[158:161], v[226:229], v[28:31]
	v_mfma_f32_16x16x32_bf16 v[24:27], v[186:189], v[226:229], v[24:27]
	v_mfma_f32_16x16x32_bf16 v[12:15], v[158:161], v[234:237], v[12:15]
	v_mfma_f32_16x16x32_bf16 v[8:11], v[186:189], v[234:237], v[8:11]
	s_setprio 0
	s_setprio 1
	v_mfma_f32_16x16x32_bf16 v[52:55], v[190:193], v[206:209], v[52:55]
	s_add_u32 s33, s33, 0x100
	s_addc_u32 s54, s54, 0
	v_mfma_f32_16x16x32_bf16 v[48:51], v[198:201], v[206:209], v[48:51]
	s_add_u32 s26, s26, 0x100
	s_addc_u32 s27, s27, 0
	v_mfma_f32_16x16x32_bf16 v[36:39], v[190:193], v[214:217], v[36:39]
	s_cmp_ge_i32 s55, s42
	s_mov_b32 s28, s55
	s_cbranch_scc1 .Lmy_kx4
	v_mfma_f32_16x16x32_bf16 v[32:35], v[198:201], v[214:217], v[32:35]
	s_add_i32 s55, s28, 2
	v_mfma_f32_16x16x32_bf16 v[20:23], v[190:193], v[222:225], v[20:23]
	s_add_u32 s92, s26, 0x80
	v_mfma_f32_16x16x32_bf16 v[16:19], v[198:201], v[222:225], v[16:19]
	s_addc_u32 s29, s27, 0
	v_mfma_f32_16x16x32_bf16 v[4:7], v[190:193], v[230:233], v[4:7]
	s_add_i32 vcc_lo, 0, 0x10000
	v_mfma_f32_16x16x32_bf16 v[0:3], v[198:201], v[230:233], v[0:3]
	s_cmp_eq_u32 s47, s28
	v_mfma_f32_16x16x32_bf16 v[52:55], v[194:197], v[210:213], v[52:55]
	s_cselect_b32 s29, s23, s29
	v_mfma_f32_16x16x32_bf16 v[48:51], v[202:205], v[210:213], v[48:51]
	s_cselect_b32 s28, s22, s92
	v_mfma_f32_16x16x32_bf16 v[36:39], v[194:197], v[218:221], v[36:39]
	v_add_u32_e32 v166, vcc_lo, v141
	v_mfma_f32_16x16x32_bf16 v[32:35], v[202:205], v[218:221], v[32:35]
	s_cselect_b32 s95, s25, s54
	v_mfma_f32_16x16x32_bf16 v[20:23], v[194:197], v[226:229], v[20:23]
	s_cselect_b32 s94, s24, s33
	v_mfma_f32_16x16x32_bf16 v[16:19], v[202:205], v[226:229], v[16:19]
	s_add_i32 s92, 0, 0x14000
	v_mfma_f32_16x16x32_bf16 v[4:7], v[194:197], v[234:237], v[4:7]
	v_mfma_f32_16x16x32_bf16 v[0:3], v[202:205], v[234:237], v[0:3]
	s_setprio 0
	s_barrier
	s_branch .Lmy_kh4
.Lmy_kx4:
	v_mfma_f32_16x16x32_bf16 v[32:35], v[198:201], v[214:217], v[32:35]
	v_mfma_f32_16x16x32_bf16 v[20:23], v[190:193], v[222:225], v[20:23]
	v_mfma_f32_16x16x32_bf16 v[16:19], v[198:201], v[222:225], v[16:19]
	v_mfma_f32_16x16x32_bf16 v[4:7], v[190:193], v[230:233], v[4:7]
	v_mfma_f32_16x16x32_bf16 v[0:3], v[198:201], v[230:233], v[0:3]
	v_mfma_f32_16x16x32_bf16 v[52:55], v[194:197], v[210:213], v[52:55]
	v_mfma_f32_16x16x32_bf16 v[48:51], v[202:205], v[210:213], v[48:51]
	v_mfma_f32_16x16x32_bf16 v[36:39], v[194:197], v[218:221], v[36:39]
	v_mfma_f32_16x16x32_bf16 v[32:35], v[202:205], v[218:221], v[32:35]
	v_mfma_f32_16x16x32_bf16 v[20:23], v[194:197], v[226:229], v[20:23]
	v_mfma_f32_16x16x32_bf16 v[16:19], v[202:205], v[226:229], v[16:19]
	v_mfma_f32_16x16x32_bf16 v[4:7], v[194:197], v[234:237], v[4:7]
	v_mfma_f32_16x16x32_bf16 v[0:3], v[202:205], v[234:237], v[0:3]
	s_setprio 0
	s_barrier
	v_readlane_b32 s54, v254, 52
	v_readlane_b32 s95, v254, 51
	v_readlane_b32 s55, v254, 53
	v_readlane_b32 s92, v254, 54
	v_readlane_b32 s94, v254, 55
	s_movk_i32 s33, 0x300

; #define PG8_STAGE(bufoff, gbase, voff) do { _Pragma("unroll") for (int _i = 0; _i < 2; ++_i) \
;         __builtin_amdgcn_global_load_lds((const unsigned*)((const char*)(gbase) + (voff)[_i]), (PG8_LAS unsigned*)(lds + (bufoff) + ldsw + _i * 8192), 16, 0, 0); } while (0)
; #define PG8_LDA(dst, b, h) do { _Pragma("unroll") for (int m = 0; m < 4; ++m) _Pragma("unroll") for (int k = 0; k < 2; ++k) dst[m][k] = *(const PG8_LAS bf16x8*)(lds + PG8_SA(b, h) + aoff + m * 2048 + k * 1024); } while (0)
; #define PG8_LDB(dst, b, h) do { _Pragma("unroll") for (int n = 0; n < 2; ++n) _Pragma("unroll") for (int k = 0; k < 2; ++k) dst[n][k] = *(const PG8_LAS bf16x8*)(lds + PG8_SB(b, h) + boff + n * 2048 + k * 1024); } while (0)
; #define PG8_MMA(ai, bj, At, Bt) do { __builtin_amdgcn_s_setprio(1); _Pragma("unroll") for (int m = 0; m < 4; ++m) _Pragma("unroll") for (int n = 0; n < 2; ++n) _Pragma("unroll") for (int k = 0; k < 2; ++k) \
;         acc[ai][bj][m][n] = __builtin_amdgcn_mfma_f32_16x16x32_bf16(Bt[n][k], At[m][k], acc[ai][bj][m][n], 0, 0, 0); __builtin_amdgcn_s_setprio(0); } while (0)
; #define PG8_WAIT_V(n) asm volatile("s_waitcnt vmcnt(" #n ")" ::: "memory")
; #define PG8_WAIT_L(n) asm volatile("s_waitcnt lgkmcnt(" #n ")" ::: "memory")
; #define PG8_BAR __builtin_amdgcn_s_barrier()
; #define PG8_SCHED __builtin_amdgcn_sched_barrier(0)
; template <class Epi, class Sched>
; __device__ __forceinline__ void gemm_phase(int wid_s, PG8_LAS unsigned char* lds, const Gemm g, const Sched& S, const Epi& E) {
;     ...
;             PG8_LDB(B0, 0, 0); PG8_LDB(B1, 0, 1); PG8_SCHED; PG8_LDA(At, 0, 0); PG8_STAGE(PG8_SA(1, 1), a1 + hstepA, voffA);
;             PG8_WAIT_V(8); PG8_WAIT_L(0); PG8_BAR; PG8_MMA(0, 0, At, B0); PG8_MMA(0, 1, At, B1); PG8_BAR; PG8_SCHED;
;             PG8_LDA(At, 0, 1); PG8_STAGE(PG8_SB(0, 0), b2, voffB); PG8_STAGE(PG8_SB(0, 1), b2 + hstepB, voffB); PG8_STAGE(PG8_SA(0, 0), a2, voffA);
;             PG8_WAIT_V(8); PG8_WAIT_L(0); PG8_BAR; PG8_MMA(1, 0, At, B0); PG8_MMA(1, 1, At, B1); PG8_BAR; PG8_SCHED;
.Lmy_kh6:
	ds_read_b128 v[138:141], v142
	ds_read_b128 v[160:163], v142 offset:1024
	ds_read_b128 v[164:167], v142 offset:2048
	ds_read_b128 v[192:195], v142 offset:3072
	v_add_u32_e32 v142, vcc_hi, v157
	ds_read_b128 v[196:199], v142
	ds_read_b128 v[200:203], v142 offset:1024
	ds_read_b128 v[204:207], v142 offset:2048
	ds_read_b128 v[208:211], v142 offset:3072
	v_lshl_add_u64 v[142:143], s[2:3], 0, v[136:137]
	s_add_i32 m0, s36, 0xc000
	ds_read_b128 v[212:215], v159
	ds_read_b128 v[216:219], v159 offset:1024
	ds_read_b128 v[220:223], v159 offset:2048
	ds_read_b128 v[224:227], v159 offset:3072
	ds_read_b128 v[228:231], v159 offset:4096
	ds_read_b128 v[232:235], v159 offset:5120
	ds_read_b128 v[236:239], v159 offset:6144
	ds_read_b128 v[240:243], v159 offset:7168
	global_load_lds_dwordx4 v[142:143], off
	v_lshl_add_u64 v[142:143], s[2:3], 0, v[134:135]
	s_add_i32 m0, s36, 0xe000
	s_nop 0
	global_load_lds_dwordx4 v[142:143], off
	s_waitcnt vmcnt(8)
	s_waitcnt lgkmcnt(0)
	s_barrier
	s_setprio 1
	s_waitcnt lgkmcnt(0)
	v_mfma_f32_16x16x32_bf16 v[124:127], v[138:141], v[212:215], v[124:127]
	v_mfma_f32_16x16x32_bf16 v[120:123], v[164:167], v[212:215], v[120:123]
	v_mfma_f32_16x16x32_bf16 v[108:111], v[138:141], v[220:223], v[108:111]
	v_mfma_f32_16x16x32_bf16 v[104:107], v[164:167], v[220:223], v[104:107]
	v_mfma_f32_16x16x32_bf16 v[92:95], v[138:141], v[228:231], v[92:95]
	v_mfma_f32_16x16x32_bf16 v[88:91], v[164:167], v[228:231], v[88:91]
	v_mfma_f32_16x16x32_bf16 v[76:79], v[138:141], v[236:239], v[76:79]
	v_mfma_f32_16x16x32_bf16 v[72:75], v[164:167], v[236:239], v[72:75]
	v_mfma_f32_16x16x32_bf16 v[124:127], v[160:163], v[216:219], v[124:127]
	v_mfma_f32_16x16x32_bf16 v[120:123], v[192:195], v[216:219], v[120:123]
	v_mfma_f32_16x16x32_bf16 v[108:111], v[160:163], v[224:227], v[108:111]
	v_mfma_f32_16x16x32_bf16 v[104:107], v[192:195], v[224:227], v[104:107]
	v_mfma_f32_16x16x32_bf16 v[92:95], v[160:163], v[232:235], v[92:95]
	v_mfma_f32_16x16x32_bf16 v[88:91], v[192:195], v[232:235], v[88:91]
	v_mfma_f32_16x16x32_bf16 v[76:79], v[160:163], v[240:243], v[76:79]
	v_mfma_f32_16x16x32_bf16 v[72:75], v[192:195], v[240:243], v[72:75]
	s_setprio 0
	s_setprio 1
	v_mfma_f32_16x16x32_bf16 v[116:119], v[196:199], v[212:215], v[116:119]
	v_mfma_f32_16x16x32_bf16 v[112:115], v[204:207], v[212:215], v[112:115]
	v_mfma_f32_16x16x32_bf16 v[100:103], v[196:199], v[220:223], v[100:103]
	v_mfma_f32_16x16x32_bf16 v[96:99], v[204:207], v[220:223], v[96:99]
	v_mfma_f32_16x16x32_bf16 v[84:87], v[196:199], v[228:231], v[84:87]
	v_mfma_f32_16x16x32_bf16 v[80:83], v[204:207], v[228:231], v[80:83]
	v_mfma_f32_16x16x32_bf16 v[68:71], v[196:199], v[236:239], v[68:71]
	v_mfma_f32_16x16x32_bf16 v[64:67], v[204:207], v[236:239], v[64:67]
	v_mfma_f32_16x16x32_bf16 v[116:119], v[200:203], v[216:219], v[116:119]
	v_mfma_f32_16x16x32_bf16 v[112:115], v[208:211], v[216:219], v[112:115]
	v_mfma_f32_16x16x32_bf16 v[100:103], v[200:203], v[224:227], v[100:103]
	v_mfma_f32_16x16x32_bf16 v[96:99], v[208:211], v[224:227], v[96:99]
	v_mfma_f32_16x16x32_bf16 v[84:87], v[200:203], v[232:235], v[84:87]
	v_mfma_f32_16x16x32_bf16 v[80:83], v[208:211], v[232:235], v[80:83]
	v_mfma_f32_16x16x32_bf16 v[68:71], v[200:203], v[240:243], v[68:71]
	v_mfma_f32_16x16x32_bf16 v[64:67], v[208:211], v[240:243], v[64:67]
	s_setprio 0
	s_barrier
	s_add_i32 vcc_lo, vcc_lo, s19
	v_lshl_add_u64 v[142:143], s[52:53], 0, v[144:145]
	s_mov_b32 m0, vcc_lo
	ds_read_b128 v[212:215], v159 offset:16384
	ds_read_b128 v[216:219], v159 offset:17408
	ds_read_b128 v[220:223], v159 offset:18432
	ds_read_b128 v[224:227], v159 offset:19456
	ds_read_b128 v[228:231], v159 offset:20480
	ds_read_b128 v[232:235], v159 offset:21504
	ds_read_b128 v[236:239], v159 offset:22528
	ds_read_b128 v[240:243], v159 offset:23552
	global_load_lds_dwordx4 v[142:143], off
	s_add_i32 m0, vcc_lo, 0x2000
	v_lshl_add_u64 v[154:155], s[52:53], 0, v[132:133]
	s_add_u32 s52, s52, s6
	s_addc_u32 s53, s53, s7
	s_add_i32 vcc_lo, vcc_hi, s19
	global_load_lds_dwordx4 v[154:155], off
	v_lshl_add_u64 v[244:245], s[52:53], 0, v[144:145]
	s_mov_b32 m0, vcc_lo
	v_lshl_add_u64 v[246:247], s[52:53], 0, v[132:133]
	global_load_lds_dwordx4 v[244:245], off
	s_add_i32 m0, vcc_lo, 0x2000
	v_lshl_add_u64 v[248:249], s[46:47], 0, v[128:129]
	global_load_lds_dwordx4 v[246:247], off
	s_mov_b32 m0, s36
	v_lshl_add_u64 v[250:251], s[46:47], 0, v[130:131]
	global_load_lds_dwordx4 v[248:249], off
	s_mov_b32 m0, s37
	s_nop 0
	global_load_lds_dwordx4 v[250:251], off
	s_waitcnt vmcnt(8)
	s_waitcnt lgkmcnt(0)
	s_barrier
; #define PG8_STAGE(bufoff, gbase, voff) do { _Pragma("unroll") for (int _i = 0; _i < 2; ++_i) \
;         __builtin_amdgcn_global_load_lds((const unsigned*)((const char*)(gbase) + (voff)[_i]), (PG8_LAS unsigned*)(lds + (bufoff) + ldsw + _i * 8192), 16, 0, 0); } while (0)
; #define PG8_LDA(dst, b, h) do { _Pragma("unroll") for (int m = 0; m < 4; ++m) _Pragma("unroll") for (int k = 0; k < 2; ++k) dst[m][k] = *(const PG8_LAS bf16x8*)(lds + PG8_SA(b, h) + aoff + m * 2048 + k * 1024); } while (0)
; #define PG8_LDB(dst, b, h) do { _Pragma("unroll") for (int n = 0; n < 2; ++n) _Pragma("unroll") for (int k = 0; k < 2; ++k) dst[n][k] = *(const PG8_LAS bf16x8*)(lds + PG8_SB(b, h) + boff + n * 2048 + k * 1024); } while (0)
; #define PG8_MMA(ai, bj, At, Bt) do { __builtin_amdgcn_s_setprio(1); _Pragma("unroll") for (int m = 0; m < 4; ++m) _Pragma("unroll") for (int n = 0; n < 2; ++n) _Pragma("unroll") for (int k = 0; k < 2; ++k) \
;         acc[ai][bj][m][n] = __builtin_amdgcn_mfma_f32_16x16x32_bf16(Bt[n][k], At[m][k], acc[ai][bj][m][n], 0, 0, 0); __builtin_amdgcn_s_setprio(0); } while (0)
; #define PG8_WAIT_V(n) asm volatile("s_waitcnt vmcnt(" #n ")" ::: "memory")
; #define PG8_WAIT_L(n) asm volatile("s_waitcnt lgkmcnt(" #n ")" ::: "memory")
; #define PG8_BAR __builtin_amdgcn_s_barrier()
; #define PG8_SCHED __builtin_amdgcn_sched_barrier(0)
; template <class Epi, class Sched>
; __device__ __forceinline__ void gemm_phase(int wid_s, PG8_LAS unsigned char* lds, const Gemm g, const Sched& S, const Epi& E) {
;     ...
;             PG8_WAIT_V(8); PG8_WAIT_L(0); PG8_BAR; PG8_MMA(1, 0, At, B0); PG8_MMA(1, 1, At, B1); PG8_BAR; PG8_SCHED;
;             PG8_LDB(B0, 1, 0); PG8_LDB(B1, 1, 1); PG8_SCHED; PG8_LDA(At, 1, 0); PG8_STAGE(PG8_SA(0, 1), a2 + hstepA, voffA);
;             PG8_WAIT_V(8); PG8_WAIT_L(0); PG8_BAR; PG8_MMA(0, 0, At, B0); PG8_MMA(0, 1, At, B1); PG8_BAR; PG8_SCHED;
	s_setprio 1
	s_waitcnt lgkmcnt(0)
	v_mfma_f32_16x16x32_bf16 v[60:63], v[138:141], v[212:215], v[60:63]
	v_mfma_f32_16x16x32_bf16 v[56:59], v[164:167], v[212:215], v[56:59]
	v_mfma_f32_16x16x32_bf16 v[44:47], v[138:141], v[220:223], v[44:47]
	v_mfma_f32_16x16x32_bf16 v[40:43], v[164:167], v[220:223], v[40:43]
	v_mfma_f32_16x16x32_bf16 v[28:31], v[138:141], v[228:231], v[28:31]
	v_mfma_f32_16x16x32_bf16 v[24:27], v[164:167], v[228:231], v[24:27]
	v_mfma_f32_16x16x32_bf16 v[12:15], v[138:141], v[236:239], v[12:15]
	v_mfma_f32_16x16x32_bf16 v[8:11], v[164:167], v[236:239], v[8:11]
	v_mfma_f32_16x16x32_bf16 v[60:63], v[160:163], v[216:219], v[60:63]
	v_mfma_f32_16x16x32_bf16 v[56:59], v[192:195], v[216:219], v[56:59]
	v_mfma_f32_16x16x32_bf16 v[44:47], v[160:163], v[224:227], v[44:47]
	v_mfma_f32_16x16x32_bf16 v[40:43], v[192:195], v[224:227], v[40:43]
	v_mfma_f32_16x16x32_bf16 v[28:31], v[160:163], v[232:235], v[28:31]
	v_mfma_f32_16x16x32_bf16 v[24:27], v[192:195], v[232:235], v[24:27]
	v_mfma_f32_16x16x32_bf16 v[12:15], v[160:163], v[240:243], v[12:15]
	v_mfma_f32_16x16x32_bf16 v[8:11], v[192:195], v[240:243], v[8:11]
	s_setprio 0
	s_setprio 1
	v_mfma_f32_16x16x32_bf16 v[52:55], v[196:199], v[212:215], v[52:55]
	v_mfma_f32_16x16x32_bf16 v[48:51], v[204:207], v[212:215], v[48:51]
	v_mfma_f32_16x16x32_bf16 v[36:39], v[196:199], v[220:223], v[36:39]
	v_mfma_f32_16x16x32_bf16 v[32:35], v[204:207], v[220:223], v[32:35]
	v_mfma_f32_16x16x32_bf16 v[20:23], v[196:199], v[228:231], v[20:23]
	v_mfma_f32_16x16x32_bf16 v[16:19], v[204:207], v[228:231], v[16:19]
	v_mfma_f32_16x16x32_bf16 v[4:7], v[196:199], v[236:239], v[4:7]
	v_mfma_f32_16x16x32_bf16 v[0:3], v[204:207], v[236:239], v[0:3]
	v_mfma_f32_16x16x32_bf16 v[52:55], v[200:203], v[216:219], v[52:55]
	v_mfma_f32_16x16x32_bf16 v[48:51], v[208:211], v[216:219], v[48:51]
	v_mfma_f32_16x16x32_bf16 v[36:39], v[200:203], v[224:227], v[36:39]
	v_mfma_f32_16x16x32_bf16 v[32:35], v[208:211], v[224:227], v[32:35]
	v_mfma_f32_16x16x32_bf16 v[20:23], v[200:203], v[232:235], v[20:23]
	v_mfma_f32_16x16x32_bf16 v[16:19], v[208:211], v[232:235], v[16:19]
	v_mfma_f32_16x16x32_bf16 v[4:7], v[200:203], v[240:243], v[4:7]
	v_mfma_f32_16x16x32_bf16 v[0:3], v[208:211], v[240:243], v[0:3]
	s_setprio 0
	s_barrier
	s_add_i32 s52, 0, 0x18000
	v_add_u32_e32 v188, s52, v157
	s_add_i32 s53, 0, 0x1c000
	ds_read_b128 v[138:141], v188
	ds_read_b128 v[160:163], v188 offset:1024
	ds_read_b128 v[164:167], v188 offset:2048
	ds_read_b128 v[192:195], v188 offset:3072
	v_add_u32_e32 v188, s53, v157
	ds_read_b128 v[196:199], v188
	ds_read_b128 v[200:203], v188 offset:1024
	ds_read_b128 v[204:207], v188 offset:2048
	ds_read_b128 v[208:211], v188 offset:3072
	s_add_u32 s46, s46, s4
	s_addc_u32 s47, s47, s5
	s_mov_b32 m0, s39
	v_lshl_add_u64 v[252:253], s[46:47], 0, v[128:129]
	ds_read_b128 v[212:215], v159 offset:32768
	ds_read_b128 v[216:219], v159 offset:33792
	ds_read_b128 v[220:223], v159 offset:34816
	ds_read_b128 v[224:227], v159 offset:35840
	ds_read_b128 v[228:231], v159 offset:36864
	ds_read_b128 v[232:235], v159 offset:37888
	ds_read_b128 v[236:239], v159 offset:38912
	ds_read_b128 v[240:243], v159 offset:39936
	global_load_lds_dwordx4 v[252:253], off
	v_lshl_add_u64 v[252:253], s[46:47], 0, v[130:131]
	s_mov_b32 m0, s40
	s_nop 0
	global_load_lds_dwordx4 v[252:253], off
	s_waitcnt vmcnt(8)
	s_waitcnt lgkmcnt(0)
	s_barrier
	s_setprio 1
	s_waitcnt lgkmcnt(0)
	v_mfma_f32_16x16x32_bf16 v[124:127], v[138:141], v[212:215], v[124:127]
	v_mfma_f32_16x16x32_bf16 v[120:123], v[164:167], v[212:215], v[120:123]
	v_mfma_f32_16x16x32_bf16 v[108:111], v[138:141], v[220:223], v[108:111]
	v_mfma_f32_16x16x32_bf16 v[104:107], v[164:167], v[220:223], v[104:107]
	v_mfma_f32_16x16x32_bf16 v[92:95], v[138:141], v[228:231], v[92:95]
	v_mfma_f32_16x16x32_bf16 v[88:91], v[164:167], v[228:231], v[88:91]
	v_mfma_f32_16x16x32_bf16 v[76:79], v[138:141], v[236:239], v[76:79]
	v_mfma_f32_16x16x32_bf16 v[72:75], v[164:167], v[236:239], v[72:75]
	v_mfma_f32_16x16x32_bf16 v[124:127], v[160:163], v[216:219], v[124:127]
	v_mfma_f32_16x16x32_bf16 v[120:123], v[192:195], v[216:219], v[120:123]
	v_mfma_f32_16x16x32_bf16 v[108:111], v[160:163], v[224:227], v[108:111]
	v_mfma_f32_16x16x32_bf16 v[104:107], v[192:195], v[224:227], v[104:107]
	v_mfma_f32_16x16x32_bf16 v[92:95], v[160:163], v[232:235], v[92:95]
	v_mfma_f32_16x16x32_bf16 v[88:91], v[192:195], v[232:235], v[88:91]
	v_mfma_f32_16x16x32_bf16 v[76:79], v[160:163], v[240:243], v[76:79]
	v_mfma_f32_16x16x32_bf16 v[72:75], v[192:195], v[240:243], v[72:75]
	s_setprio 0
	s_setprio 1
	v_mfma_f32_16x16x32_bf16 v[116:119], v[196:199], v[212:215], v[116:119]
	v_mfma_f32_16x16x32_bf16 v[112:115], v[204:207], v[212:215], v[112:115]
	v_mfma_f32_16x16x32_bf16 v[100:103], v[196:199], v[220:223], v[100:103]
	v_mfma_f32_16x16x32_bf16 v[96:99], v[204:207], v[220:223], v[96:99]
	v_mfma_f32_16x16x32_bf16 v[84:87], v[196:199], v[228:231], v[84:87]
	v_mfma_f32_16x16x32_bf16 v[80:83], v[204:207], v[228:231], v[80:83]
	v_mfma_f32_16x16x32_bf16 v[68:71], v[196:199], v[236:239], v[68:71]
	v_mfma_f32_16x16x32_bf16 v[64:67], v[204:207], v[236:239], v[64:67]
	v_mfma_f32_16x16x32_bf16 v[116:119], v[200:203], v[216:219], v[116:119]
	v_mfma_f32_16x16x32_bf16 v[112:115], v[208:211], v[216:219], v[112:115]
	v_mfma_f32_16x16x32_bf16 v[100:103], v[200:203], v[224:227], v[100:103]
	v_mfma_f32_16x16x32_bf16 v[96:99], v[208:211], v[224:227], v[96:99]
	v_mfma_f32_16x16x32_bf16 v[84:87], v[200:203], v[232:235], v[84:87]
	v_mfma_f32_16x16x32_bf16 v[80:83], v[208:211], v[232:235], v[80:83]
	v_mfma_f32_16x16x32_bf16 v[68:71], v[200:203], v[240:243], v[68:71]
	v_mfma_f32_16x16x32_bf16 v[64:67], v[208:211], v[240:243], v[64:67]
	s_setprio 0
	s_barrier
; #define PG8_STAGE(bufoff, gbase, voff) do { _Pragma("unroll") for (int _i = 0; _i < 2; ++_i) \
;         __builtin_amdgcn_global_load_lds((const unsigned*)((const char*)(gbase) + (voff)[_i]), (PG8_LAS unsigned*)(lds + (bufoff) + ldsw + _i * 8192), 16, 0, 0); } while (0)
; #define PG8_LDA(dst, b, h) do { _Pragma("unroll") for (int m = 0; m < 4; ++m) _Pragma("unroll") for (int k = 0; k < 2; ++k) dst[m][k] = *(const PG8_LAS bf16x8*)(lds + PG8_SA(b, h) + aoff + m * 2048 + k * 1024); } while (0)
; #define PG8_MMA(ai, bj, At, Bt) do { __builtin_amdgcn_s_setprio(1); _Pragma("unroll") for (int m = 0; m < 4; ++m) _Pragma("unroll") for (int n = 0; n < 2; ++n) _Pragma("unroll") for (int k = 0; k < 2; ++k) \
;         acc[ai][bj][m][n] = __builtin_amdgcn_mfma_f32_16x16x32_bf16(Bt[n][k], At[m][k], acc[ai][bj][m][n], 0, 0, 0); __builtin_amdgcn_s_setprio(0); } while (0)
; #define PG8_WAIT_V(n) asm volatile("s_waitcnt vmcnt(" #n ")" ::: "memory")
; #define PG8_WAIT_L(n) asm volatile("s_waitcnt lgkmcnt(" #n ")" ::: "memory")
; #define PG8_BAR __builtin_amdgcn_s_barrier()
; #define PG8_SCHED __builtin_amdgcn_sched_barrier(0)
; template <class Epi, class Sched>
; __device__ __forceinline__ void gemm_phase(int wid_s, PG8_LAS unsigned char* lds, const Gemm g, const Sched& S, const Epi& E) {
;     ...
;         for (int t = 0; t < nt; t += 2) {
;             const bool last = (t == nt - 2);
;             const char* a1 = cA + (size_t)(t + 1) * kstep;
;             const char* a2 = last ? nA : cA + (size_t)(t + 2) * kstep; const char* b2 = last ? nB : cB + (size_t)(t + 2) * kstep;
;     ...
;             PG8_LDA(At, 1, 1); PG8_STAGE(PG8_SB(1, 0), b3, voffB); PG8_STAGE(PG8_SB(1, 1), b3 + hstepB, voffB); PG8_STAGE(PG8_SA(1, 0), a3, voffA);
;             PG8_WAIT_V(8); PG8_WAIT_L(0); PG8_BAR; PG8_MMA(1, 0, At, B0); PG8_MMA(1, 1, At, B1); PG8_BAR; PG8_SCHED;
;         }
	s_add_i32 s46, s52, s19
	v_lshl_add_u64 v[142:143], v[142:143], 0, s[96:97]
	s_mov_b32 m0, s46
	ds_read_b128 v[212:215], v159 offset:49152
	ds_read_b128 v[216:219], v159 offset:50176
	ds_read_b128 v[220:223], v159 offset:51200
	ds_read_b128 v[224:227], v159 offset:52224
	ds_read_b128 v[228:231], v159 offset:53248
	ds_read_b128 v[232:235], v159 offset:54272
	ds_read_b128 v[236:239], v159 offset:55296
	ds_read_b128 v[240:243], v159 offset:56320
	global_load_lds_dwordx4 v[142:143], off
	v_lshl_add_u64 v[142:143], v[154:155], 0, s[96:97]
	s_add_i32 m0, s46, 0x2000
	s_add_i32 s46, s53, s19
	global_load_lds_dwordx4 v[142:143], off
	v_lshl_add_u64 v[142:143], v[244:245], 0, s[96:97]
	s_mov_b32 m0, s46
	s_nop 0
	global_load_lds_dwordx4 v[142:143], off
	v_lshl_add_u64 v[142:143], v[246:247], 0, s[96:97]
	s_add_i32 m0, s46, 0x2000
	s_nop 0
	global_load_lds_dwordx4 v[142:143], off
	v_lshl_add_u64 v[142:143], v[248:249], 0, s[96:97]
	s_mov_b32 m0, s54
	s_nop 0
	global_load_lds_dwordx4 v[142:143], off
	v_lshl_add_u64 v[142:143], v[250:251], 0, s[96:97]
	s_mov_b32 m0, s55
	s_nop 0
	global_load_lds_dwordx4 v[142:143], off
	s_waitcnt vmcnt(8)
	s_waitcnt lgkmcnt(0)
	s_barrier
	s_setprio 1
	s_waitcnt lgkmcnt(0)
	v_mfma_f32_16x16x32_bf16 v[60:63], v[138:141], v[212:215], v[60:63]
	v_mfma_f32_16x16x32_bf16 v[56:59], v[164:167], v[212:215], v[56:59]
	v_mfma_f32_16x16x32_bf16 v[44:47], v[138:141], v[220:223], v[44:47]
	v_mfma_f32_16x16x32_bf16 v[40:43], v[164:167], v[220:223], v[40:43]
	v_mfma_f32_16x16x32_bf16 v[28:31], v[138:141], v[228:231], v[28:31]
	v_mfma_f32_16x16x32_bf16 v[24:27], v[164:167], v[228:231], v[24:27]
	v_mfma_f32_16x16x32_bf16 v[12:15], v[138:141], v[236:239], v[12:15]
	v_mfma_f32_16x16x32_bf16 v[8:11], v[164:167], v[236:239], v[8:11]
	v_mfma_f32_16x16x32_bf16 v[60:63], v[160:163], v[216:219], v[60:63]
	v_mfma_f32_16x16x32_bf16 v[56:59], v[192:195], v[216:219], v[56:59]
	v_mfma_f32_16x16x32_bf16 v[44:47], v[160:163], v[224:227], v[44:47]
	v_mfma_f32_16x16x32_bf16 v[40:43], v[192:195], v[224:227], v[40:43]
	v_mfma_f32_16x16x32_bf16 v[28:31], v[160:163], v[232:235], v[28:31]
	v_mfma_f32_16x16x32_bf16 v[24:27], v[192:195], v[232:235], v[24:27]
	v_mfma_f32_16x16x32_bf16 v[12:15], v[160:163], v[240:243], v[12:15]
	v_mfma_f32_16x16x32_bf16 v[8:11], v[192:195], v[240:243], v[8:11]
	s_setprio 0
	s_setprio 1
	v_mfma_f32_16x16x32_bf16 v[52:55], v[196:199], v[212:215], v[52:55]
	s_add_u32 s33, s33, 0x100
	s_addc_u32 s50, s50, 0
	v_mfma_f32_16x16x32_bf16 v[48:51], v[204:207], v[212:215], v[48:51]
	s_add_u32 s2, s2, 0x100
	s_addc_u32 s3, s3, 0
	v_mfma_f32_16x16x32_bf16 v[36:39], v[196:199], v[220:223], v[36:39]
	s_cmp_ge_i32 s51, s45
	s_mov_b32 s46, s51
	s_cbranch_scc1 .Lmy_kx6
	v_mfma_f32_16x16x32_bf16 v[32:35], v[204:207], v[220:223], v[32:35]
	s_add_i32 s51, s46, 2
	v_mfma_f32_16x16x32_bf16 v[20:23], v[196:199], v[228:231], v[20:23]
	s_add_u32 s52, s2, 0x80
	v_mfma_f32_16x16x32_bf16 v[16:19], v[204:207], v[228:231], v[16:19]
	s_addc_u32 s47, s3, 0
	v_mfma_f32_16x16x32_bf16 v[4:7], v[196:199], v[236:239], v[4:7]
	s_add_i32 vcc_lo, 0, 0x10000
	v_mfma_f32_16x16x32_bf16 v[0:3], v[204:207], v[236:239], v[0:3]
	s_cmp_eq_u32 s56, s46
	v_mfma_f32_16x16x32_bf16 v[52:55], v[200:203], v[216:219], v[52:55]
	s_cselect_b32 s47, s29, s47
	v_mfma_f32_16x16x32_bf16 v[48:51], v[208:211], v[216:219], v[48:51]
	s_cselect_b32 s46, s28, s52
	v_mfma_f32_16x16x32_bf16 v[36:39], v[200:203], v[224:227], v[36:39]
	v_add_u32_e32 v142, vcc_lo, v157
	v_mfma_f32_16x16x32_bf16 v[32:35], v[208:211], v[224:227], v[32:35]
	s_cselect_b32 s53, s31, s50
	v_mfma_f32_16x16x32_bf16 v[20:23], v[200:203], v[232:235], v[20:23]
	s_cselect_b32 s52, s30, s33
	v_mfma_f32_16x16x32_bf16 v[16:19], v[208:211], v[232:235], v[16:19]
	s_add_i32 vcc_hi, 0, 0x14000
	v_mfma_f32_16x16x32_bf16 v[4:7], v[200:203], v[240:243], v[4:7]
	v_mfma_f32_16x16x32_bf16 v[0:3], v[208:211], v[240:243], v[0:3]
	s_setprio 0
	s_barrier
	s_branch .Lmy_kh6
.Lmy_kx6:
	v_mfma_f32_16x16x32_bf16 v[32:35], v[204:207], v[220:223], v[32:35]
	v_mfma_f32_16x16x32_bf16 v[20:23], v[196:199], v[228:231], v[20:23]
	v_mfma_f32_16x16x32_bf16 v[16:19], v[204:207], v[228:231], v[16:19]
	v_mfma_f32_16x16x32_bf16 v[4:7], v[196:199], v[236:239], v[4:7]
	v_mfma_f32_16x16x32_bf16 v[0:3], v[204:207], v[236:239], v[0:3]
	v_mfma_f32_16x16x32_bf16 v[52:55], v[200:203], v[216:219], v[52:55]
	v_mfma_f32_16x16x32_bf16 v[48:51], v[208:211], v[216:219], v[48:51]
	v_mfma_f32_16x16x32_bf16 v[36:39], v[200:203], v[224:227], v[36:39]
	v_mfma_f32_16x16x32_bf16 v[32:35], v[208:211], v[224:227], v[32:35]
	v_mfma_f32_16x16x32_bf16 v[20:23], v[200:203], v[232:235], v[20:23]
	v_mfma_f32_16x16x32_bf16 v[16:19], v[208:211], v[232:235], v[16:19]
	v_mfma_f32_16x16x32_bf16 v[4:7], v[200:203], v[240:243], v[4:7]
	v_mfma_f32_16x16x32_bf16 v[0:3], v[208:211], v[240:243], v[0:3]
	s_setprio 0
	s_barrier
	s_movk_i32 s51, 0x200
	s_movk_i32 s33, 0x300

; #define PG8_STAGE(bufoff, gbase, voff) do { _Pragma("unroll") for (int _i = 0; _i < 2; ++_i) \
;         __builtin_amdgcn_global_load_lds((const unsigned*)((const char*)(gbase) + (voff)[_i]), (PG8_LAS unsigned*)(lds + (bufoff) + ldsw + _i * 8192), 16, 0, 0); } while (0)
; #define PG8_LDA(dst, b, h) do { _Pragma("unroll") for (int m = 0; m < 4; ++m) _Pragma("unroll") for (int k = 0; k < 2; ++k) dst[m][k] = *(const PG8_LAS bf16x8*)(lds + PG8_SA(b, h) + aoff + m * 2048 + k * 1024); } while (0)
; #define PG8_LDB(dst, b, h) do { _Pragma("unroll") for (int n = 0; n < 2; ++n) _Pragma("unroll") for (int k = 0; k < 2; ++k) dst[n][k] = *(const PG8_LAS bf16x8*)(lds + PG8_SB(b, h) + boff + n * 2048 + k * 1024); } while (0)
; #define PG8_MMA(ai, bj, At, Bt) do { __builtin_amdgcn_s_setprio(1); _Pragma("unroll") for (int m = 0; m < 4; ++m) _Pragma("unroll") for (int n = 0; n < 2; ++n) _Pragma("unroll") for (int k = 0; k < 2; ++k) \
;         acc[ai][bj][m][n] = __builtin_amdgcn_mfma_f32_16x16x32_bf16(Bt[n][k], At[m][k], acc[ai][bj][m][n], 0, 0, 0); __builtin_amdgcn_s_setprio(0); } while (0)
; #define PG8_WAIT_V(n) asm volatile("s_waitcnt vmcnt(" #n ")" ::: "memory")
; #define PG8_WAIT_L(n) asm volatile("s_waitcnt lgkmcnt(" #n ")" ::: "memory")
; #define PG8_BAR __builtin_amdgcn_s_barrier()
; #define PG8_SCHED __builtin_amdgcn_sched_barrier(0)
; template <class Epi, class Sched>
; __device__ __forceinline__ void gemm_phase(int wid_s, PG8_LAS unsigned char* lds, const Gemm g, const Sched& S, const Epi& E) {
;     ...
;             PG8_LDB(B0, 0, 0); PG8_LDB(B1, 0, 1); PG8_SCHED; PG8_LDA(At, 0, 0); PG8_STAGE(PG8_SA(1, 1), a1 + hstepA, voffA);
;             PG8_WAIT_V(8); PG8_WAIT_L(0); PG8_BAR; PG8_MMA(0, 0, At, B0); PG8_MMA(0, 1, At, B1); PG8_BAR; PG8_SCHED;
;             PG8_LDA(At, 0, 1); PG8_STAGE(PG8_SB(0, 0), b2, voffB); PG8_STAGE(PG8_SB(0, 1), b2 + hstepB, voffB); PG8_STAGE(PG8_SA(0, 0), a2, voffA);
;             PG8_WAIT_V(8); PG8_WAIT_L(0); PG8_BAR; PG8_MMA(1, 0, At, B0); PG8_MMA(1, 1, At, B1); PG8_BAR; PG8_SCHED;
.Lmy_kh7:
	ds_read_b128 v[138:141], v142
	ds_read_b128 v[160:163], v142 offset:1024
	ds_read_b128 v[164:167], v142 offset:2048
	ds_read_b128 v[192:195], v142 offset:3072
	v_add_u32_e32 v142, s45, v157
	ds_read_b128 v[196:199], v142
	ds_read_b128 v[200:203], v142 offset:1024
	ds_read_b128 v[204:207], v142 offset:2048
	ds_read_b128 v[208:211], v142 offset:3072
	v_lshl_add_u64 v[142:143], s[4:5], 0, v[136:137]
	s_add_i32 m0, s52, 0xc000
	ds_read_b128 v[212:215], v159
	ds_read_b128 v[216:219], v159 offset:1024
	ds_read_b128 v[220:223], v159 offset:2048
	ds_read_b128 v[224:227], v159 offset:3072
	ds_read_b128 v[228:231], v159 offset:4096
	ds_read_b128 v[232:235], v159 offset:5120
	ds_read_b128 v[236:239], v159 offset:6144
	ds_read_b128 v[240:243], v159 offset:7168
	global_load_lds_dwordx4 v[142:143], off
	v_lshl_add_u64 v[142:143], s[4:5], 0, v[134:135]
	s_add_i32 m0, s52, 0xe000
	s_nop 0
	global_load_lds_dwordx4 v[142:143], off
	s_waitcnt vmcnt(8)
	s_waitcnt lgkmcnt(0)
	s_barrier
	s_setprio 1
	s_waitcnt lgkmcnt(0)
	v_mfma_f32_16x16x32_bf16 v[124:127], v[138:141], v[212:215], v[124:127]
	v_mfma_f32_16x16x32_bf16 v[120:123], v[164:167], v[212:215], v[120:123]
	v_mfma_f32_16x16x32_bf16 v[108:111], v[138:141], v[220:223], v[108:111]
	v_mfma_f32_16x16x32_bf16 v[104:107], v[164:167], v[220:223], v[104:107]
	v_mfma_f32_16x16x32_bf16 v[92:95], v[138:141], v[228:231], v[92:95]
	v_mfma_f32_16x16x32_bf16 v[88:91], v[164:167], v[228:231], v[88:91]
	v_mfma_f32_16x16x32_bf16 v[76:79], v[138:141], v[236:239], v[76:79]
	v_mfma_f32_16x16x32_bf16 v[72:75], v[164:167], v[236:239], v[72:75]
	v_mfma_f32_16x16x32_bf16 v[124:127], v[160:163], v[216:219], v[124:127]
	v_mfma_f32_16x16x32_bf16 v[120:123], v[192:195], v[216:219], v[120:123]
	v_mfma_f32_16x16x32_bf16 v[108:111], v[160:163], v[224:227], v[108:111]
	v_mfma_f32_16x16x32_bf16 v[104:107], v[192:195], v[224:227], v[104:107]
	v_mfma_f32_16x16x32_bf16 v[92:95], v[160:163], v[232:235], v[92:95]
	v_mfma_f32_16x16x32_bf16 v[88:91], v[192:195], v[232:235], v[88:91]
	v_mfma_f32_16x16x32_bf16 v[76:79], v[160:163], v[240:243], v[76:79]
	v_mfma_f32_16x16x32_bf16 v[72:75], v[192:195], v[240:243], v[72:75]
	s_setprio 0
	s_setprio 1
	v_mfma_f32_16x16x32_bf16 v[116:119], v[196:199], v[212:215], v[116:119]
	v_mfma_f32_16x16x32_bf16 v[112:115], v[204:207], v[212:215], v[112:115]
	v_mfma_f32_16x16x32_bf16 v[100:103], v[196:199], v[220:223], v[100:103]
	v_mfma_f32_16x16x32_bf16 v[96:99], v[204:207], v[220:223], v[96:99]
	v_mfma_f32_16x16x32_bf16 v[84:87], v[196:199], v[228:231], v[84:87]
	v_mfma_f32_16x16x32_bf16 v[80:83], v[204:207], v[228:231], v[80:83]
	v_mfma_f32_16x16x32_bf16 v[68:71], v[196:199], v[236:239], v[68:71]
	v_mfma_f32_16x16x32_bf16 v[64:67], v[204:207], v[236:239], v[64:67]
	v_mfma_f32_16x16x32_bf16 v[116:119], v[200:203], v[216:219], v[116:119]
	v_mfma_f32_16x16x32_bf16 v[112:115], v[208:211], v[216:219], v[112:115]
	v_mfma_f32_16x16x32_bf16 v[100:103], v[200:203], v[224:227], v[100:103]
	v_mfma_f32_16x16x32_bf16 v[96:99], v[208:211], v[224:227], v[96:99]
	v_mfma_f32_16x16x32_bf16 v[84:87], v[200:203], v[232:235], v[84:87]
	v_mfma_f32_16x16x32_bf16 v[80:83], v[208:211], v[232:235], v[80:83]
	v_mfma_f32_16x16x32_bf16 v[68:71], v[200:203], v[240:243], v[68:71]
	v_mfma_f32_16x16x32_bf16 v[64:67], v[208:211], v[240:243], v[64:67]
	s_setprio 0
	s_barrier
	s_add_i32 s18, s18, s47
	v_lshl_add_u64 v[142:143], vcc, 0, v[144:145]
	s_mov_b32 m0, s18
	ds_read_b128 v[212:215], v159 offset:16384
	ds_read_b128 v[216:219], v159 offset:17408
	ds_read_b128 v[220:223], v159 offset:18432
	ds_read_b128 v[224:227], v159 offset:19456
	ds_read_b128 v[228:231], v159 offset:20480
	ds_read_b128 v[232:235], v159 offset:21504
	ds_read_b128 v[236:239], v159 offset:22528
	ds_read_b128 v[240:243], v159 offset:23552
	global_load_lds_dwordx4 v[142:143], off
	s_add_i32 m0, s18, 0x2000
	v_lshl_add_u64 v[244:245], vcc, 0, v[132:133]
	s_add_u32 vcc_lo, vcc_lo, s12
	s_addc_u32 vcc_hi, vcc_hi, s13
	s_add_i32 s18, s45, s47
	global_load_lds_dwordx4 v[244:245], off
	v_lshl_add_u64 v[246:247], vcc, 0, v[144:145]
	s_mov_b32 m0, s18
	v_lshl_add_u64 v[248:249], vcc, 0, v[132:133]
	global_load_lds_dwordx4 v[246:247], off
	s_add_i32 m0, s18, 0x2000
	v_lshl_add_u64 v[250:251], s[34:35], 0, v[128:129]
	global_load_lds_dwordx4 v[248:249], off
	s_mov_b32 m0, s52
	v_lshl_add_u64 v[252:253], s[34:35], 0, v[130:131]
	global_load_lds_dwordx4 v[250:251], off
	s_mov_b32 m0, s53
	s_nop 0
	global_load_lds_dwordx4 v[252:253], off
	s_waitcnt vmcnt(8)
	s_waitcnt lgkmcnt(0)
	s_barrier
; #define PG8_STAGE(bufoff, gbase, voff) do { _Pragma("unroll") for (int _i = 0; _i < 2; ++_i) \
;         __builtin_amdgcn_global_load_lds((const unsigned*)((const char*)(gbase) + (voff)[_i]), (PG8_LAS unsigned*)(lds + (bufoff) + ldsw + _i * 8192), 16, 0, 0); } while (0)
; #define PG8_LDA(dst, b, h) do { _Pragma("unroll") for (int m = 0; m < 4; ++m) _Pragma("unroll") for (int k = 0; k < 2; ++k) dst[m][k] = *(const PG8_LAS bf16x8*)(lds + PG8_SA(b, h) + aoff + m * 2048 + k * 1024); } while (0)
; #define PG8_LDB(dst, b, h) do { _Pragma("unroll") for (int n = 0; n < 2; ++n) _Pragma("unroll") for (int k = 0; k < 2; ++k) dst[n][k] = *(const PG8_LAS bf16x8*)(lds + PG8_SB(b, h) + boff + n * 2048 + k * 1024); } while (0)
; #define PG8_MMA(ai, bj, At, Bt) do { __builtin_amdgcn_s_setprio(1); _Pragma("unroll") for (int m = 0; m < 4; ++m) _Pragma("unroll") for (int n = 0; n < 2; ++n) _Pragma("unroll") for (int k = 0; k < 2; ++k) \
;         acc[ai][bj][m][n] = __builtin_amdgcn_mfma_f32_16x16x32_bf16(Bt[n][k], At[m][k], acc[ai][bj][m][n], 0, 0, 0); __builtin_amdgcn_s_setprio(0); } while (0)
; #define PG8_WAIT_V(n) asm volatile("s_waitcnt vmcnt(" #n ")" ::: "memory")
; #define PG8_WAIT_L(n) asm volatile("s_waitcnt lgkmcnt(" #n ")" ::: "memory")
; #define PG8_BAR __builtin_amdgcn_s_barrier()
; #define PG8_SCHED __builtin_amdgcn_sched_barrier(0)
; template <class Epi, class Sched>
; __device__ __forceinline__ void gemm_phase(int wid_s, PG8_LAS unsigned char* lds, const Gemm g, const Sched& S, const Epi& E) {
;     ...
;             PG8_WAIT_V(8); PG8_WAIT_L(0); PG8_BAR; PG8_MMA(1, 0, At, B0); PG8_MMA(1, 1, At, B1); PG8_BAR; PG8_SCHED;
;             PG8_LDB(B0, 1, 0); PG8_LDB(B1, 1, 1); PG8_SCHED; PG8_LDA(At, 1, 0); PG8_STAGE(PG8_SA(0, 1), a2 + hstepA, voffA);
;             PG8_WAIT_V(8); PG8_WAIT_L(0); PG8_BAR; PG8_MMA(0, 0, At, B0); PG8_MMA(0, 1, At, B1); PG8_BAR; PG8_SCHED;
	s_setprio 1
	s_waitcnt lgkmcnt(0)
	v_mfma_f32_16x16x32_bf16 v[60:63], v[138:141], v[212:215], v[60:63]
	v_mfma_f32_16x16x32_bf16 v[56:59], v[164:167], v[212:215], v[56:59]
	v_mfma_f32_16x16x32_bf16 v[44:47], v[138:141], v[220:223], v[44:47]
	v_mfma_f32_16x16x32_bf16 v[40:43], v[164:167], v[220:223], v[40:43]
	v_mfma_f32_16x16x32_bf16 v[28:31], v[138:141], v[228:231], v[28:31]
	v_mfma_f32_16x16x32_bf16 v[24:27], v[164:167], v[228:231], v[24:27]
	v_mfma_f32_16x16x32_bf16 v[12:15], v[138:141], v[236:239], v[12:15]
	v_mfma_f32_16x16x32_bf16 v[8:11], v[164:167], v[236:239], v[8:11]
	v_mfma_f32_16x16x32_bf16 v[60:63], v[160:163], v[216:219], v[60:63]
	v_mfma_f32_16x16x32_bf16 v[56:59], v[192:195], v[216:219], v[56:59]
	v_mfma_f32_16x16x32_bf16 v[44:47], v[160:163], v[224:227], v[44:47]
	v_mfma_f32_16x16x32_bf16 v[40:43], v[192:195], v[224:227], v[40:43]
	v_mfma_f32_16x16x32_bf16 v[28:31], v[160:163], v[232:235], v[28:31]
	v_mfma_f32_16x16x32_bf16 v[24:27], v[192:195], v[232:235], v[24:27]
	v_mfma_f32_16x16x32_bf16 v[12:15], v[160:163], v[240:243], v[12:15]
	v_mfma_f32_16x16x32_bf16 v[8:11], v[192:195], v[240:243], v[8:11]
	s_setprio 0
	s_setprio 1
	v_mfma_f32_16x16x32_bf16 v[52:55], v[196:199], v[212:215], v[52:55]
	v_mfma_f32_16x16x32_bf16 v[48:51], v[204:207], v[212:215], v[48:51]
	v_mfma_f32_16x16x32_bf16 v[36:39], v[196:199], v[220:223], v[36:39]
	v_mfma_f32_16x16x32_bf16 v[32:35], v[204:207], v[220:223], v[32:35]
	v_mfma_f32_16x16x32_bf16 v[20:23], v[196:199], v[228:231], v[20:23]
	v_mfma_f32_16x16x32_bf16 v[16:19], v[204:207], v[228:231], v[16:19]
	v_mfma_f32_16x16x32_bf16 v[4:7], v[196:199], v[236:239], v[4:7]
	v_mfma_f32_16x16x32_bf16 v[0:3], v[204:207], v[236:239], v[0:3]
	v_mfma_f32_16x16x32_bf16 v[52:55], v[200:203], v[216:219], v[52:55]
	v_mfma_f32_16x16x32_bf16 v[48:51], v[208:211], v[216:219], v[48:51]
	v_mfma_f32_16x16x32_bf16 v[36:39], v[200:203], v[224:227], v[36:39]
	v_mfma_f32_16x16x32_bf16 v[32:35], v[208:211], v[224:227], v[32:35]
	v_mfma_f32_16x16x32_bf16 v[20:23], v[200:203], v[232:235], v[20:23]
	v_mfma_f32_16x16x32_bf16 v[16:19], v[208:211], v[232:235], v[16:19]
	v_mfma_f32_16x16x32_bf16 v[4:7], v[200:203], v[240:243], v[4:7]
	v_mfma_f32_16x16x32_bf16 v[0:3], v[208:211], v[240:243], v[0:3]
	s_setprio 0
	s_barrier
	s_add_i32 s18, 0, 0x18000
	v_add_u32_e32 v188, s18, v157
	s_add_i32 s45, 0, 0x1c000
	ds_read_b128 v[138:141], v188
	ds_read_b128 v[160:163], v188 offset:1024
	ds_read_b128 v[164:167], v188 offset:2048
	ds_read_b128 v[192:195], v188 offset:3072
	v_add_u32_e32 v188, s45, v157
	ds_read_b128 v[196:199], v188
	ds_read_b128 v[200:203], v188 offset:1024
	ds_read_b128 v[204:207], v188 offset:2048
	ds_read_b128 v[208:211], v188 offset:3072
	s_add_u32 s34, s34, s10
	s_addc_u32 s35, s35, s11
	s_mov_b32 m0, s54
	v_lshl_add_u64 v[188:189], s[34:35], 0, v[128:129]
	ds_read_b128 v[212:215], v159 offset:32768
	ds_read_b128 v[216:219], v159 offset:33792
	ds_read_b128 v[220:223], v159 offset:34816
	ds_read_b128 v[224:227], v159 offset:35840
	ds_read_b128 v[228:231], v159 offset:36864
	ds_read_b128 v[232:235], v159 offset:37888
	ds_read_b128 v[236:239], v159 offset:38912
	ds_read_b128 v[240:243], v159 offset:39936
	global_load_lds_dwordx4 v[188:189], off
	v_lshl_add_u64 v[188:189], s[34:35], 0, v[130:131]
	s_mov_b32 m0, s55
	s_nop 0
	global_load_lds_dwordx4 v[188:189], off
	s_waitcnt vmcnt(8)
	s_waitcnt lgkmcnt(0)
	s_barrier
	s_setprio 1
	s_waitcnt lgkmcnt(0)
	v_mfma_f32_16x16x32_bf16 v[124:127], v[138:141], v[212:215], v[124:127]
	v_mfma_f32_16x16x32_bf16 v[120:123], v[164:167], v[212:215], v[120:123]
	v_mfma_f32_16x16x32_bf16 v[108:111], v[138:141], v[220:223], v[108:111]
	v_mfma_f32_16x16x32_bf16 v[104:107], v[164:167], v[220:223], v[104:107]
	v_mfma_f32_16x16x32_bf16 v[92:95], v[138:141], v[228:231], v[92:95]
	v_mfma_f32_16x16x32_bf16 v[88:91], v[164:167], v[228:231], v[88:91]
	v_mfma_f32_16x16x32_bf16 v[76:79], v[138:141], v[236:239], v[76:79]
	v_mfma_f32_16x16x32_bf16 v[72:75], v[164:167], v[236:239], v[72:75]
	v_mfma_f32_16x16x32_bf16 v[124:127], v[160:163], v[216:219], v[124:127]
	v_mfma_f32_16x16x32_bf16 v[120:123], v[192:195], v[216:219], v[120:123]
	v_mfma_f32_16x16x32_bf16 v[108:111], v[160:163], v[224:227], v[108:111]
	v_mfma_f32_16x16x32_bf16 v[104:107], v[192:195], v[224:227], v[104:107]
	v_mfma_f32_16x16x32_bf16 v[92:95], v[160:163], v[232:235], v[92:95]
	v_mfma_f32_16x16x32_bf16 v[88:91], v[192:195], v[232:235], v[88:91]
	v_mfma_f32_16x16x32_bf16 v[76:79], v[160:163], v[240:243], v[76:79]
	v_mfma_f32_16x16x32_bf16 v[72:75], v[192:195], v[240:243], v[72:75]
	s_setprio 0
	s_setprio 1
	v_mfma_f32_16x16x32_bf16 v[116:119], v[196:199], v[212:215], v[116:119]
	v_mfma_f32_16x16x32_bf16 v[112:115], v[204:207], v[212:215], v[112:115]
	v_mfma_f32_16x16x32_bf16 v[100:103], v[196:199], v[220:223], v[100:103]
	v_mfma_f32_16x16x32_bf16 v[96:99], v[204:207], v[220:223], v[96:99]
	v_mfma_f32_16x16x32_bf16 v[84:87], v[196:199], v[228:231], v[84:87]
	v_mfma_f32_16x16x32_bf16 v[80:83], v[204:207], v[228:231], v[80:83]
	v_mfma_f32_16x16x32_bf16 v[68:71], v[196:199], v[236:239], v[68:71]
	v_mfma_f32_16x16x32_bf16 v[64:67], v[204:207], v[236:239], v[64:67]
	v_mfma_f32_16x16x32_bf16 v[116:119], v[200:203], v[216:219], v[116:119]
	v_mfma_f32_16x16x32_bf16 v[112:115], v[208:211], v[216:219], v[112:115]
	v_mfma_f32_16x16x32_bf16 v[100:103], v[200:203], v[224:227], v[100:103]
	v_mfma_f32_16x16x32_bf16 v[96:99], v[208:211], v[224:227], v[96:99]
	v_mfma_f32_16x16x32_bf16 v[84:87], v[200:203], v[232:235], v[84:87]
	v_mfma_f32_16x16x32_bf16 v[80:83], v[208:211], v[232:235], v[80:83]
	v_mfma_f32_16x16x32_bf16 v[68:71], v[200:203], v[240:243], v[68:71]
	v_mfma_f32_16x16x32_bf16 v[64:67], v[208:211], v[240:243], v[64:67]
	s_setprio 0
	s_barrier
; #define PG8_STAGE(bufoff, gbase, voff) do { _Pragma("unroll") for (int _i = 0; _i < 2; ++_i) \
;         __builtin_amdgcn_global_load_lds((const unsigned*)((const char*)(gbase) + (voff)[_i]), (PG8_LAS unsigned*)(lds + (bufoff) + ldsw + _i * 8192), 16, 0, 0); } while (0)
; #define PG8_LDA(dst, b, h) do { _Pragma("unroll") for (int m = 0; m < 4; ++m) _Pragma("unroll") for (int k = 0; k < 2; ++k) dst[m][k] = *(const PG8_LAS bf16x8*)(lds + PG8_SA(b, h) + aoff + m * 2048 + k * 1024); } while (0)
; #define PG8_MMA(ai, bj, At, Bt) do { __builtin_amdgcn_s_setprio(1); _Pragma("unroll") for (int m = 0; m < 4; ++m) _Pragma("unroll") for (int n = 0; n < 2; ++n) _Pragma("unroll") for (int k = 0; k < 2; ++k) \
;         acc[ai][bj][m][n] = __builtin_amdgcn_mfma_f32_16x16x32_bf16(Bt[n][k], At[m][k], acc[ai][bj][m][n], 0, 0, 0); __builtin_amdgcn_s_setprio(0); } while (0)
; #define PG8_WAIT_V(n) asm volatile("s_waitcnt vmcnt(" #n ")" ::: "memory")
; #define PG8_WAIT_L(n) asm volatile("s_waitcnt lgkmcnt(" #n ")" ::: "memory")
; #define PG8_BAR __builtin_amdgcn_s_barrier()
; #define PG8_SCHED __builtin_amdgcn_sched_barrier(0)
; template <class Epi, class Sched>
; __device__ __forceinline__ void gemm_phase(int wid_s, PG8_LAS unsigned char* lds, const Gemm g, const Sched& S, const Epi& E) {
;     ...
;         for (int t = 0; t < nt; t += 2) {
;             const bool last = (t == nt - 2);
;             const char* a1 = cA + (size_t)(t + 1) * kstep;
;             const char* a2 = last ? nA : cA + (size_t)(t + 2) * kstep; const char* b2 = last ? nB : cB + (size_t)(t + 2) * kstep;
;             const char* a3 = a2 + kstep; const char* b3 = b2 + kstep;
;     ...
;             PG8_LDA(At, 1, 1); PG8_STAGE(PG8_SB(1, 0), b3, voffB); PG8_STAGE(PG8_SB(1, 1), b3 + hstepB, voffB); PG8_STAGE(PG8_SA(1, 0), a3, voffA);
;             PG8_WAIT_V(8); PG8_WAIT_L(0); PG8_BAR; PG8_MMA(1, 0, At, B0); PG8_MMA(1, 1, At, B1); PG8_BAR; PG8_SCHED;
	s_add_i32 s18, s18, s47
	v_lshl_add_u64 v[142:143], v[142:143], 0, s[96:97]
	s_mov_b32 m0, s18
	ds_read_b128 v[212:215], v159 offset:49152
	ds_read_b128 v[216:219], v159 offset:50176
	ds_read_b128 v[220:223], v159 offset:51200
	ds_read_b128 v[224:227], v159 offset:52224
	ds_read_b128 v[228:231], v159 offset:53248
	ds_read_b128 v[232:235], v159 offset:54272
	ds_read_b128 v[236:239], v159 offset:55296
	ds_read_b128 v[240:243], v159 offset:56320
	global_load_lds_dwordx4 v[142:143], off
	v_lshl_add_u64 v[142:143], v[244:245], 0, s[96:97]
	s_add_i32 m0, s18, 0x2000
	s_add_i32 s18, s45, s47
	global_load_lds_dwordx4 v[142:143], off
	v_lshl_add_u64 v[142:143], v[246:247], 0, s[96:97]
	s_mov_b32 m0, s18
	s_nop 0
	global_load_lds_dwordx4 v[142:143], off
	v_lshl_add_u64 v[142:143], v[248:249], 0, s[96:97]
	s_add_i32 m0, s18, 0x2000
	s_nop 0
	global_load_lds_dwordx4 v[142:143], off
	v_lshl_add_u64 v[142:143], v[250:251], 0, s[96:97]
	s_mov_b32 m0, s56
	s_nop 0
	global_load_lds_dwordx4 v[142:143], off
	v_lshl_add_u64 v[142:143], v[252:253], 0, s[96:97]
	s_mov_b32 m0, s57
	s_nop 0
	global_load_lds_dwordx4 v[142:143], off
	s_waitcnt vmcnt(8)
	s_waitcnt lgkmcnt(0)
	s_barrier
	s_setprio 1
	s_waitcnt lgkmcnt(0)
	v_mfma_f32_16x16x32_bf16 v[60:63], v[138:141], v[212:215], v[60:63]
	v_mfma_f32_16x16x32_bf16 v[56:59], v[164:167], v[212:215], v[56:59]
	v_mfma_f32_16x16x32_bf16 v[44:47], v[138:141], v[220:223], v[44:47]
	v_mfma_f32_16x16x32_bf16 v[40:43], v[164:167], v[220:223], v[40:43]
	v_mfma_f32_16x16x32_bf16 v[28:31], v[138:141], v[228:231], v[28:31]
	v_mfma_f32_16x16x32_bf16 v[24:27], v[164:167], v[228:231], v[24:27]
	v_mfma_f32_16x16x32_bf16 v[12:15], v[138:141], v[236:239], v[12:15]
	v_mfma_f32_16x16x32_bf16 v[8:11], v[164:167], v[236:239], v[8:11]
	v_mfma_f32_16x16x32_bf16 v[60:63], v[160:163], v[216:219], v[60:63]
	v_mfma_f32_16x16x32_bf16 v[56:59], v[192:195], v[216:219], v[56:59]
	v_mfma_f32_16x16x32_bf16 v[44:47], v[160:163], v[224:227], v[44:47]
	v_mfma_f32_16x16x32_bf16 v[40:43], v[192:195], v[224:227], v[40:43]
	v_mfma_f32_16x16x32_bf16 v[28:31], v[160:163], v[232:235], v[28:31]
	v_mfma_f32_16x16x32_bf16 v[24:27], v[192:195], v[232:235], v[24:27]
	v_mfma_f32_16x16x32_bf16 v[12:15], v[160:163], v[240:243], v[12:15]
	v_mfma_f32_16x16x32_bf16 v[8:11], v[192:195], v[240:243], v[8:11]
	s_setprio 0
	s_setprio 1
	v_mfma_f32_16x16x32_bf16 v[52:55], v[196:199], v[212:215], v[52:55]
	s_add_u32 s33, s33, 0x100
	s_addc_u32 s51, s51, 0
	v_mfma_f32_16x16x32_bf16 v[48:51], v[204:207], v[212:215], v[48:51]
	s_add_u32 s4, s4, 0x100
	s_addc_u32 s5, s5, 0
	v_mfma_f32_16x16x32_bf16 v[36:39], v[196:199], v[220:223], v[36:39]
	s_cmp_ge_i32 s44, s94
	s_mov_b32 s34, s44
	s_cbranch_scc1 .Lmy_kx7
	v_mfma_f32_16x16x32_bf16 v[32:35], v[204:207], v[220:223], v[32:35]
	s_add_i32 s44, s34, 2
	v_mfma_f32_16x16x32_bf16 v[20:23], v[196:199], v[228:231], v[20:23]
	s_add_u32 s45, s4, 0x80
	v_mfma_f32_16x16x32_bf16 v[16:19], v[204:207], v[228:231], v[16:19]
	s_addc_u32 s35, s5, 0
	v_mfma_f32_16x16x32_bf16 v[4:7], v[196:199], v[236:239], v[4:7]
	s_add_i32 s18, 0, 0x10000
	v_mfma_f32_16x16x32_bf16 v[0:3], v[204:207], v[236:239], v[0:3]
	s_cmp_eq_u32 s95, s34
	v_mfma_f32_16x16x32_bf16 v[52:55], v[200:203], v[216:219], v[52:55]
	s_cselect_b32 s35, s29, s35
	v_mfma_f32_16x16x32_bf16 v[48:51], v[208:211], v[216:219], v[48:51]
	s_cselect_b32 s34, s28, s45
	v_mfma_f32_16x16x32_bf16 v[36:39], v[200:203], v[224:227], v[36:39]
	v_add_u32_e32 v142, s18, v157
	v_mfma_f32_16x16x32_bf16 v[32:35], v[208:211], v[224:227], v[32:35]
	s_cselect_b32 vcc_hi, s31, s51
	v_mfma_f32_16x16x32_bf16 v[20:23], v[200:203], v[232:235], v[20:23]
	s_cselect_b32 vcc_lo, s30, s33
	v_mfma_f32_16x16x32_bf16 v[16:19], v[208:211], v[232:235], v[16:19]
	s_add_i32 s45, 0, 0x14000
	v_mfma_f32_16x16x32_bf16 v[4:7], v[200:203], v[240:243], v[4:7]
	v_mfma_f32_16x16x32_bf16 v[0:3], v[208:211], v[240:243], v[0:3]
	s_setprio 0
	s_barrier
	s_branch .Lmy_kh7
.Lmy_kx7:
	v_mfma_f32_16x16x32_bf16 v[32:35], v[204:207], v[220:223], v[32:35]
	v_mfma_f32_16x16x32_bf16 v[20:23], v[196:199], v[228:231], v[20:23]
	v_mfma_f32_16x16x32_bf16 v[16:19], v[204:207], v[228:231], v[16:19]
	v_mfma_f32_16x16x32_bf16 v[4:7], v[196:199], v[236:239], v[4:7]
	v_mfma_f32_16x16x32_bf16 v[0:3], v[204:207], v[236:239], v[0:3]
	v_mfma_f32_16x16x32_bf16 v[52:55], v[200:203], v[216:219], v[52:55]
	v_mfma_f32_16x16x32_bf16 v[48:51], v[208:211], v[216:219], v[48:51]
	v_mfma_f32_16x16x32_bf16 v[36:39], v[200:203], v[224:227], v[36:39]
	v_mfma_f32_16x16x32_bf16 v[32:35], v[208:211], v[224:227], v[32:35]
	v_mfma_f32_16x16x32_bf16 v[20:23], v[200:203], v[232:235], v[20:23]
	v_mfma_f32_16x16x32_bf16 v[16:19], v[208:211], v[232:235], v[16:19]
	v_mfma_f32_16x16x32_bf16 v[4:7], v[200:203], v[240:243], v[4:7]
	v_mfma_f32_16x16x32_bf16 v[0:3], v[208:211], v[240:243], v[0:3]
	s_setprio 0
	s_barrier
	s_movk_i32 s33, 0x300

; #define PG8_STAGE(bufoff, gbase, voff) do { _Pragma("unroll") for (int _i = 0; _i < 2; ++_i) \
;         __builtin_amdgcn_global_load_lds((const unsigned*)((const char*)(gbase) + (voff)[_i]), (PG8_LAS unsigned*)(lds + (bufoff) + ldsw + _i * 8192), 16, 0, 0); } while (0)
; #define PG8_LDA(dst, b, h) do { _Pragma("unroll") for (int m = 0; m < 4; ++m) _Pragma("unroll") for (int k = 0; k < 2; ++k) dst[m][k] = *(const PG8_LAS bf16x8*)(lds + PG8_SA(b, h) + aoff + m * 2048 + k * 1024); } while (0)
; #define PG8_LDB(dst, b, h) do { _Pragma("unroll") for (int n = 0; n < 2; ++n) _Pragma("unroll") for (int k = 0; k < 2; ++k) dst[n][k] = *(const PG8_LAS bf16x8*)(lds + PG8_SB(b, h) + boff + n * 2048 + k * 1024); } while (0)
; #define PG8_MMA(ai, bj, At, Bt) do { __builtin_amdgcn_s_setprio(1); _Pragma("unroll") for (int m = 0; m < 4; ++m) _Pragma("unroll") for (int n = 0; n < 2; ++n) _Pragma("unroll") for (int k = 0; k < 2; ++k) \
;         acc[ai][bj][m][n] = __builtin_amdgcn_mfma_f32_16x16x32_bf16(Bt[n][k], At[m][k], acc[ai][bj][m][n], 0, 0, 0); __builtin_amdgcn_s_setprio(0); } while (0)
; #define PG8_WAIT_V(n) asm volatile("s_waitcnt vmcnt(" #n ")" ::: "memory")
; #define PG8_WAIT_L(n) asm volatile("s_waitcnt lgkmcnt(" #n ")" ::: "memory")
; #define PG8_BAR __builtin_amdgcn_s_barrier()
; #define PG8_SCHED __builtin_amdgcn_sched_barrier(0)
; template <class Epi, class Sched>
; __device__ __forceinline__ void gemm_phase(int wid_s, PG8_LAS unsigned char* lds, const Gemm g, const Sched& S, const Epi& E) {
;     ...
;             PG8_LDB(B0, 0, 0); PG8_LDB(B1, 0, 1); PG8_SCHED; PG8_LDA(At, 0, 0); PG8_STAGE(PG8_SA(1, 1), a1 + hstepA, voffA);
;             PG8_WAIT_V(8); PG8_WAIT_L(0); PG8_BAR; PG8_MMA(0, 0, At, B0); PG8_MMA(0, 1, At, B1); PG8_BAR; PG8_SCHED;
;             PG8_LDA(At, 0, 1); PG8_STAGE(PG8_SB(0, 0), b2, voffB); PG8_STAGE(PG8_SB(0, 1), b2 + hstepB, voffB); PG8_STAGE(PG8_SA(0, 0), a2, voffA);
.Lmy_kh8:
	ds_read_b128 v[156:159], v155
	ds_read_b128 v[160:163], v155 offset:1024
	ds_read_b128 v[164:167], v155 offset:2048
	ds_read_b128 v[192:195], v155 offset:3072
	v_add_u32_e32 v155, s92, v143
	ds_read_b128 v[196:199], v155
	ds_read_b128 v[200:203], v155 offset:1024
	ds_read_b128 v[204:207], v155 offset:2048
	ds_read_b128 v[208:211], v155 offset:3072
	v_lshl_add_u64 v[188:189], s[26:27], 0, v[140:141]
	s_add_i32 m0, s40, 0xc000
	ds_read_b128 v[212:215], v154
	ds_read_b128 v[216:219], v154 offset:1024
	ds_read_b128 v[220:223], v154 offset:2048
	ds_read_b128 v[224:227], v154 offset:3072
	ds_read_b128 v[228:231], v154 offset:4096
	ds_read_b128 v[232:235], v154 offset:5120
	ds_read_b128 v[236:239], v154 offset:6144
	ds_read_b128 v[240:243], v154 offset:7168
	global_load_lds_dwordx4 v[188:189], off
	v_lshl_add_u64 v[188:189], s[26:27], 0, v[138:139]
	s_add_i32 m0, s40, 0xe000
	s_nop 0
	global_load_lds_dwordx4 v[188:189], off
	s_waitcnt vmcnt(8)
	s_waitcnt lgkmcnt(0)
	s_barrier
	s_setprio 1
	s_waitcnt lgkmcnt(0)
	v_mfma_f32_16x16x32_bf16 v[124:127], v[156:159], v[212:215], v[124:127]
	v_mfma_f32_16x16x32_bf16 v[120:123], v[164:167], v[212:215], v[120:123]
	v_mfma_f32_16x16x32_bf16 v[112:115], v[156:159], v[220:223], v[112:115]
	v_mfma_f32_16x16x32_bf16 v[108:111], v[164:167], v[220:223], v[108:111]
	v_mfma_f32_16x16x32_bf16 v[92:95], v[156:159], v[228:231], v[92:95]
	v_mfma_f32_16x16x32_bf16 v[88:91], v[164:167], v[228:231], v[88:91]
	v_mfma_f32_16x16x32_bf16 v[76:79], v[156:159], v[236:239], v[76:79]
	v_mfma_f32_16x16x32_bf16 v[72:75], v[164:167], v[236:239], v[72:75]
	v_mfma_f32_16x16x32_bf16 v[124:127], v[160:163], v[216:219], v[124:127]
	v_mfma_f32_16x16x32_bf16 v[120:123], v[192:195], v[216:219], v[120:123]
	v_mfma_f32_16x16x32_bf16 v[112:115], v[160:163], v[224:227], v[112:115]
	v_mfma_f32_16x16x32_bf16 v[108:111], v[192:195], v[224:227], v[108:111]
	v_mfma_f32_16x16x32_bf16 v[92:95], v[160:163], v[232:235], v[92:95]
	v_mfma_f32_16x16x32_bf16 v[88:91], v[192:195], v[232:235], v[88:91]
	v_mfma_f32_16x16x32_bf16 v[76:79], v[160:163], v[240:243], v[76:79]
	v_mfma_f32_16x16x32_bf16 v[72:75], v[192:195], v[240:243], v[72:75]
	s_setprio 0
	s_setprio 1
	v_mfma_f32_16x16x32_bf16 v[104:107], v[196:199], v[212:215], v[104:107]
	v_mfma_f32_16x16x32_bf16 v[116:119], v[204:207], v[212:215], v[116:119]
	v_mfma_f32_16x16x32_bf16 v[100:103], v[196:199], v[220:223], v[100:103]
	v_mfma_f32_16x16x32_bf16 v[96:99], v[204:207], v[220:223], v[96:99]
	v_mfma_f32_16x16x32_bf16 v[84:87], v[196:199], v[228:231], v[84:87]
	v_mfma_f32_16x16x32_bf16 v[80:83], v[204:207], v[228:231], v[80:83]
	v_mfma_f32_16x16x32_bf16 v[68:71], v[196:199], v[236:239], v[68:71]
	v_mfma_f32_16x16x32_bf16 v[64:67], v[204:207], v[236:239], v[64:67]
	v_mfma_f32_16x16x32_bf16 v[104:107], v[200:203], v[216:219], v[104:107]
	v_mfma_f32_16x16x32_bf16 v[116:119], v[208:211], v[216:219], v[116:119]
	v_mfma_f32_16x16x32_bf16 v[100:103], v[200:203], v[224:227], v[100:103]
	v_mfma_f32_16x16x32_bf16 v[96:99], v[208:211], v[224:227], v[96:99]
	v_mfma_f32_16x16x32_bf16 v[84:87], v[200:203], v[232:235], v[84:87]
	v_mfma_f32_16x16x32_bf16 v[80:83], v[208:211], v[232:235], v[80:83]
	v_mfma_f32_16x16x32_bf16 v[68:71], v[200:203], v[240:243], v[68:71]
	v_mfma_f32_16x16x32_bf16 v[64:67], v[208:211], v[240:243], v[64:67]
	s_setprio 0
	s_barrier
	s_add_i32 vcc_lo, vcc_lo, s39
	v_lshl_add_u64 v[188:189], s[94:95], 0, v[130:131]
	s_mov_b32 m0, vcc_lo
	ds_read_b128 v[212:215], v154 offset:16384
	ds_read_b128 v[216:219], v154 offset:17408
	ds_read_b128 v[220:223], v154 offset:18432
	ds_read_b128 v[224:227], v154 offset:19456
	ds_read_b128 v[228:231], v154 offset:20480
	ds_read_b128 v[232:235], v154 offset:21504
	ds_read_b128 v[236:239], v154 offset:22528
	ds_read_b128 v[240:243], v154 offset:23552
	global_load_lds_dwordx4 v[188:189], off
	s_add_i32 m0, vcc_lo, 0x2000
	v_lshl_add_u64 v[244:245], s[94:95], 0, v[134:135]
	s_add_u32 s94, s94, s6
	s_addc_u32 s95, s95, s7
	s_add_i32 s92, s92, s39
	global_load_lds_dwordx4 v[244:245], off
	v_lshl_add_u64 v[246:247], s[94:95], 0, v[130:131]
	s_mov_b32 m0, s92
	v_lshl_add_u64 v[248:249], s[94:95], 0, v[134:135]
	global_load_lds_dwordx4 v[246:247], off
	s_add_i32 m0, s92, 0x2000
	v_lshl_add_u64 v[250:251], s[28:29], 0, v[128:129]
	global_load_lds_dwordx4 v[248:249], off
	s_mov_b32 m0, s40
	v_lshl_add_u64 v[252:253], s[28:29], 0, v[132:133]
	global_load_lds_dwordx4 v[250:251], off
	s_mov_b32 m0, s41
	s_nop 0
	global_load_lds_dwordx4 v[252:253], off
	s_waitcnt vmcnt(8)
	s_waitcnt lgkmcnt(0)
	s_barrier
; #define PG8_STAGE(bufoff, gbase, voff) do { _Pragma("unroll") for (int _i = 0; _i < 2; ++_i) \
;         __builtin_amdgcn_global_load_lds((const unsigned*)((const char*)(gbase) + (voff)[_i]), (PG8_LAS unsigned*)(lds + (bufoff) + ldsw + _i * 8192), 16, 0, 0); } while (0)
; #define PG8_LDA(dst, b, h) do { _Pragma("unroll") for (int m = 0; m < 4; ++m) _Pragma("unroll") for (int k = 0; k < 2; ++k) dst[m][k] = *(const PG8_LAS bf16x8*)(lds + PG8_SA(b, h) + aoff + m * 2048 + k * 1024); } while (0)
; #define PG8_LDB(dst, b, h) do { _Pragma("unroll") for (int n = 0; n < 2; ++n) _Pragma("unroll") for (int k = 0; k < 2; ++k) dst[n][k] = *(const PG8_LAS bf16x8*)(lds + PG8_SB(b, h) + boff + n * 2048 + k * 1024); } while (0)
; #define PG8_MMA(ai, bj, At, Bt) do { __builtin_amdgcn_s_setprio(1); _Pragma("unroll") for (int m = 0; m < 4; ++m) _Pragma("unroll") for (int n = 0; n < 2; ++n) _Pragma("unroll") for (int k = 0; k < 2; ++k) \
;         acc[ai][bj][m][n] = __builtin_amdgcn_mfma_f32_16x16x32_bf16(Bt[n][k], At[m][k], acc[ai][bj][m][n], 0, 0, 0); __builtin_amdgcn_s_setprio(0); } while (0)
; #define PG8_WAIT_V(n) asm volatile("s_waitcnt vmcnt(" #n ")" ::: "memory")
; #define PG8_WAIT_L(n) asm volatile("s_waitcnt lgkmcnt(" #n ")" ::: "memory")
; #define PG8_BAR __builtin_amdgcn_s_barrier()
; #define PG8_SCHED __builtin_amdgcn_sched_barrier(0)
; template <class Epi, class Sched>
; __device__ __forceinline__ void gemm_phase(int wid_s, PG8_LAS unsigned char* lds, const Gemm g, const Sched& S, const Epi& E) {
;     ...
;             PG8_WAIT_V(8); PG8_WAIT_L(0); PG8_BAR; PG8_MMA(1, 0, At, B0); PG8_MMA(1, 1, At, B1); PG8_BAR; PG8_SCHED;
;             PG8_LDB(B0, 1, 0); PG8_LDB(B1, 1, 1); PG8_SCHED; PG8_LDA(At, 1, 0); PG8_STAGE(PG8_SA(0, 1), a2 + hstepA, voffA);
;             PG8_WAIT_V(8); PG8_WAIT_L(0); PG8_BAR; PG8_MMA(0, 0, At, B0); PG8_MMA(0, 1, At, B1); PG8_BAR; PG8_SCHED;
	s_setprio 1
	s_waitcnt lgkmcnt(0)
	v_mfma_f32_16x16x32_bf16 v[60:63], v[156:159], v[212:215], v[60:63]
	v_mfma_f32_16x16x32_bf16 v[56:59], v[164:167], v[212:215], v[56:59]
	v_mfma_f32_16x16x32_bf16 v[44:47], v[156:159], v[220:223], v[44:47]
	v_mfma_f32_16x16x32_bf16 v[40:43], v[164:167], v[220:223], v[40:43]
	v_mfma_f32_16x16x32_bf16 v[28:31], v[156:159], v[228:231], v[28:31]
	v_mfma_f32_16x16x32_bf16 v[24:27], v[164:167], v[228:231], v[24:27]
	v_mfma_f32_16x16x32_bf16 v[12:15], v[156:159], v[236:239], v[12:15]
	v_mfma_f32_16x16x32_bf16 v[8:11], v[164:167], v[236:239], v[8:11]
	v_mfma_f32_16x16x32_bf16 v[60:63], v[160:163], v[216:219], v[60:63]
	v_mfma_f32_16x16x32_bf16 v[56:59], v[192:195], v[216:219], v[56:59]
	v_mfma_f32_16x16x32_bf16 v[44:47], v[160:163], v[224:227], v[44:47]
	v_mfma_f32_16x16x32_bf16 v[40:43], v[192:195], v[224:227], v[40:43]
	v_mfma_f32_16x16x32_bf16 v[28:31], v[160:163], v[232:235], v[28:31]
	v_mfma_f32_16x16x32_bf16 v[24:27], v[192:195], v[232:235], v[24:27]
	v_mfma_f32_16x16x32_bf16 v[12:15], v[160:163], v[240:243], v[12:15]
	v_mfma_f32_16x16x32_bf16 v[8:11], v[192:195], v[240:243], v[8:11]
	s_setprio 0
	s_setprio 1
	v_mfma_f32_16x16x32_bf16 v[52:55], v[196:199], v[212:215], v[52:55]
	v_mfma_f32_16x16x32_bf16 v[48:51], v[204:207], v[212:215], v[48:51]
	v_mfma_f32_16x16x32_bf16 v[36:39], v[196:199], v[220:223], v[36:39]
	v_mfma_f32_16x16x32_bf16 v[32:35], v[204:207], v[220:223], v[32:35]
	v_mfma_f32_16x16x32_bf16 v[20:23], v[196:199], v[228:231], v[20:23]
	v_mfma_f32_16x16x32_bf16 v[16:19], v[204:207], v[228:231], v[16:19]
	v_mfma_f32_16x16x32_bf16 v[4:7], v[196:199], v[236:239], v[4:7]
	v_mfma_f32_16x16x32_bf16 v[0:3], v[204:207], v[236:239], v[0:3]
	v_mfma_f32_16x16x32_bf16 v[52:55], v[200:203], v[216:219], v[52:55]
	v_mfma_f32_16x16x32_bf16 v[48:51], v[208:211], v[216:219], v[48:51]
	v_mfma_f32_16x16x32_bf16 v[36:39], v[200:203], v[224:227], v[36:39]
	v_mfma_f32_16x16x32_bf16 v[32:35], v[208:211], v[224:227], v[32:35]
	v_mfma_f32_16x16x32_bf16 v[20:23], v[200:203], v[232:235], v[20:23]
	v_mfma_f32_16x16x32_bf16 v[16:19], v[208:211], v[232:235], v[16:19]
	v_mfma_f32_16x16x32_bf16 v[4:7], v[200:203], v[240:243], v[4:7]
	v_mfma_f32_16x16x32_bf16 v[0:3], v[208:211], v[240:243], v[0:3]
	s_setprio 0
	s_barrier
	s_add_i32 s92, 0, 0x18000
	v_add_u32_e32 v155, s92, v143
	s_add_i32 s94, 0, 0x1c000
	ds_read_b128 v[156:159], v155
	ds_read_b128 v[160:163], v155 offset:1024
	ds_read_b128 v[164:167], v155 offset:2048
	ds_read_b128 v[192:195], v155 offset:3072
	v_add_u32_e32 v155, s94, v143
	ds_read_b128 v[196:199], v155
	ds_read_b128 v[200:203], v155 offset:1024
	ds_read_b128 v[204:207], v155 offset:2048
	ds_read_b128 v[208:211], v155 offset:3072
	s_add_u32 s28, s28, s4
	s_addc_u32 s29, s29, s5
	s_mov_b32 m0, s42
	v_lshl_add_u64 v[190:191], s[28:29], 0, v[128:129]
	ds_read_b128 v[212:215], v154 offset:32768
	ds_read_b128 v[216:219], v154 offset:33792
	ds_read_b128 v[220:223], v154 offset:34816
	ds_read_b128 v[224:227], v154 offset:35840
	ds_read_b128 v[228:231], v154 offset:36864
	ds_read_b128 v[232:235], v154 offset:37888
	ds_read_b128 v[236:239], v154 offset:38912
	ds_read_b128 v[240:243], v154 offset:39936
	global_load_lds_dwordx4 v[190:191], off
	v_lshl_add_u64 v[190:191], s[28:29], 0, v[132:133]
	s_mov_b32 m0, s44
	s_nop 0
	global_load_lds_dwordx4 v[190:191], off
	s_waitcnt vmcnt(8)
	s_waitcnt lgkmcnt(0)
	s_barrier
	s_setprio 1
	s_waitcnt lgkmcnt(0)
	v_mfma_f32_16x16x32_bf16 v[124:127], v[156:159], v[212:215], v[124:127]
	v_mfma_f32_16x16x32_bf16 v[120:123], v[164:167], v[212:215], v[120:123]
	v_mfma_f32_16x16x32_bf16 v[112:115], v[156:159], v[220:223], v[112:115]
	v_mfma_f32_16x16x32_bf16 v[108:111], v[164:167], v[220:223], v[108:111]
	v_mfma_f32_16x16x32_bf16 v[92:95], v[156:159], v[228:231], v[92:95]
	v_mfma_f32_16x16x32_bf16 v[88:91], v[164:167], v[228:231], v[88:91]
	v_mfma_f32_16x16x32_bf16 v[76:79], v[156:159], v[236:239], v[76:79]
	v_mfma_f32_16x16x32_bf16 v[72:75], v[164:167], v[236:239], v[72:75]
	v_mfma_f32_16x16x32_bf16 v[124:127], v[160:163], v[216:219], v[124:127]
	v_mfma_f32_16x16x32_bf16 v[120:123], v[192:195], v[216:219], v[120:123]
	v_mfma_f32_16x16x32_bf16 v[112:115], v[160:163], v[224:227], v[112:115]
	v_mfma_f32_16x16x32_bf16 v[108:111], v[192:195], v[224:227], v[108:111]
	v_mfma_f32_16x16x32_bf16 v[92:95], v[160:163], v[232:235], v[92:95]
	v_mfma_f32_16x16x32_bf16 v[88:91], v[192:195], v[232:235], v[88:91]
	v_mfma_f32_16x16x32_bf16 v[76:79], v[160:163], v[240:243], v[76:79]
	v_mfma_f32_16x16x32_bf16 v[72:75], v[192:195], v[240:243], v[72:75]
	s_setprio 0
	s_setprio 1
	v_mfma_f32_16x16x32_bf16 v[104:107], v[196:199], v[212:215], v[104:107]
	v_mfma_f32_16x16x32_bf16 v[116:119], v[204:207], v[212:215], v[116:119]
	v_mfma_f32_16x16x32_bf16 v[100:103], v[196:199], v[220:223], v[100:103]
	v_mfma_f32_16x16x32_bf16 v[96:99], v[204:207], v[220:223], v[96:99]
	v_mfma_f32_16x16x32_bf16 v[84:87], v[196:199], v[228:231], v[84:87]
	v_mfma_f32_16x16x32_bf16 v[80:83], v[204:207], v[228:231], v[80:83]
	v_mfma_f32_16x16x32_bf16 v[68:71], v[196:199], v[236:239], v[68:71]
	v_mfma_f32_16x16x32_bf16 v[64:67], v[204:207], v[236:239], v[64:67]
	v_mfma_f32_16x16x32_bf16 v[104:107], v[200:203], v[216:219], v[104:107]
	v_mfma_f32_16x16x32_bf16 v[116:119], v[208:211], v[216:219], v[116:119]
	v_mfma_f32_16x16x32_bf16 v[100:103], v[200:203], v[224:227], v[100:103]
	v_mfma_f32_16x16x32_bf16 v[96:99], v[208:211], v[224:227], v[96:99]
	v_mfma_f32_16x16x32_bf16 v[84:87], v[200:203], v[232:235], v[84:87]
	v_mfma_f32_16x16x32_bf16 v[80:83], v[208:211], v[232:235], v[80:83]
	v_mfma_f32_16x16x32_bf16 v[68:71], v[200:203], v[240:243], v[68:71]
	v_mfma_f32_16x16x32_bf16 v[64:67], v[208:211], v[240:243], v[64:67]
	s_setprio 0
	s_barrier
; #define PG8_STAGE(bufoff, gbase, voff) do { _Pragma("unroll") for (int _i = 0; _i < 2; ++_i) \
;         __builtin_amdgcn_global_load_lds((const unsigned*)((const char*)(gbase) + (voff)[_i]), (PG8_LAS unsigned*)(lds + (bufoff) + ldsw + _i * 8192), 16, 0, 0); } while (0)
; #define PG8_LDA(dst, b, h) do { _Pragma("unroll") for (int m = 0; m < 4; ++m) _Pragma("unroll") for (int k = 0; k < 2; ++k) dst[m][k] = *(const PG8_LAS bf16x8*)(lds + PG8_SA(b, h) + aoff + m * 2048 + k * 1024); } while (0)
; #define PG8_MMA(ai, bj, At, Bt) do { __builtin_amdgcn_s_setprio(1); _Pragma("unroll") for (int m = 0; m < 4; ++m) _Pragma("unroll") for (int n = 0; n < 2; ++n) _Pragma("unroll") for (int k = 0; k < 2; ++k) \
;         acc[ai][bj][m][n] = __builtin_amdgcn_mfma_f32_16x16x32_bf16(Bt[n][k], At[m][k], acc[ai][bj][m][n], 0, 0, 0); __builtin_amdgcn_s_setprio(0); } while (0)
; #define PG8_WAIT_V(n) asm volatile("s_waitcnt vmcnt(" #n ")" ::: "memory")
; #define PG8_WAIT_L(n) asm volatile("s_waitcnt lgkmcnt(" #n ")" ::: "memory")
; #define PG8_BAR __builtin_amdgcn_s_barrier()
; #define PG8_SCHED __builtin_amdgcn_sched_barrier(0)
; template <class Epi, class Sched>
; __device__ __forceinline__ void gemm_phase(int wid_s, PG8_LAS unsigned char* lds, const Gemm g, const Sched& S, const Epi& E) {
;     ...
;         for (int t = 0; t < nt; t += 2) {
;             const bool last = (t == nt - 2);
;             const char* a1 = cA + (size_t)(t + 1) * kstep;
;             const char* a2 = last ? nA : cA + (size_t)(t + 2) * kstep; const char* b2 = last ? nB : cB + (size_t)(t + 2) * kstep;
;             const char* a3 = a2 + kstep; const char* b3 = b2 + kstep;
;     ...
;             PG8_LDA(At, 1, 1); PG8_STAGE(PG8_SB(1, 0), b3, voffB); PG8_STAGE(PG8_SB(1, 1), b3 + hstepB, voffB); PG8_STAGE(PG8_SA(1, 0), a3, voffA);
;             PG8_WAIT_V(8); PG8_WAIT_L(0); PG8_BAR; PG8_MMA(1, 0, At, B0); PG8_MMA(1, 1, At, B1); PG8_BAR; PG8_SCHED;
	s_add_i32 s28, s92, s39
	v_lshl_add_u64 v[188:189], v[188:189], 0, s[96:97]
	s_mov_b32 m0, s28
	ds_read_b128 v[212:215], v154 offset:49152
	ds_read_b128 v[216:219], v154 offset:50176
	ds_read_b128 v[220:223], v154 offset:51200
	ds_read_b128 v[224:227], v154 offset:52224
	ds_read_b128 v[228:231], v154 offset:53248
	ds_read_b128 v[232:235], v154 offset:54272
	ds_read_b128 v[236:239], v154 offset:55296
	ds_read_b128 v[240:243], v154 offset:56320
	global_load_lds_dwordx4 v[188:189], off
	v_lshl_add_u64 v[188:189], v[244:245], 0, s[96:97]
	s_add_i32 m0, s28, 0x2000
	s_add_i32 s28, s94, s39
	global_load_lds_dwordx4 v[188:189], off
	v_lshl_add_u64 v[188:189], v[246:247], 0, s[96:97]
	s_mov_b32 m0, s28
	s_nop 0
	global_load_lds_dwordx4 v[188:189], off
	v_lshl_add_u64 v[188:189], v[248:249], 0, s[96:97]
	s_add_i32 m0, s28, 0x2000
	s_nop 0
	global_load_lds_dwordx4 v[188:189], off
	v_lshl_add_u64 v[188:189], v[250:251], 0, s[96:97]
	s_mov_b32 m0, s47
	s_nop 0
	global_load_lds_dwordx4 v[188:189], off
	v_lshl_add_u64 v[188:189], v[252:253], 0, s[96:97]
	s_mov_b32 m0, s48
	s_nop 0
	global_load_lds_dwordx4 v[188:189], off
	s_waitcnt vmcnt(8)
	s_waitcnt lgkmcnt(0)
	s_barrier
	s_setprio 1
	s_waitcnt lgkmcnt(0)
	v_mfma_f32_16x16x32_bf16 v[60:63], v[156:159], v[212:215], v[60:63]
	v_mfma_f32_16x16x32_bf16 v[56:59], v[164:167], v[212:215], v[56:59]
	v_mfma_f32_16x16x32_bf16 v[44:47], v[156:159], v[220:223], v[44:47]
	v_mfma_f32_16x16x32_bf16 v[40:43], v[164:167], v[220:223], v[40:43]
	v_mfma_f32_16x16x32_bf16 v[28:31], v[156:159], v[228:231], v[28:31]
	v_mfma_f32_16x16x32_bf16 v[24:27], v[164:167], v[228:231], v[24:27]
	v_mfma_f32_16x16x32_bf16 v[12:15], v[156:159], v[236:239], v[12:15]
	v_mfma_f32_16x16x32_bf16 v[8:11], v[164:167], v[236:239], v[8:11]
	v_mfma_f32_16x16x32_bf16 v[60:63], v[160:163], v[216:219], v[60:63]
	v_mfma_f32_16x16x32_bf16 v[56:59], v[192:195], v[216:219], v[56:59]
	v_mfma_f32_16x16x32_bf16 v[44:47], v[160:163], v[224:227], v[44:47]
	v_mfma_f32_16x16x32_bf16 v[40:43], v[192:195], v[224:227], v[40:43]
	v_mfma_f32_16x16x32_bf16 v[28:31], v[160:163], v[232:235], v[28:31]
	v_mfma_f32_16x16x32_bf16 v[24:27], v[192:195], v[232:235], v[24:27]
	v_mfma_f32_16x16x32_bf16 v[12:15], v[160:163], v[240:243], v[12:15]
	v_mfma_f32_16x16x32_bf16 v[8:11], v[192:195], v[240:243], v[8:11]
	s_setprio 0
	s_setprio 1
	v_mfma_f32_16x16x32_bf16 v[52:55], v[196:199], v[212:215], v[52:55]
	s_add_u32 s33, s33, 0x100
	s_addc_u32 s56, s56, 0
	v_mfma_f32_16x16x32_bf16 v[48:51], v[204:207], v[212:215], v[48:51]
	s_add_u32 s26, s26, 0x100
	s_addc_u32 s27, s27, 0
	v_mfma_f32_16x16x32_bf16 v[36:39], v[196:199], v[220:223], v[36:39]
	s_cmp_ge_i32 s57, s45
	s_mov_b32 s28, s57
	s_cbranch_scc1 .Lmy_kx8
	v_mfma_f32_16x16x32_bf16 v[32:35], v[204:207], v[220:223], v[32:35]
	s_add_i32 s57, s28, 2
	v_mfma_f32_16x16x32_bf16 v[20:23], v[196:199], v[228:231], v[20:23]
	s_add_u32 s92, s26, 0x80
	v_mfma_f32_16x16x32_bf16 v[16:19], v[204:207], v[228:231], v[16:19]
	s_addc_u32 s29, s27, 0
	v_mfma_f32_16x16x32_bf16 v[4:7], v[196:199], v[236:239], v[4:7]
	s_add_i32 vcc_lo, 0, 0x10000
	v_mfma_f32_16x16x32_bf16 v[0:3], v[204:207], v[236:239], v[0:3]
	s_cmp_eq_u32 s49, s28
	v_mfma_f32_16x16x32_bf16 v[52:55], v[200:203], v[216:219], v[52:55]
	s_cselect_b32 s29, s23, s29
	v_mfma_f32_16x16x32_bf16 v[48:51], v[208:211], v[216:219], v[48:51]
	s_cselect_b32 s28, s22, s92
	v_mfma_f32_16x16x32_bf16 v[36:39], v[200:203], v[224:227], v[36:39]
	v_add_u32_e32 v155, vcc_lo, v143
	v_mfma_f32_16x16x32_bf16 v[32:35], v[208:211], v[224:227], v[32:35]
	s_cselect_b32 s95, s25, s56
	v_mfma_f32_16x16x32_bf16 v[20:23], v[200:203], v[232:235], v[20:23]
	s_cselect_b32 s94, s24, s33
	v_mfma_f32_16x16x32_bf16 v[16:19], v[208:211], v[232:235], v[16:19]
	s_add_i32 s92, 0, 0x14000
	v_mfma_f32_16x16x32_bf16 v[4:7], v[200:203], v[240:243], v[4:7]
	v_mfma_f32_16x16x32_bf16 v[0:3], v[208:211], v[240:243], v[0:3]
	s_setprio 0
	s_barrier
	s_branch .Lmy_kh8
.Lmy_kx8:
	v_mfma_f32_16x16x32_bf16 v[32:35], v[204:207], v[220:223], v[32:35]
	v_mfma_f32_16x16x32_bf16 v[20:23], v[196:199], v[228:231], v[20:23]
	v_mfma_f32_16x16x32_bf16 v[16:19], v[204:207], v[228:231], v[16:19]
	v_mfma_f32_16x16x32_bf16 v[4:7], v[196:199], v[236:239], v[4:7]
	v_mfma_f32_16x16x32_bf16 v[0:3], v[204:207], v[236:239], v[0:3]
	v_mfma_f32_16x16x32_bf16 v[52:55], v[200:203], v[216:219], v[52:55]
	v_mfma_f32_16x16x32_bf16 v[48:51], v[208:211], v[216:219], v[48:51]
	v_mfma_f32_16x16x32_bf16 v[36:39], v[200:203], v[224:227], v[36:39]
	v_mfma_f32_16x16x32_bf16 v[32:35], v[208:211], v[224:227], v[32:35]
	v_mfma_f32_16x16x32_bf16 v[20:23], v[200:203], v[232:235], v[20:23]
	v_mfma_f32_16x16x32_bf16 v[16:19], v[208:211], v[232:235], v[16:19]
	v_mfma_f32_16x16x32_bf16 v[4:7], v[200:203], v[240:243], v[4:7]
	v_mfma_f32_16x16x32_bf16 v[0:3], v[208:211], v[240:243], v[0:3]
	s_setprio 0
	s_barrier
	v_readlane_b32 s95, v254, 51
	v_readlane_b32 s92, v254, 54
	v_readlane_b32 s94, v254, 55
	s_and_b64 vcc, exec, s[20:21]
	s_cbranch_vccnz .LBB0_1850
	s_branch .LBB0_1851

; #define PG8_STAGE(bufoff, gbase, voff) do { _Pragma("unroll") for (int _i = 0; _i < 2; ++_i) \
;         __builtin_amdgcn_global_load_lds((const unsigned*)((const char*)(gbase) + (voff)[_i]), (PG8_LAS unsigned*)(lds + (bufoff) + ldsw + _i * 8192), 16, 0, 0); } while (0)
; #define PG8_LDA(dst, b, h) do { _Pragma("unroll") for (int m = 0; m < 4; ++m) _Pragma("unroll") for (int k = 0; k < 2; ++k) dst[m][k] = *(const PG8_LAS bf16x8*)(lds + PG8_SA(b, h) + aoff + m * 2048 + k * 1024); } while (0)
; #define PG8_LDB(dst, b, h) do { _Pragma("unroll") for (int n = 0; n < 2; ++n) _Pragma("unroll") for (int k = 0; k < 2; ++k) dst[n][k] = *(const PG8_LAS bf16x8*)(lds + PG8_SB(b, h) + boff + n * 2048 + k * 1024); } while (0)
; #define PG8_MMA(ai, bj, At, Bt) do { __builtin_amdgcn_s_setprio(1); _Pragma("unroll") for (int m = 0; m < 4; ++m) _Pragma("unroll") for (int n = 0; n < 2; ++n) _Pragma("unroll") for (int k = 0; k < 2; ++k) \
;         acc[ai][bj][m][n] = __builtin_amdgcn_mfma_f32_16x16x32_bf16(Bt[n][k], At[m][k], acc[ai][bj][m][n], 0, 0, 0); __builtin_amdgcn_s_setprio(0); } while (0)
; #define PG8_WAIT_V(n) asm volatile("s_waitcnt vmcnt(" #n ")" ::: "memory")
; #define PG8_WAIT_L(n) asm volatile("s_waitcnt lgkmcnt(" #n ")" ::: "memory")
; #define PG8_BAR __builtin_amdgcn_s_barrier()
; #define PG8_SCHED __builtin_amdgcn_sched_barrier(0)
; template <class Epi, class Sched>
; __device__ __forceinline__ void gemm_phase(int wid_s, PG8_LAS unsigned char* lds, const Gemm g, const Sched& S, const Epi& E) {
;     ...
;             PG8_LDB(B0, 0, 0); PG8_LDB(B1, 0, 1); PG8_SCHED; PG8_LDA(At, 0, 0); PG8_STAGE(PG8_SA(1, 1), a1 + hstepA, voffA);
;             PG8_WAIT_V(8); PG8_WAIT_L(0); PG8_BAR; PG8_MMA(0, 0, At, B0); PG8_MMA(0, 1, At, B1); PG8_BAR; PG8_SCHED;
;             PG8_LDA(At, 0, 1); PG8_STAGE(PG8_SB(0, 0), b2, voffB); PG8_STAGE(PG8_SB(0, 1), b2 + hstepB, voffB); PG8_STAGE(PG8_SA(0, 0), a2, voffA);
.Lmy_kh9:
	ds_read_b128 v[156:159], v138
	ds_read_b128 v[160:163], v138 offset:1024
	ds_read_b128 v[164:167], v138 offset:2048
	ds_read_b128 v[188:191], v138 offset:3072
	v_add_u32_e32 v138, s94, v142
	ds_read_b128 v[192:195], v138
	ds_read_b128 v[196:199], v138 offset:1024
	ds_read_b128 v[200:203], v138 offset:2048
	ds_read_b128 v[204:207], v138 offset:3072
	v_lshl_add_u64 v[138:139], s[26:27], 0, v[136:137]
	s_add_i32 m0, s39, 0xc000
	ds_read_b128 v[208:211], v154
	ds_read_b128 v[212:215], v154 offset:1024
	ds_read_b128 v[216:219], v154 offset:2048
	ds_read_b128 v[220:223], v154 offset:3072
	ds_read_b128 v[224:227], v154 offset:4096
	ds_read_b128 v[228:231], v154 offset:5120
	ds_read_b128 v[232:235], v154 offset:6144
	ds_read_b128 v[236:239], v154 offset:7168
	global_load_lds_dwordx4 v[138:139], off
	v_lshl_add_u64 v[138:139], s[26:27], 0, v[134:135]
	s_add_i32 m0, s39, 0xe000
	s_nop 0
	global_load_lds_dwordx4 v[138:139], off
	s_waitcnt vmcnt(8)
	s_waitcnt lgkmcnt(0)
	s_barrier
	s_setprio 1
	s_waitcnt lgkmcnt(0)
	v_mfma_f32_16x16x32_bf16 v[120:123], v[156:159], v[208:211], v[120:123]
	v_mfma_f32_16x16x32_bf16 v[124:127], v[164:167], v[208:211], v[124:127]
	v_mfma_f32_16x16x32_bf16 v[108:111], v[156:159], v[216:219], v[108:111]
	v_mfma_f32_16x16x32_bf16 v[104:107], v[164:167], v[216:219], v[104:107]
	v_mfma_f32_16x16x32_bf16 v[92:95], v[156:159], v[224:227], v[92:95]
	v_mfma_f32_16x16x32_bf16 v[88:91], v[164:167], v[224:227], v[88:91]
	v_mfma_f32_16x16x32_bf16 v[76:79], v[156:159], v[232:235], v[76:79]
	v_mfma_f32_16x16x32_bf16 v[72:75], v[164:167], v[232:235], v[72:75]
	v_mfma_f32_16x16x32_bf16 v[120:123], v[160:163], v[212:215], v[120:123]
	v_mfma_f32_16x16x32_bf16 v[124:127], v[188:191], v[212:215], v[124:127]
	v_mfma_f32_16x16x32_bf16 v[108:111], v[160:163], v[220:223], v[108:111]
	v_mfma_f32_16x16x32_bf16 v[104:107], v[188:191], v[220:223], v[104:107]
	v_mfma_f32_16x16x32_bf16 v[92:95], v[160:163], v[228:231], v[92:95]
	v_mfma_f32_16x16x32_bf16 v[88:91], v[188:191], v[228:231], v[88:91]
	v_mfma_f32_16x16x32_bf16 v[76:79], v[160:163], v[236:239], v[76:79]
	v_mfma_f32_16x16x32_bf16 v[72:75], v[188:191], v[236:239], v[72:75]
	s_setprio 0
	s_setprio 1
	v_mfma_f32_16x16x32_bf16 v[116:119], v[192:195], v[208:211], v[116:119]
	v_mfma_f32_16x16x32_bf16 v[112:115], v[200:203], v[208:211], v[112:115]
	v_mfma_f32_16x16x32_bf16 v[100:103], v[192:195], v[216:219], v[100:103]
	v_mfma_f32_16x16x32_bf16 v[96:99], v[200:203], v[216:219], v[96:99]
	v_mfma_f32_16x16x32_bf16 v[84:87], v[192:195], v[224:227], v[84:87]
	v_mfma_f32_16x16x32_bf16 v[80:83], v[200:203], v[224:227], v[80:83]
	v_mfma_f32_16x16x32_bf16 v[68:71], v[192:195], v[232:235], v[68:71]
	v_mfma_f32_16x16x32_bf16 v[64:67], v[200:203], v[232:235], v[64:67]
	v_mfma_f32_16x16x32_bf16 v[116:119], v[196:199], v[212:215], v[116:119]
	v_mfma_f32_16x16x32_bf16 v[112:115], v[204:207], v[212:215], v[112:115]
	v_mfma_f32_16x16x32_bf16 v[100:103], v[196:199], v[220:223], v[100:103]
	v_mfma_f32_16x16x32_bf16 v[96:99], v[204:207], v[220:223], v[96:99]
	v_mfma_f32_16x16x32_bf16 v[84:87], v[196:199], v[228:231], v[84:87]
	v_mfma_f32_16x16x32_bf16 v[80:83], v[204:207], v[228:231], v[80:83]
	v_mfma_f32_16x16x32_bf16 v[68:71], v[196:199], v[236:239], v[68:71]
	v_mfma_f32_16x16x32_bf16 v[64:67], v[204:207], v[236:239], v[64:67]
	s_setprio 0
	s_barrier
	s_add_i32 s92, s92, s37
	v_lshl_add_u64 v[138:139], s[56:57], 0, v[144:145]
	s_mov_b32 m0, s92
	ds_read_b128 v[208:211], v154 offset:16384
	ds_read_b128 v[212:215], v154 offset:17408
	ds_read_b128 v[216:219], v154 offset:18432
	ds_read_b128 v[220:223], v154 offset:19456
	ds_read_b128 v[224:227], v154 offset:20480
	ds_read_b128 v[228:231], v154 offset:21504
	ds_read_b128 v[232:235], v154 offset:22528
	ds_read_b128 v[236:239], v154 offset:23552
	global_load_lds_dwordx4 v[138:139], off
	s_add_i32 m0, s92, 0x2000
	v_lshl_add_u64 v[240:241], s[56:57], 0, v[132:133]
	s_add_u32 s56, s56, s8
	s_addc_u32 s57, s57, s9
	s_add_i32 s92, s94, s37
	global_load_lds_dwordx4 v[240:241], off
	v_lshl_add_u64 v[242:243], s[56:57], 0, v[144:145]
	s_mov_b32 m0, s92
	v_lshl_add_u64 v[244:245], s[56:57], 0, v[132:133]
	global_load_lds_dwordx4 v[242:243], off
	s_add_i32 m0, s92, 0x2000
	v_lshl_add_u64 v[246:247], s[28:29], 0, v[128:129]
	global_load_lds_dwordx4 v[244:245], off
	s_mov_b32 m0, s39
	v_lshl_add_u64 v[248:249], s[28:29], 0, v[130:131]
	global_load_lds_dwordx4 v[246:247], off
	s_mov_b32 m0, s40
	s_nop 0
	global_load_lds_dwordx4 v[248:249], off
	s_waitcnt vmcnt(8)
	s_waitcnt lgkmcnt(0)
	s_barrier
; #define PG8_STAGE(bufoff, gbase, voff) do { _Pragma("unroll") for (int _i = 0; _i < 2; ++_i) \
;         __builtin_amdgcn_global_load_lds((const unsigned*)((const char*)(gbase) + (voff)[_i]), (PG8_LAS unsigned*)(lds + (bufoff) + ldsw + _i * 8192), 16, 0, 0); } while (0)
; #define PG8_LDA(dst, b, h) do { _Pragma("unroll") for (int m = 0; m < 4; ++m) _Pragma("unroll") for (int k = 0; k < 2; ++k) dst[m][k] = *(const PG8_LAS bf16x8*)(lds + PG8_SA(b, h) + aoff + m * 2048 + k * 1024); } while (0)
; #define PG8_LDB(dst, b, h) do { _Pragma("unroll") for (int n = 0; n < 2; ++n) _Pragma("unroll") for (int k = 0; k < 2; ++k) dst[n][k] = *(const PG8_LAS bf16x8*)(lds + PG8_SB(b, h) + boff + n * 2048 + k * 1024); } while (0)
; #define PG8_MMA(ai, bj, At, Bt) do { __builtin_amdgcn_s_setprio(1); _Pragma("unroll") for (int m = 0; m < 4; ++m) _Pragma("unroll") for (int n = 0; n < 2; ++n) _Pragma("unroll") for (int k = 0; k < 2; ++k) \
;         acc[ai][bj][m][n] = __builtin_amdgcn_mfma_f32_16x16x32_bf16(Bt[n][k], At[m][k], acc[ai][bj][m][n], 0, 0, 0); __builtin_amdgcn_s_setprio(0); } while (0)
; #define PG8_WAIT_V(n) asm volatile("s_waitcnt vmcnt(" #n ")" ::: "memory")
; #define PG8_WAIT_L(n) asm volatile("s_waitcnt lgkmcnt(" #n ")" ::: "memory")
; #define PG8_BAR __builtin_amdgcn_s_barrier()
; #define PG8_SCHED __builtin_amdgcn_sched_barrier(0)
; template <class Epi, class Sched>
; __device__ __forceinline__ void gemm_phase(int wid_s, PG8_LAS unsigned char* lds, const Gemm g, const Sched& S, const Epi& E) {
;     ...
;             PG8_WAIT_V(8); PG8_WAIT_L(0); PG8_BAR; PG8_MMA(1, 0, At, B0); PG8_MMA(1, 1, At, B1); PG8_BAR; PG8_SCHED;
;             PG8_LDB(B0, 1, 0); PG8_LDB(B1, 1, 1); PG8_SCHED; PG8_LDA(At, 1, 0); PG8_STAGE(PG8_SA(0, 1), a2 + hstepA, voffA);
;             PG8_WAIT_V(8); PG8_WAIT_L(0); PG8_BAR; PG8_MMA(0, 0, At, B0); PG8_MMA(0, 1, At, B1); PG8_BAR; PG8_SCHED;
	s_setprio 1
	s_waitcnt lgkmcnt(0)
	v_mfma_f32_16x16x32_bf16 v[60:63], v[156:159], v[208:211], v[60:63]
	v_mfma_f32_16x16x32_bf16 v[56:59], v[164:167], v[208:211], v[56:59]
	v_mfma_f32_16x16x32_bf16 v[44:47], v[156:159], v[216:219], v[44:47]
	v_mfma_f32_16x16x32_bf16 v[40:43], v[164:167], v[216:219], v[40:43]
	v_mfma_f32_16x16x32_bf16 v[28:31], v[156:159], v[224:227], v[28:31]
	v_mfma_f32_16x16x32_bf16 v[24:27], v[164:167], v[224:227], v[24:27]
	v_mfma_f32_16x16x32_bf16 v[12:15], v[156:159], v[232:235], v[12:15]
	v_mfma_f32_16x16x32_bf16 v[8:11], v[164:167], v[232:235], v[8:11]
	v_mfma_f32_16x16x32_bf16 v[60:63], v[160:163], v[212:215], v[60:63]
	v_mfma_f32_16x16x32_bf16 v[56:59], v[188:191], v[212:215], v[56:59]
	v_mfma_f32_16x16x32_bf16 v[44:47], v[160:163], v[220:223], v[44:47]
	v_mfma_f32_16x16x32_bf16 v[40:43], v[188:191], v[220:223], v[40:43]
	v_mfma_f32_16x16x32_bf16 v[28:31], v[160:163], v[228:231], v[28:31]
	v_mfma_f32_16x16x32_bf16 v[24:27], v[188:191], v[228:231], v[24:27]
	v_mfma_f32_16x16x32_bf16 v[12:15], v[160:163], v[236:239], v[12:15]
	v_mfma_f32_16x16x32_bf16 v[8:11], v[188:191], v[236:239], v[8:11]
	s_setprio 0
	s_setprio 1
	v_mfma_f32_16x16x32_bf16 v[52:55], v[192:195], v[208:211], v[52:55]
	v_mfma_f32_16x16x32_bf16 v[48:51], v[200:203], v[208:211], v[48:51]
	v_mfma_f32_16x16x32_bf16 v[36:39], v[192:195], v[216:219], v[36:39]
	v_mfma_f32_16x16x32_bf16 v[32:35], v[200:203], v[216:219], v[32:35]
	v_mfma_f32_16x16x32_bf16 v[20:23], v[192:195], v[224:227], v[20:23]
	v_mfma_f32_16x16x32_bf16 v[16:19], v[200:203], v[224:227], v[16:19]
	v_mfma_f32_16x16x32_bf16 v[4:7], v[192:195], v[232:235], v[4:7]
	v_mfma_f32_16x16x32_bf16 v[0:3], v[200:203], v[232:235], v[0:3]
	v_mfma_f32_16x16x32_bf16 v[52:55], v[196:199], v[212:215], v[52:55]
	v_mfma_f32_16x16x32_bf16 v[48:51], v[204:207], v[212:215], v[48:51]
	v_mfma_f32_16x16x32_bf16 v[36:39], v[196:199], v[220:223], v[36:39]
	v_mfma_f32_16x16x32_bf16 v[32:35], v[204:207], v[220:223], v[32:35]
	v_mfma_f32_16x16x32_bf16 v[20:23], v[196:199], v[228:231], v[20:23]
	v_mfma_f32_16x16x32_bf16 v[16:19], v[204:207], v[228:231], v[16:19]
	v_mfma_f32_16x16x32_bf16 v[4:7], v[196:199], v[236:239], v[4:7]
	v_mfma_f32_16x16x32_bf16 v[0:3], v[204:207], v[236:239], v[0:3]
	s_setprio 0
	s_barrier
	s_add_i32 s56, 0, 0x18000
	v_add_u32_e32 v140, s56, v142
	s_add_i32 s57, 0, 0x1c000
	ds_read_b128 v[156:159], v140
	ds_read_b128 v[160:163], v140 offset:1024
	ds_read_b128 v[164:167], v140 offset:2048
	ds_read_b128 v[188:191], v140 offset:3072
	v_add_u32_e32 v140, s57, v142
	ds_read_b128 v[192:195], v140
	ds_read_b128 v[196:199], v140 offset:1024
	ds_read_b128 v[200:203], v140 offset:2048
	ds_read_b128 v[204:207], v140 offset:3072
	s_add_u32 s28, s28, s6
	s_addc_u32 s29, s29, s7
	s_mov_b32 m0, s41
	v_lshl_add_u64 v[250:251], s[28:29], 0, v[128:129]
	ds_read_b128 v[208:211], v154 offset:32768
	ds_read_b128 v[212:215], v154 offset:33792
	ds_read_b128 v[216:219], v154 offset:34816
	ds_read_b128 v[220:223], v154 offset:35840
	ds_read_b128 v[224:227], v154 offset:36864
	ds_read_b128 v[228:231], v154 offset:37888
	ds_read_b128 v[232:235], v154 offset:38912
	ds_read_b128 v[236:239], v154 offset:39936
	global_load_lds_dwordx4 v[250:251], off
	v_lshl_add_u64 v[250:251], s[28:29], 0, v[130:131]
	s_mov_b32 m0, s42
	s_nop 0
	global_load_lds_dwordx4 v[250:251], off
	s_waitcnt vmcnt(8)
	s_waitcnt lgkmcnt(0)
	s_barrier
	s_setprio 1
	s_waitcnt lgkmcnt(0)
	v_mfma_f32_16x16x32_bf16 v[120:123], v[156:159], v[208:211], v[120:123]
	v_mfma_f32_16x16x32_bf16 v[124:127], v[164:167], v[208:211], v[124:127]
	v_mfma_f32_16x16x32_bf16 v[108:111], v[156:159], v[216:219], v[108:111]
	v_mfma_f32_16x16x32_bf16 v[104:107], v[164:167], v[216:219], v[104:107]
	v_mfma_f32_16x16x32_bf16 v[92:95], v[156:159], v[224:227], v[92:95]
	v_mfma_f32_16x16x32_bf16 v[88:91], v[164:167], v[224:227], v[88:91]
	v_mfma_f32_16x16x32_bf16 v[76:79], v[156:159], v[232:235], v[76:79]
	v_mfma_f32_16x16x32_bf16 v[72:75], v[164:167], v[232:235], v[72:75]
	v_mfma_f32_16x16x32_bf16 v[120:123], v[160:163], v[212:215], v[120:123]
	v_mfma_f32_16x16x32_bf16 v[124:127], v[188:191], v[212:215], v[124:127]
	v_mfma_f32_16x16x32_bf16 v[108:111], v[160:163], v[220:223], v[108:111]
	v_mfma_f32_16x16x32_bf16 v[104:107], v[188:191], v[220:223], v[104:107]
	v_mfma_f32_16x16x32_bf16 v[92:95], v[160:163], v[228:231], v[92:95]
	v_mfma_f32_16x16x32_bf16 v[88:91], v[188:191], v[228:231], v[88:91]
	v_mfma_f32_16x16x32_bf16 v[76:79], v[160:163], v[236:239], v[76:79]
	v_mfma_f32_16x16x32_bf16 v[72:75], v[188:191], v[236:239], v[72:75]
	s_setprio 0
	s_setprio 1
	v_mfma_f32_16x16x32_bf16 v[116:119], v[192:195], v[208:211], v[116:119]
	v_mfma_f32_16x16x32_bf16 v[112:115], v[200:203], v[208:211], v[112:115]
	v_mfma_f32_16x16x32_bf16 v[100:103], v[192:195], v[216:219], v[100:103]
	v_mfma_f32_16x16x32_bf16 v[96:99], v[200:203], v[216:219], v[96:99]
	v_mfma_f32_16x16x32_bf16 v[84:87], v[192:195], v[224:227], v[84:87]
	v_mfma_f32_16x16x32_bf16 v[80:83], v[200:203], v[224:227], v[80:83]
	v_mfma_f32_16x16x32_bf16 v[68:71], v[192:195], v[232:235], v[68:71]
	v_mfma_f32_16x16x32_bf16 v[64:67], v[200:203], v[232:235], v[64:67]
	v_mfma_f32_16x16x32_bf16 v[116:119], v[196:199], v[212:215], v[116:119]
	v_mfma_f32_16x16x32_bf16 v[112:115], v[204:207], v[212:215], v[112:115]
	v_mfma_f32_16x16x32_bf16 v[100:103], v[196:199], v[220:223], v[100:103]
	v_mfma_f32_16x16x32_bf16 v[96:99], v[204:207], v[220:223], v[96:99]
	v_mfma_f32_16x16x32_bf16 v[84:87], v[196:199], v[228:231], v[84:87]
	v_mfma_f32_16x16x32_bf16 v[80:83], v[204:207], v[228:231], v[80:83]
	v_mfma_f32_16x16x32_bf16 v[68:71], v[196:199], v[236:239], v[68:71]
	v_mfma_f32_16x16x32_bf16 v[64:67], v[204:207], v[236:239], v[64:67]
	s_setprio 0
	s_barrier
; #define PG8_STAGE(bufoff, gbase, voff) do { _Pragma("unroll") for (int _i = 0; _i < 2; ++_i) \
;         __builtin_amdgcn_global_load_lds((const unsigned*)((const char*)(gbase) + (voff)[_i]), (PG8_LAS unsigned*)(lds + (bufoff) + ldsw + _i * 8192), 16, 0, 0); } while (0)
; #define PG8_LDA(dst, b, h) do { _Pragma("unroll") for (int m = 0; m < 4; ++m) _Pragma("unroll") for (int k = 0; k < 2; ++k) dst[m][k] = *(const PG8_LAS bf16x8*)(lds + PG8_SA(b, h) + aoff + m * 2048 + k * 1024); } while (0)
; #define PG8_MMA(ai, bj, At, Bt) do { __builtin_amdgcn_s_setprio(1); _Pragma("unroll") for (int m = 0; m < 4; ++m) _Pragma("unroll") for (int n = 0; n < 2; ++n) _Pragma("unroll") for (int k = 0; k < 2; ++k) \
;         acc[ai][bj][m][n] = __builtin_amdgcn_mfma_f32_16x16x32_bf16(Bt[n][k], At[m][k], acc[ai][bj][m][n], 0, 0, 0); __builtin_amdgcn_s_setprio(0); } while (0)
; #define PG8_WAIT_V(n) asm volatile("s_waitcnt vmcnt(" #n ")" ::: "memory")
; #define PG8_WAIT_L(n) asm volatile("s_waitcnt lgkmcnt(" #n ")" ::: "memory")
; #define PG8_BAR __builtin_amdgcn_s_barrier()
; #define PG8_SCHED __builtin_amdgcn_sched_barrier(0)
; template <class Epi, class Sched>
; __device__ __forceinline__ void gemm_phase(int wid_s, PG8_LAS unsigned char* lds, const Gemm g, const Sched& S, const Epi& E) {
;     ...
;         for (int t = 0; t < nt; t += 2) {
;             const bool last = (t == nt - 2);
;             const char* a1 = cA + (size_t)(t + 1) * kstep;
;             const char* a2 = last ? nA : cA + (size_t)(t + 2) * kstep; const char* b2 = last ? nB : cB + (size_t)(t + 2) * kstep;
;             const char* a3 = a2 + kstep; const char* b3 = b2 + kstep;
;     ...
;             PG8_LDA(At, 1, 1); PG8_STAGE(PG8_SB(1, 0), b3, voffB); PG8_STAGE(PG8_SB(1, 1), b3 + hstepB, voffB); PG8_STAGE(PG8_SA(1, 0), a3, voffA);
;             PG8_WAIT_V(8); PG8_WAIT_L(0); PG8_BAR; PG8_MMA(1, 0, At, B0); PG8_MMA(1, 1, At, B1); PG8_BAR; PG8_SCHED;
	s_add_i32 s28, s56, s37
	v_lshl_add_u64 v[138:139], v[138:139], 0, s[96:97]
	s_mov_b32 m0, s28
	ds_read_b128 v[208:211], v154 offset:49152
	ds_read_b128 v[212:215], v154 offset:50176
	ds_read_b128 v[216:219], v154 offset:51200
	ds_read_b128 v[220:223], v154 offset:52224
	ds_read_b128 v[224:227], v154 offset:53248
	ds_read_b128 v[228:231], v154 offset:54272
	ds_read_b128 v[232:235], v154 offset:55296
	ds_read_b128 v[236:239], v154 offset:56320
	global_load_lds_dwordx4 v[138:139], off
	v_lshl_add_u64 v[138:139], v[240:241], 0, s[96:97]
	s_add_i32 m0, s28, 0x2000
	s_add_i32 s28, s57, s37
	global_load_lds_dwordx4 v[138:139], off
	v_lshl_add_u64 v[138:139], v[242:243], 0, s[96:97]
	s_mov_b32 m0, s28
	s_nop 0
	global_load_lds_dwordx4 v[138:139], off
	v_lshl_add_u64 v[138:139], v[244:245], 0, s[96:97]
	s_add_i32 m0, s28, 0x2000
	s_nop 0
	global_load_lds_dwordx4 v[138:139], off
	v_lshl_add_u64 v[138:139], v[246:247], 0, s[96:97]
	s_mov_b32 m0, s44
	s_nop 0
	global_load_lds_dwordx4 v[138:139], off
	v_lshl_add_u64 v[138:139], v[248:249], 0, s[96:97]
	s_mov_b32 m0, s45
	s_nop 0
	global_load_lds_dwordx4 v[138:139], off
	s_waitcnt vmcnt(8)
	s_waitcnt lgkmcnt(0)
	s_barrier
	s_setprio 1
	s_waitcnt lgkmcnt(0)
	v_mfma_f32_16x16x32_bf16 v[60:63], v[156:159], v[208:211], v[60:63]
	v_mfma_f32_16x16x32_bf16 v[56:59], v[164:167], v[208:211], v[56:59]
	v_mfma_f32_16x16x32_bf16 v[44:47], v[156:159], v[216:219], v[44:47]
	v_mfma_f32_16x16x32_bf16 v[40:43], v[164:167], v[216:219], v[40:43]
	v_mfma_f32_16x16x32_bf16 v[28:31], v[156:159], v[224:227], v[28:31]
	v_mfma_f32_16x16x32_bf16 v[24:27], v[164:167], v[224:227], v[24:27]
	v_mfma_f32_16x16x32_bf16 v[12:15], v[156:159], v[232:235], v[12:15]
	v_mfma_f32_16x16x32_bf16 v[8:11], v[164:167], v[232:235], v[8:11]
	v_mfma_f32_16x16x32_bf16 v[60:63], v[160:163], v[212:215], v[60:63]
	v_mfma_f32_16x16x32_bf16 v[56:59], v[188:191], v[212:215], v[56:59]
	v_mfma_f32_16x16x32_bf16 v[44:47], v[160:163], v[220:223], v[44:47]
	v_mfma_f32_16x16x32_bf16 v[40:43], v[188:191], v[220:223], v[40:43]
	v_mfma_f32_16x16x32_bf16 v[28:31], v[160:163], v[228:231], v[28:31]
	v_mfma_f32_16x16x32_bf16 v[24:27], v[188:191], v[228:231], v[24:27]
	v_mfma_f32_16x16x32_bf16 v[12:15], v[160:163], v[236:239], v[12:15]
	v_mfma_f32_16x16x32_bf16 v[8:11], v[188:191], v[236:239], v[8:11]
	s_setprio 0
	s_setprio 1
	v_mfma_f32_16x16x32_bf16 v[52:55], v[192:195], v[208:211], v[52:55]
	s_add_u32 s33, s33, 0x100
	s_addc_u32 s54, s54, 0
	v_mfma_f32_16x16x32_bf16 v[48:51], v[200:203], v[208:211], v[48:51]
	s_add_u32 s26, s26, 0x100
	s_addc_u32 s27, s27, 0
	v_mfma_f32_16x16x32_bf16 v[36:39], v[192:195], v[216:219], v[36:39]
	s_cmp_ge_i32 s55, s46
	s_mov_b32 s28, s55
	s_cbranch_scc1 .Lmy_kx9
	v_mfma_f32_16x16x32_bf16 v[32:35], v[200:203], v[216:219], v[32:35]
	s_add_i32 s55, s28, 2
	v_mfma_f32_16x16x32_bf16 v[20:23], v[192:195], v[224:227], v[20:23]
	s_add_u32 s56, s26, 0x80
	v_mfma_f32_16x16x32_bf16 v[16:19], v[200:203], v[224:227], v[16:19]
	s_addc_u32 s29, s27, 0
	v_mfma_f32_16x16x32_bf16 v[4:7], v[192:195], v[232:235], v[4:7]
	s_add_i32 s92, 0, 0x10000
	v_mfma_f32_16x16x32_bf16 v[0:3], v[200:203], v[232:235], v[0:3]
	s_cmp_eq_u32 s47, s28
	v_mfma_f32_16x16x32_bf16 v[52:55], v[196:199], v[212:215], v[52:55]
	s_cselect_b32 s29, s5, s29
	v_mfma_f32_16x16x32_bf16 v[48:51], v[204:207], v[212:215], v[48:51]
	s_cselect_b32 s28, s4, s56
	v_mfma_f32_16x16x32_bf16 v[36:39], v[196:199], v[220:223], v[36:39]
	v_add_u32_e32 v138, s92, v142
	v_mfma_f32_16x16x32_bf16 v[32:35], v[204:207], v[220:223], v[32:35]
	s_cselect_b32 s57, s25, s54
	v_mfma_f32_16x16x32_bf16 v[20:23], v[196:199], v[228:231], v[20:23]
	s_cselect_b32 s56, s24, s33
	v_mfma_f32_16x16x32_bf16 v[16:19], v[204:207], v[228:231], v[16:19]
	s_add_i32 s94, 0, 0x14000
	v_mfma_f32_16x16x32_bf16 v[4:7], v[196:199], v[236:239], v[4:7]
	v_mfma_f32_16x16x32_bf16 v[0:3], v[204:207], v[236:239], v[0:3]
	s_setprio 0
	s_barrier
	s_branch .Lmy_kh9
.Lmy_kx9:
	v_mfma_f32_16x16x32_bf16 v[32:35], v[200:203], v[216:219], v[32:35]
	v_mfma_f32_16x16x32_bf16 v[20:23], v[192:195], v[224:227], v[20:23]
	v_mfma_f32_16x16x32_bf16 v[16:19], v[200:203], v[224:227], v[16:19]
	v_mfma_f32_16x16x32_bf16 v[4:7], v[192:195], v[232:235], v[4:7]
	v_mfma_f32_16x16x32_bf16 v[0:3], v[200:203], v[232:235], v[0:3]
	v_mfma_f32_16x16x32_bf16 v[52:55], v[196:199], v[212:215], v[52:55]
	v_mfma_f32_16x16x32_bf16 v[48:51], v[204:207], v[212:215], v[48:51]
	v_mfma_f32_16x16x32_bf16 v[36:39], v[196:199], v[220:223], v[36:39]
	v_mfma_f32_16x16x32_bf16 v[32:35], v[204:207], v[220:223], v[32:35]
	v_mfma_f32_16x16x32_bf16 v[20:23], v[196:199], v[228:231], v[20:23]
	v_mfma_f32_16x16x32_bf16 v[16:19], v[204:207], v[228:231], v[16:19]
	v_mfma_f32_16x16x32_bf16 v[4:7], v[196:199], v[236:239], v[4:7]
	v_mfma_f32_16x16x32_bf16 v[0:3], v[204:207], v[236:239], v[0:3]
	s_setprio 0
	s_barrier
	v_readlane_b32 s54, v254, 52
	v_readlane_b32 s55, v254, 53
	v_readlane_b32 s92, v254, 54
	v_readlane_b32 s94, v254, 55

; #define PG8_STAGE(bufoff, gbase, voff) do { _Pragma("unroll") for (int _i = 0; _i < 2; ++_i) \
;         __builtin_amdgcn_global_load_lds((const unsigned*)((const char*)(gbase) + (voff)[_i]), (PG8_LAS unsigned*)(lds + (bufoff) + ldsw + _i * 8192), 16, 0, 0); } while (0)
; #define PG8_LDA(dst, b, h) do { _Pragma("unroll") for (int m = 0; m < 4; ++m) _Pragma("unroll") for (int k = 0; k < 2; ++k) dst[m][k] = *(const PG8_LAS bf16x8*)(lds + PG8_SA(b, h) + aoff + m * 2048 + k * 1024); } while (0)
; #define PG8_LDB(dst, b, h) do { _Pragma("unroll") for (int n = 0; n < 2; ++n) _Pragma("unroll") for (int k = 0; k < 2; ++k) dst[n][k] = *(const PG8_LAS bf16x8*)(lds + PG8_SB(b, h) + boff + n * 2048 + k * 1024); } while (0)
; #define PG8_MMA(ai, bj, At, Bt) do { __builtin_amdgcn_s_setprio(1); _Pragma("unroll") for (int m = 0; m < 4; ++m) _Pragma("unroll") for (int n = 0; n < 2; ++n) _Pragma("unroll") for (int k = 0; k < 2; ++k) \
;         acc[ai][bj][m][n] = __builtin_amdgcn_mfma_f32_16x16x32_bf16(Bt[n][k], At[m][k], acc[ai][bj][m][n], 0, 0, 0); __builtin_amdgcn_s_setprio(0); } while (0)
; #define PG8_WAIT_V(n) asm volatile("s_waitcnt vmcnt(" #n ")" ::: "memory")
; #define PG8_WAIT_L(n) asm volatile("s_waitcnt lgkmcnt(" #n ")" ::: "memory")
; #define PG8_BAR __builtin_amdgcn_s_barrier()
; #define PG8_SCHED __builtin_amdgcn_sched_barrier(0)
; template <class Epi, class Sched>
; __device__ __forceinline__ void gemm_phase(int wid_s, PG8_LAS unsigned char* lds, const Gemm g, const Sched& S, const Epi& E) {
;     ...
;             PG8_LDB(B0, 0, 0); PG8_LDB(B1, 0, 1); PG8_SCHED; PG8_LDA(At, 0, 0); PG8_STAGE(PG8_SA(1, 1), a1 + hstepA, voffA);
;             PG8_WAIT_V(8); PG8_WAIT_L(0); PG8_BAR; PG8_MMA(0, 0, At, B0); PG8_MMA(0, 1, At, B1); PG8_BAR; PG8_SCHED;
;             PG8_LDA(At, 0, 1); PG8_STAGE(PG8_SB(0, 0), b2, voffB); PG8_STAGE(PG8_SB(0, 1), b2 + hstepB, voffB); PG8_STAGE(PG8_SA(0, 0), a2, voffA);
.Lmy_kh10:
	ds_read_b128 v[138:141], v142
	ds_read_b128 v[160:163], v142 offset:1024
	ds_read_b128 v[164:167], v142 offset:2048
	ds_read_b128 v[188:191], v142 offset:3072
	v_add_u32_e32 v142, s45, v157
	ds_read_b128 v[192:195], v142
	ds_read_b128 v[196:199], v142 offset:1024
	ds_read_b128 v[200:203], v142 offset:2048
	ds_read_b128 v[204:207], v142 offset:3072
	v_lshl_add_u64 v[142:143], s[4:5], 0, v[136:137]
	s_add_i32 m0, s52, 0xc000
	ds_read_b128 v[208:211], v159
	ds_read_b128 v[212:215], v159 offset:1024
	ds_read_b128 v[216:219], v159 offset:2048
	ds_read_b128 v[220:223], v159 offset:3072
	ds_read_b128 v[224:227], v159 offset:4096
	ds_read_b128 v[228:231], v159 offset:5120
	ds_read_b128 v[232:235], v159 offset:6144
	ds_read_b128 v[236:239], v159 offset:7168
	global_load_lds_dwordx4 v[142:143], off
	v_lshl_add_u64 v[142:143], s[4:5], 0, v[134:135]
	s_add_i32 m0, s52, 0xe000
	s_nop 0
	global_load_lds_dwordx4 v[142:143], off
	s_waitcnt vmcnt(8)
	s_waitcnt lgkmcnt(0)
	s_barrier
	s_setprio 1
	s_waitcnt lgkmcnt(0)
	v_mfma_f32_16x16x32_bf16 v[124:127], v[138:141], v[208:211], v[124:127]
	v_mfma_f32_16x16x32_bf16 v[120:123], v[164:167], v[208:211], v[120:123]
	v_mfma_f32_16x16x32_bf16 v[108:111], v[138:141], v[216:219], v[108:111]
	v_mfma_f32_16x16x32_bf16 v[104:107], v[164:167], v[216:219], v[104:107]
	v_mfma_f32_16x16x32_bf16 v[92:95], v[138:141], v[224:227], v[92:95]
	v_mfma_f32_16x16x32_bf16 v[88:91], v[164:167], v[224:227], v[88:91]
	v_mfma_f32_16x16x32_bf16 v[76:79], v[138:141], v[232:235], v[76:79]
	v_mfma_f32_16x16x32_bf16 v[72:75], v[164:167], v[232:235], v[72:75]
	v_mfma_f32_16x16x32_bf16 v[124:127], v[160:163], v[212:215], v[124:127]
	v_mfma_f32_16x16x32_bf16 v[120:123], v[188:191], v[212:215], v[120:123]
	v_mfma_f32_16x16x32_bf16 v[108:111], v[160:163], v[220:223], v[108:111]
	v_mfma_f32_16x16x32_bf16 v[104:107], v[188:191], v[220:223], v[104:107]
	v_mfma_f32_16x16x32_bf16 v[92:95], v[160:163], v[228:231], v[92:95]
	v_mfma_f32_16x16x32_bf16 v[88:91], v[188:191], v[228:231], v[88:91]
	v_mfma_f32_16x16x32_bf16 v[76:79], v[160:163], v[236:239], v[76:79]
	v_mfma_f32_16x16x32_bf16 v[72:75], v[188:191], v[236:239], v[72:75]
	s_setprio 0
	s_setprio 1
	v_mfma_f32_16x16x32_bf16 v[116:119], v[192:195], v[208:211], v[116:119]
	v_mfma_f32_16x16x32_bf16 v[112:115], v[200:203], v[208:211], v[112:115]
	v_mfma_f32_16x16x32_bf16 v[100:103], v[192:195], v[216:219], v[100:103]
	v_mfma_f32_16x16x32_bf16 v[96:99], v[200:203], v[216:219], v[96:99]
	v_mfma_f32_16x16x32_bf16 v[84:87], v[192:195], v[224:227], v[84:87]
	v_mfma_f32_16x16x32_bf16 v[80:83], v[200:203], v[224:227], v[80:83]
	v_mfma_f32_16x16x32_bf16 v[68:71], v[192:195], v[232:235], v[68:71]
	v_mfma_f32_16x16x32_bf16 v[64:67], v[200:203], v[232:235], v[64:67]
	v_mfma_f32_16x16x32_bf16 v[116:119], v[196:199], v[212:215], v[116:119]
	v_mfma_f32_16x16x32_bf16 v[112:115], v[204:207], v[212:215], v[112:115]
	v_mfma_f32_16x16x32_bf16 v[100:103], v[196:199], v[220:223], v[100:103]
	v_mfma_f32_16x16x32_bf16 v[96:99], v[204:207], v[220:223], v[96:99]
	v_mfma_f32_16x16x32_bf16 v[84:87], v[196:199], v[228:231], v[84:87]
	v_mfma_f32_16x16x32_bf16 v[80:83], v[204:207], v[228:231], v[80:83]
	v_mfma_f32_16x16x32_bf16 v[68:71], v[196:199], v[236:239], v[68:71]
	v_mfma_f32_16x16x32_bf16 v[64:67], v[204:207], v[236:239], v[64:67]
	s_setprio 0
	s_barrier
	s_add_i32 s18, s18, s47
	v_lshl_add_u64 v[142:143], vcc, 0, v[144:145]
	s_mov_b32 m0, s18
	ds_read_b128 v[208:211], v159 offset:16384
	ds_read_b128 v[212:215], v159 offset:17408
	ds_read_b128 v[216:219], v159 offset:18432
	ds_read_b128 v[220:223], v159 offset:19456
	ds_read_b128 v[224:227], v159 offset:20480
	ds_read_b128 v[228:231], v159 offset:21504
	ds_read_b128 v[232:235], v159 offset:22528
	ds_read_b128 v[236:239], v159 offset:23552
	global_load_lds_dwordx4 v[142:143], off
	s_add_i32 m0, s18, 0x2000
	v_lshl_add_u64 v[240:241], vcc, 0, v[132:133]
	s_add_u32 vcc_lo, vcc_lo, s12
	s_addc_u32 vcc_hi, vcc_hi, s13
	s_add_i32 s18, s45, s47
	global_load_lds_dwordx4 v[240:241], off
	v_lshl_add_u64 v[242:243], vcc, 0, v[144:145]
	s_mov_b32 m0, s18
	v_lshl_add_u64 v[244:245], vcc, 0, v[132:133]
	global_load_lds_dwordx4 v[242:243], off
	s_add_i32 m0, s18, 0x2000
	v_lshl_add_u64 v[246:247], s[34:35], 0, v[128:129]
	global_load_lds_dwordx4 v[244:245], off
	s_mov_b32 m0, s52
	v_lshl_add_u64 v[248:249], s[34:35], 0, v[130:131]
	global_load_lds_dwordx4 v[246:247], off
	s_mov_b32 m0, s53
	s_nop 0
	global_load_lds_dwordx4 v[248:249], off
	s_waitcnt vmcnt(8)
	s_waitcnt lgkmcnt(0)
	s_barrier
; #define PG8_STAGE(bufoff, gbase, voff) do { _Pragma("unroll") for (int _i = 0; _i < 2; ++_i) \
;         __builtin_amdgcn_global_load_lds((const unsigned*)((const char*)(gbase) + (voff)[_i]), (PG8_LAS unsigned*)(lds + (bufoff) + ldsw + _i * 8192), 16, 0, 0); } while (0)
; #define PG8_LDA(dst, b, h) do { _Pragma("unroll") for (int m = 0; m < 4; ++m) _Pragma("unroll") for (int k = 0; k < 2; ++k) dst[m][k] = *(const PG8_LAS bf16x8*)(lds + PG8_SA(b, h) + aoff + m * 2048 + k * 1024); } while (0)
; #define PG8_LDB(dst, b, h) do { _Pragma("unroll") for (int n = 0; n < 2; ++n) _Pragma("unroll") for (int k = 0; k < 2; ++k) dst[n][k] = *(const PG8_LAS bf16x8*)(lds + PG8_SB(b, h) + boff + n * 2048 + k * 1024); } while (0)
; #define PG8_MMA(ai, bj, At, Bt) do { __builtin_amdgcn_s_setprio(1); _Pragma("unroll") for (int m = 0; m < 4; ++m) _Pragma("unroll") for (int n = 0; n < 2; ++n) _Pragma("unroll") for (int k = 0; k < 2; ++k) \
;         acc[ai][bj][m][n] = __builtin_amdgcn_mfma_f32_16x16x32_bf16(Bt[n][k], At[m][k], acc[ai][bj][m][n], 0, 0, 0); __builtin_amdgcn_s_setprio(0); } while (0)
; #define PG8_WAIT_V(n) asm volatile("s_waitcnt vmcnt(" #n ")" ::: "memory")
; #define PG8_WAIT_L(n) asm volatile("s_waitcnt lgkmcnt(" #n ")" ::: "memory")
; #define PG8_BAR __builtin_amdgcn_s_barrier()
; #define PG8_SCHED __builtin_amdgcn_sched_barrier(0)
; template <class Epi, class Sched>
; __device__ __forceinline__ void gemm_phase(int wid_s, PG8_LAS unsigned char* lds, const Gemm g, const Sched& S, const Epi& E) {
;     ...
;             PG8_WAIT_V(8); PG8_WAIT_L(0); PG8_BAR; PG8_MMA(1, 0, At, B0); PG8_MMA(1, 1, At, B1); PG8_BAR; PG8_SCHED;
;             PG8_LDB(B0, 1, 0); PG8_LDB(B1, 1, 1); PG8_SCHED; PG8_LDA(At, 1, 0); PG8_STAGE(PG8_SA(0, 1), a2 + hstepA, voffA);
;             PG8_WAIT_V(8); PG8_WAIT_L(0); PG8_BAR; PG8_MMA(0, 0, At, B0); PG8_MMA(0, 1, At, B1); PG8_BAR; PG8_SCHED;
	s_setprio 1
	s_waitcnt lgkmcnt(0)
	v_mfma_f32_16x16x32_bf16 v[60:63], v[138:141], v[208:211], v[60:63]
	v_mfma_f32_16x16x32_bf16 v[56:59], v[164:167], v[208:211], v[56:59]
	v_mfma_f32_16x16x32_bf16 v[44:47], v[138:141], v[216:219], v[44:47]
	v_mfma_f32_16x16x32_bf16 v[40:43], v[164:167], v[216:219], v[40:43]
	v_mfma_f32_16x16x32_bf16 v[28:31], v[138:141], v[224:227], v[28:31]
	v_mfma_f32_16x16x32_bf16 v[24:27], v[164:167], v[224:227], v[24:27]
	v_mfma_f32_16x16x32_bf16 v[12:15], v[138:141], v[232:235], v[12:15]
	v_mfma_f32_16x16x32_bf16 v[8:11], v[164:167], v[232:235], v[8:11]
	v_mfma_f32_16x16x32_bf16 v[60:63], v[160:163], v[212:215], v[60:63]
	v_mfma_f32_16x16x32_bf16 v[56:59], v[188:191], v[212:215], v[56:59]
	v_mfma_f32_16x16x32_bf16 v[44:47], v[160:163], v[220:223], v[44:47]
	v_mfma_f32_16x16x32_bf16 v[40:43], v[188:191], v[220:223], v[40:43]
	v_mfma_f32_16x16x32_bf16 v[28:31], v[160:163], v[228:231], v[28:31]
	v_mfma_f32_16x16x32_bf16 v[24:27], v[188:191], v[228:231], v[24:27]
	v_mfma_f32_16x16x32_bf16 v[12:15], v[160:163], v[236:239], v[12:15]
	v_mfma_f32_16x16x32_bf16 v[8:11], v[188:191], v[236:239], v[8:11]
	s_setprio 0
	s_setprio 1
	v_mfma_f32_16x16x32_bf16 v[52:55], v[192:195], v[208:211], v[52:55]
	v_mfma_f32_16x16x32_bf16 v[48:51], v[200:203], v[208:211], v[48:51]
	v_mfma_f32_16x16x32_bf16 v[36:39], v[192:195], v[216:219], v[36:39]
	v_mfma_f32_16x16x32_bf16 v[32:35], v[200:203], v[216:219], v[32:35]
	v_mfma_f32_16x16x32_bf16 v[20:23], v[192:195], v[224:227], v[20:23]
	v_mfma_f32_16x16x32_bf16 v[16:19], v[200:203], v[224:227], v[16:19]
	v_mfma_f32_16x16x32_bf16 v[4:7], v[192:195], v[232:235], v[4:7]
	v_mfma_f32_16x16x32_bf16 v[0:3], v[200:203], v[232:235], v[0:3]
	v_mfma_f32_16x16x32_bf16 v[52:55], v[196:199], v[212:215], v[52:55]
	v_mfma_f32_16x16x32_bf16 v[48:51], v[204:207], v[212:215], v[48:51]
	v_mfma_f32_16x16x32_bf16 v[36:39], v[196:199], v[220:223], v[36:39]
	v_mfma_f32_16x16x32_bf16 v[32:35], v[204:207], v[220:223], v[32:35]
	v_mfma_f32_16x16x32_bf16 v[20:23], v[196:199], v[228:231], v[20:23]
	v_mfma_f32_16x16x32_bf16 v[16:19], v[204:207], v[228:231], v[16:19]
	v_mfma_f32_16x16x32_bf16 v[4:7], v[196:199], v[236:239], v[4:7]
	v_mfma_f32_16x16x32_bf16 v[0:3], v[204:207], v[236:239], v[0:3]
	s_setprio 0
	s_barrier
	s_add_i32 s18, 0, 0x18000
	v_add_u32_e32 v185, s18, v157
	s_add_i32 s45, 0, 0x1c000
	ds_read_b128 v[138:141], v185
	ds_read_b128 v[160:163], v185 offset:1024
	ds_read_b128 v[164:167], v185 offset:2048
	ds_read_b128 v[188:191], v185 offset:3072
	v_add_u32_e32 v185, s45, v157
	ds_read_b128 v[192:195], v185
	ds_read_b128 v[196:199], v185 offset:1024
	ds_read_b128 v[200:203], v185 offset:2048
	ds_read_b128 v[204:207], v185 offset:3072
	s_add_u32 s34, s34, s10
	s_addc_u32 s35, s35, s11
	s_mov_b32 m0, s54
	v_lshl_add_u64 v[250:251], s[34:35], 0, v[128:129]
	ds_read_b128 v[208:211], v159 offset:32768
	ds_read_b128 v[212:215], v159 offset:33792
	ds_read_b128 v[216:219], v159 offset:34816
	ds_read_b128 v[220:223], v159 offset:35840
	ds_read_b128 v[224:227], v159 offset:36864
	ds_read_b128 v[228:231], v159 offset:37888
	ds_read_b128 v[232:235], v159 offset:38912
	ds_read_b128 v[236:239], v159 offset:39936
	global_load_lds_dwordx4 v[250:251], off
	v_lshl_add_u64 v[250:251], s[34:35], 0, v[130:131]
	s_mov_b32 m0, s55
	s_nop 0
	global_load_lds_dwordx4 v[250:251], off
	s_waitcnt vmcnt(8)
	s_waitcnt lgkmcnt(0)
	s_barrier
	s_setprio 1
	s_waitcnt lgkmcnt(0)
	v_mfma_f32_16x16x32_bf16 v[124:127], v[138:141], v[208:211], v[124:127]
	v_mfma_f32_16x16x32_bf16 v[120:123], v[164:167], v[208:211], v[120:123]
	v_mfma_f32_16x16x32_bf16 v[108:111], v[138:141], v[216:219], v[108:111]
	v_mfma_f32_16x16x32_bf16 v[104:107], v[164:167], v[216:219], v[104:107]
	v_mfma_f32_16x16x32_bf16 v[92:95], v[138:141], v[224:227], v[92:95]
	v_mfma_f32_16x16x32_bf16 v[88:91], v[164:167], v[224:227], v[88:91]
	v_mfma_f32_16x16x32_bf16 v[76:79], v[138:141], v[232:235], v[76:79]
	v_mfma_f32_16x16x32_bf16 v[72:75], v[164:167], v[232:235], v[72:75]
	v_mfma_f32_16x16x32_bf16 v[124:127], v[160:163], v[212:215], v[124:127]
	v_mfma_f32_16x16x32_bf16 v[120:123], v[188:191], v[212:215], v[120:123]
	v_mfma_f32_16x16x32_bf16 v[108:111], v[160:163], v[220:223], v[108:111]
	v_mfma_f32_16x16x32_bf16 v[104:107], v[188:191], v[220:223], v[104:107]
	v_mfma_f32_16x16x32_bf16 v[92:95], v[160:163], v[228:231], v[92:95]
	v_mfma_f32_16x16x32_bf16 v[88:91], v[188:191], v[228:231], v[88:91]
	v_mfma_f32_16x16x32_bf16 v[76:79], v[160:163], v[236:239], v[76:79]
	v_mfma_f32_16x16x32_bf16 v[72:75], v[188:191], v[236:239], v[72:75]
	s_setprio 0
	s_setprio 1
	v_mfma_f32_16x16x32_bf16 v[116:119], v[192:195], v[208:211], v[116:119]
	v_mfma_f32_16x16x32_bf16 v[112:115], v[200:203], v[208:211], v[112:115]
	v_mfma_f32_16x16x32_bf16 v[100:103], v[192:195], v[216:219], v[100:103]
	v_mfma_f32_16x16x32_bf16 v[96:99], v[200:203], v[216:219], v[96:99]
	v_mfma_f32_16x16x32_bf16 v[84:87], v[192:195], v[224:227], v[84:87]
	v_mfma_f32_16x16x32_bf16 v[80:83], v[200:203], v[224:227], v[80:83]
	v_mfma_f32_16x16x32_bf16 v[68:71], v[192:195], v[232:235], v[68:71]
	v_mfma_f32_16x16x32_bf16 v[64:67], v[200:203], v[232:235], v[64:67]
	v_mfma_f32_16x16x32_bf16 v[116:119], v[196:199], v[212:215], v[116:119]
	v_mfma_f32_16x16x32_bf16 v[112:115], v[204:207], v[212:215], v[112:115]
	v_mfma_f32_16x16x32_bf16 v[100:103], v[196:199], v[220:223], v[100:103]
	v_mfma_f32_16x16x32_bf16 v[96:99], v[204:207], v[220:223], v[96:99]
	v_mfma_f32_16x16x32_bf16 v[84:87], v[196:199], v[228:231], v[84:87]
	v_mfma_f32_16x16x32_bf16 v[80:83], v[204:207], v[228:231], v[80:83]
	v_mfma_f32_16x16x32_bf16 v[68:71], v[196:199], v[236:239], v[68:71]
	v_mfma_f32_16x16x32_bf16 v[64:67], v[204:207], v[236:239], v[64:67]
	s_setprio 0
	s_barrier
; #define PG8_STAGE(bufoff, gbase, voff) do { _Pragma("unroll") for (int _i = 0; _i < 2; ++_i) \
;         __builtin_amdgcn_global_load_lds((const unsigned*)((const char*)(gbase) + (voff)[_i]), (PG8_LAS unsigned*)(lds + (bufoff) + ldsw + _i * 8192), 16, 0, 0); } while (0)
; #define PG8_LDA(dst, b, h) do { _Pragma("unroll") for (int m = 0; m < 4; ++m) _Pragma("unroll") for (int k = 0; k < 2; ++k) dst[m][k] = *(const PG8_LAS bf16x8*)(lds + PG8_SA(b, h) + aoff + m * 2048 + k * 1024); } while (0)
; #define PG8_MMA(ai, bj, At, Bt) do { __builtin_amdgcn_s_setprio(1); _Pragma("unroll") for (int m = 0; m < 4; ++m) _Pragma("unroll") for (int n = 0; n < 2; ++n) _Pragma("unroll") for (int k = 0; k < 2; ++k) \
;         acc[ai][bj][m][n] = __builtin_amdgcn_mfma_f32_16x16x32_bf16(Bt[n][k], At[m][k], acc[ai][bj][m][n], 0, 0, 0); __builtin_amdgcn_s_setprio(0); } while (0)
; #define PG8_WAIT_V(n) asm volatile("s_waitcnt vmcnt(" #n ")" ::: "memory")
; #define PG8_WAIT_L(n) asm volatile("s_waitcnt lgkmcnt(" #n ")" ::: "memory")
; #define PG8_BAR __builtin_amdgcn_s_barrier()
; #define PG8_SCHED __builtin_amdgcn_sched_barrier(0)
; template <class Epi, class Sched>
; __device__ __forceinline__ void gemm_phase(int wid_s, PG8_LAS unsigned char* lds, const Gemm g, const Sched& S, const Epi& E) {
;     ...
;         for (int t = 0; t < nt; t += 2) {
;             const bool last = (t == nt - 2);
;             const char* a1 = cA + (size_t)(t + 1) * kstep;
;             const char* a2 = last ? nA : cA + (size_t)(t + 2) * kstep; const char* b2 = last ? nB : cB + (size_t)(t + 2) * kstep;
;             const char* a3 = a2 + kstep; const char* b3 = b2 + kstep;
;     ...
;             PG8_LDA(At, 1, 1); PG8_STAGE(PG8_SB(1, 0), b3, voffB); PG8_STAGE(PG8_SB(1, 1), b3 + hstepB, voffB); PG8_STAGE(PG8_SA(1, 0), a3, voffA);
;             PG8_WAIT_V(8); PG8_WAIT_L(0); PG8_BAR; PG8_MMA(1, 0, At, B0); PG8_MMA(1, 1, At, B1); PG8_BAR; PG8_SCHED;
	s_add_i32 s18, s18, s47
	v_lshl_add_u64 v[142:143], v[142:143], 0, s[96:97]
	s_mov_b32 m0, s18
	ds_read_b128 v[208:211], v159 offset:49152
	ds_read_b128 v[212:215], v159 offset:50176
	ds_read_b128 v[216:219], v159 offset:51200
	ds_read_b128 v[220:223], v159 offset:52224
	ds_read_b128 v[224:227], v159 offset:53248
	ds_read_b128 v[228:231], v159 offset:54272
	ds_read_b128 v[232:235], v159 offset:55296
	ds_read_b128 v[236:239], v159 offset:56320
	global_load_lds_dwordx4 v[142:143], off
	v_lshl_add_u64 v[142:143], v[240:241], 0, s[96:97]
	s_add_i32 m0, s18, 0x2000
	s_add_i32 s18, s45, s47
	global_load_lds_dwordx4 v[142:143], off
	v_lshl_add_u64 v[142:143], v[242:243], 0, s[96:97]
	s_mov_b32 m0, s18
	s_nop 0
	global_load_lds_dwordx4 v[142:143], off
	v_lshl_add_u64 v[142:143], v[244:245], 0, s[96:97]
	s_add_i32 m0, s18, 0x2000
	s_nop 0
	global_load_lds_dwordx4 v[142:143], off
	v_lshl_add_u64 v[142:143], v[246:247], 0, s[96:97]
	s_mov_b32 m0, s56
	s_nop 0
	global_load_lds_dwordx4 v[142:143], off
	v_lshl_add_u64 v[142:143], v[248:249], 0, s[96:97]
	s_mov_b32 m0, s57
	s_nop 0
	global_load_lds_dwordx4 v[142:143], off
	s_waitcnt vmcnt(8)
	s_waitcnt lgkmcnt(0)
	s_barrier
	s_setprio 1
	s_waitcnt lgkmcnt(0)
	v_mfma_f32_16x16x32_bf16 v[60:63], v[138:141], v[208:211], v[60:63]
	v_mfma_f32_16x16x32_bf16 v[56:59], v[164:167], v[208:211], v[56:59]
	v_mfma_f32_16x16x32_bf16 v[44:47], v[138:141], v[216:219], v[44:47]
	v_mfma_f32_16x16x32_bf16 v[40:43], v[164:167], v[216:219], v[40:43]
	v_mfma_f32_16x16x32_bf16 v[28:31], v[138:141], v[224:227], v[28:31]
	v_mfma_f32_16x16x32_bf16 v[24:27], v[164:167], v[224:227], v[24:27]
	v_mfma_f32_16x16x32_bf16 v[12:15], v[138:141], v[232:235], v[12:15]
	v_mfma_f32_16x16x32_bf16 v[8:11], v[164:167], v[232:235], v[8:11]
	v_mfma_f32_16x16x32_bf16 v[60:63], v[160:163], v[212:215], v[60:63]
	v_mfma_f32_16x16x32_bf16 v[56:59], v[188:191], v[212:215], v[56:59]
	v_mfma_f32_16x16x32_bf16 v[44:47], v[160:163], v[220:223], v[44:47]
	v_mfma_f32_16x16x32_bf16 v[40:43], v[188:191], v[220:223], v[40:43]
	v_mfma_f32_16x16x32_bf16 v[28:31], v[160:163], v[228:231], v[28:31]
	v_mfma_f32_16x16x32_bf16 v[24:27], v[188:191], v[228:231], v[24:27]
	v_mfma_f32_16x16x32_bf16 v[12:15], v[160:163], v[236:239], v[12:15]
	v_mfma_f32_16x16x32_bf16 v[8:11], v[188:191], v[236:239], v[8:11]
	s_setprio 0
	s_setprio 1
	v_mfma_f32_16x16x32_bf16 v[52:55], v[192:195], v[208:211], v[52:55]
	s_add_u32 s33, s33, 0x100
	s_addc_u32 s51, s51, 0
	v_mfma_f32_16x16x32_bf16 v[48:51], v[200:203], v[208:211], v[48:51]
	s_add_u32 s4, s4, 0x100
	s_addc_u32 s5, s5, 0
	v_mfma_f32_16x16x32_bf16 v[36:39], v[192:195], v[216:219], v[36:39]
	s_cmp_ge_i32 s44, s94
	s_mov_b32 s34, s44
	s_cbranch_scc1 .Lmy_kx10
	v_mfma_f32_16x16x32_bf16 v[32:35], v[200:203], v[216:219], v[32:35]
	s_add_i32 s44, s34, 2
	v_mfma_f32_16x16x32_bf16 v[20:23], v[192:195], v[224:227], v[20:23]
	s_add_u32 s45, s4, 0x80
	v_mfma_f32_16x16x32_bf16 v[16:19], v[200:203], v[224:227], v[16:19]
	s_addc_u32 s35, s5, 0
	v_mfma_f32_16x16x32_bf16 v[4:7], v[192:195], v[232:235], v[4:7]
	s_add_i32 s18, 0, 0x10000
	v_mfma_f32_16x16x32_bf16 v[0:3], v[200:203], v[232:235], v[0:3]
	s_cmp_eq_u32 s95, s34
	v_mfma_f32_16x16x32_bf16 v[52:55], v[196:199], v[212:215], v[52:55]
	s_cselect_b32 s35, s29, s35
	v_mfma_f32_16x16x32_bf16 v[48:51], v[204:207], v[212:215], v[48:51]
	s_cselect_b32 s34, s28, s45
	v_mfma_f32_16x16x32_bf16 v[36:39], v[196:199], v[220:223], v[36:39]
	v_add_u32_e32 v142, s18, v157
	v_mfma_f32_16x16x32_bf16 v[32:35], v[204:207], v[220:223], v[32:35]
	s_cselect_b32 vcc_hi, s31, s51
	v_mfma_f32_16x16x32_bf16 v[20:23], v[196:199], v[228:231], v[20:23]
	s_cselect_b32 vcc_lo, s30, s33
	v_mfma_f32_16x16x32_bf16 v[16:19], v[204:207], v[228:231], v[16:19]
	s_add_i32 s45, 0, 0x14000
	v_mfma_f32_16x16x32_bf16 v[4:7], v[196:199], v[236:239], v[4:7]
	v_mfma_f32_16x16x32_bf16 v[0:3], v[204:207], v[236:239], v[0:3]
	s_setprio 0
	s_barrier
	s_branch .Lmy_kh10
.Lmy_kx10:
	v_mfma_f32_16x16x32_bf16 v[32:35], v[200:203], v[216:219], v[32:35]
	v_mfma_f32_16x16x32_bf16 v[20:23], v[192:195], v[224:227], v[20:23]
	v_mfma_f32_16x16x32_bf16 v[16:19], v[200:203], v[224:227], v[16:19]
	v_mfma_f32_16x16x32_bf16 v[4:7], v[192:195], v[232:235], v[4:7]
	v_mfma_f32_16x16x32_bf16 v[0:3], v[200:203], v[232:235], v[0:3]
	v_mfma_f32_16x16x32_bf16 v[52:55], v[196:199], v[212:215], v[52:55]
	v_mfma_f32_16x16x32_bf16 v[48:51], v[204:207], v[212:215], v[48:51]
	v_mfma_f32_16x16x32_bf16 v[36:39], v[196:199], v[220:223], v[36:39]
	v_mfma_f32_16x16x32_bf16 v[32:35], v[204:207], v[220:223], v[32:35]
	v_mfma_f32_16x16x32_bf16 v[20:23], v[196:199], v[228:231], v[20:23]
	v_mfma_f32_16x16x32_bf16 v[16:19], v[204:207], v[228:231], v[16:19]
	v_mfma_f32_16x16x32_bf16 v[4:7], v[196:199], v[236:239], v[4:7]
	v_mfma_f32_16x16x32_bf16 v[0:3], v[204:207], v[236:239], v[0:3]
	s_setprio 0
	s_barrier
	s_movk_i32 s33, 0x300

; #define PG8_STAGE(bufoff, gbase, voff) do { _Pragma("unroll") for (int _i = 0; _i < 2; ++_i) \
;         __builtin_amdgcn_global_load_lds((const unsigned*)((const char*)(gbase) + (voff)[_i]), (PG8_LAS unsigned*)(lds + (bufoff) + ldsw + _i * 8192), 16, 0, 0); } while (0)
; #define PG8_LDA(dst, b, h) do { _Pragma("unroll") for (int m = 0; m < 4; ++m) _Pragma("unroll") for (int k = 0; k < 2; ++k) dst[m][k] = *(const PG8_LAS bf16x8*)(lds + PG8_SA(b, h) + aoff + m * 2048 + k * 1024); } while (0)
; #define PG8_LDB(dst, b, h) do { _Pragma("unroll") for (int n = 0; n < 2; ++n) _Pragma("unroll") for (int k = 0; k < 2; ++k) dst[n][k] = *(const PG8_LAS bf16x8*)(lds + PG8_SB(b, h) + boff + n * 2048 + k * 1024); } while (0)
; #define PG8_MMA(ai, bj, At, Bt) do { __builtin_amdgcn_s_setprio(1); _Pragma("unroll") for (int m = 0; m < 4; ++m) _Pragma("unroll") for (int n = 0; n < 2; ++n) _Pragma("unroll") for (int k = 0; k < 2; ++k) \
;         acc[ai][bj][m][n] = __builtin_amdgcn_mfma_f32_16x16x32_bf16(Bt[n][k], At[m][k], acc[ai][bj][m][n], 0, 0, 0); __builtin_amdgcn_s_setprio(0); } while (0)
; #define PG8_WAIT_V(n) asm volatile("s_waitcnt vmcnt(" #n ")" ::: "memory")
; #define PG8_WAIT_L(n) asm volatile("s_waitcnt lgkmcnt(" #n ")" ::: "memory")
; #define PG8_BAR __builtin_amdgcn_s_barrier()
; #define PG8_SCHED __builtin_amdgcn_sched_barrier(0)
; template <class Epi, class Sched>
; __device__ __forceinline__ void gemm_phase(int wid_s, PG8_LAS unsigned char* lds, const Gemm g, const Sched& S, const Epi& E) {
;     ...
;             PG8_LDB(B0, 0, 0); PG8_LDB(B1, 0, 1); PG8_SCHED; PG8_LDA(At, 0, 0); PG8_STAGE(PG8_SA(1, 1), a1 + hstepA, voffA);
;             PG8_WAIT_V(8); PG8_WAIT_L(0); PG8_BAR; PG8_MMA(0, 0, At, B0); PG8_MMA(0, 1, At, B1); PG8_BAR; PG8_SCHED;
;             PG8_LDA(At, 0, 1); PG8_STAGE(PG8_SB(0, 0), b2, voffB); PG8_STAGE(PG8_SB(0, 1), b2 + hstepB, voffB); PG8_STAGE(PG8_SA(0, 0), a2, voffA);
.Lmy_kh11:
	ds_read_b128 v[158:161], v138
	ds_read_b128 v[162:165], v138 offset:1024
	ds_read_b128 v[188:191], v138 offset:2048
	ds_read_b128 v[192:195], v138 offset:3072
	v_add_u32_e32 v138, s94, v154
	ds_read_b128 v[196:199], v138
	ds_read_b128 v[200:203], v138 offset:1024
	ds_read_b128 v[204:207], v138 offset:2048
	ds_read_b128 v[208:211], v138 offset:3072
	v_lshl_add_u64 v[138:139], s[26:27], 0, v[136:137]
	s_add_i32 m0, s36, 0xc000
	ds_read_b128 v[212:215], v156
	ds_read_b128 v[216:219], v156 offset:1024
	ds_read_b128 v[220:223], v156 offset:2048
	ds_read_b128 v[224:227], v156 offset:3072
	ds_read_b128 v[228:231], v156 offset:4096
	ds_read_b128 v[232:235], v156 offset:5120
	ds_read_b128 v[236:239], v156 offset:6144
	ds_read_b128 v[240:243], v156 offset:7168
	global_load_lds_dwordx4 v[138:139], off
	v_lshl_add_u64 v[138:139], s[26:27], 0, v[134:135]
	s_add_i32 m0, s36, 0xe000
	s_nop 0
	global_load_lds_dwordx4 v[138:139], off
	s_waitcnt vmcnt(8)
	s_waitcnt lgkmcnt(0)
	s_barrier
	s_setprio 1
	s_waitcnt lgkmcnt(0)
	v_mfma_f32_16x16x32_bf16 v[124:127], v[158:161], v[212:215], v[124:127]
	v_mfma_f32_16x16x32_bf16 v[120:123], v[188:191], v[212:215], v[120:123]
	v_mfma_f32_16x16x32_bf16 v[108:111], v[158:161], v[220:223], v[108:111]
	v_mfma_f32_16x16x32_bf16 v[104:107], v[188:191], v[220:223], v[104:107]
	v_mfma_f32_16x16x32_bf16 v[92:95], v[158:161], v[228:231], v[92:95]
	v_mfma_f32_16x16x32_bf16 v[88:91], v[188:191], v[228:231], v[88:91]
	v_mfma_f32_16x16x32_bf16 v[76:79], v[158:161], v[236:239], v[76:79]
	v_mfma_f32_16x16x32_bf16 v[72:75], v[188:191], v[236:239], v[72:75]
	v_mfma_f32_16x16x32_bf16 v[124:127], v[162:165], v[216:219], v[124:127]
	v_mfma_f32_16x16x32_bf16 v[120:123], v[192:195], v[216:219], v[120:123]
	v_mfma_f32_16x16x32_bf16 v[108:111], v[162:165], v[224:227], v[108:111]
	v_mfma_f32_16x16x32_bf16 v[104:107], v[192:195], v[224:227], v[104:107]
	v_mfma_f32_16x16x32_bf16 v[92:95], v[162:165], v[232:235], v[92:95]
	v_mfma_f32_16x16x32_bf16 v[88:91], v[192:195], v[232:235], v[88:91]
	v_mfma_f32_16x16x32_bf16 v[76:79], v[162:165], v[240:243], v[76:79]
	v_mfma_f32_16x16x32_bf16 v[72:75], v[192:195], v[240:243], v[72:75]
	s_setprio 0
	s_setprio 1
	v_mfma_f32_16x16x32_bf16 v[116:119], v[196:199], v[212:215], v[116:119]
	v_mfma_f32_16x16x32_bf16 v[112:115], v[204:207], v[212:215], v[112:115]
	v_mfma_f32_16x16x32_bf16 v[100:103], v[196:199], v[220:223], v[100:103]
	v_mfma_f32_16x16x32_bf16 v[96:99], v[204:207], v[220:223], v[96:99]
	v_mfma_f32_16x16x32_bf16 v[84:87], v[196:199], v[228:231], v[84:87]
	v_mfma_f32_16x16x32_bf16 v[80:83], v[204:207], v[228:231], v[80:83]
	v_mfma_f32_16x16x32_bf16 v[68:71], v[196:199], v[236:239], v[68:71]
	v_mfma_f32_16x16x32_bf16 v[64:67], v[204:207], v[236:239], v[64:67]
	v_mfma_f32_16x16x32_bf16 v[116:119], v[200:203], v[216:219], v[116:119]
	v_mfma_f32_16x16x32_bf16 v[112:115], v[208:211], v[216:219], v[112:115]
	v_mfma_f32_16x16x32_bf16 v[100:103], v[200:203], v[224:227], v[100:103]
	v_mfma_f32_16x16x32_bf16 v[96:99], v[208:211], v[224:227], v[96:99]
	v_mfma_f32_16x16x32_bf16 v[84:87], v[200:203], v[232:235], v[84:87]
	v_mfma_f32_16x16x32_bf16 v[80:83], v[208:211], v[232:235], v[80:83]
	v_mfma_f32_16x16x32_bf16 v[68:71], v[200:203], v[240:243], v[68:71]
	v_mfma_f32_16x16x32_bf16 v[64:67], v[208:211], v[240:243], v[64:67]
	s_setprio 0
	s_barrier
	s_add_i32 s92, s92, s34
	v_lshl_add_u64 v[138:139], s[56:57], 0, v[144:145]
	s_mov_b32 m0, s92
	ds_read_b128 v[212:215], v156 offset:16384
	ds_read_b128 v[216:219], v156 offset:17408
	ds_read_b128 v[220:223], v156 offset:18432
	ds_read_b128 v[224:227], v156 offset:19456
	ds_read_b128 v[228:231], v156 offset:20480
	ds_read_b128 v[232:235], v156 offset:21504
	ds_read_b128 v[236:239], v156 offset:22528
	ds_read_b128 v[240:243], v156 offset:23552
	global_load_lds_dwordx4 v[138:139], off
	s_add_i32 m0, s92, 0x2000
	v_lshl_add_u64 v[142:143], s[56:57], 0, v[128:129]
	s_add_u32 s56, s56, s8
	s_addc_u32 s57, s57, s9
	s_add_i32 s92, s94, s34
	global_load_lds_dwordx4 v[142:143], off
	v_lshl_add_u64 v[166:167], s[56:57], 0, v[144:145]
	s_mov_b32 m0, s92
	v_lshl_add_u64 v[244:245], s[56:57], 0, v[128:129]
	global_load_lds_dwordx4 v[166:167], off
	s_add_i32 m0, s92, 0x2000
	v_lshl_add_u64 v[246:247], s[28:29], 0, v[132:133]
	global_load_lds_dwordx4 v[244:245], off
	s_mov_b32 m0, s36
	v_lshl_add_u64 v[248:249], s[28:29], 0, v[130:131]
	global_load_lds_dwordx4 v[246:247], off
	s_mov_b32 m0, s37
	s_nop 0
	global_load_lds_dwordx4 v[248:249], off
	s_waitcnt vmcnt(8)
	s_waitcnt lgkmcnt(0)
	s_barrier
; #define PG8_STAGE(bufoff, gbase, voff) do { _Pragma("unroll") for (int _i = 0; _i < 2; ++_i) \
;         __builtin_amdgcn_global_load_lds((const unsigned*)((const char*)(gbase) + (voff)[_i]), (PG8_LAS unsigned*)(lds + (bufoff) + ldsw + _i * 8192), 16, 0, 0); } while (0)
; #define PG8_LDA(dst, b, h) do { _Pragma("unroll") for (int m = 0; m < 4; ++m) _Pragma("unroll") for (int k = 0; k < 2; ++k) dst[m][k] = *(const PG8_LAS bf16x8*)(lds + PG8_SA(b, h) + aoff + m * 2048 + k * 1024); } while (0)
; #define PG8_LDB(dst, b, h) do { _Pragma("unroll") for (int n = 0; n < 2; ++n) _Pragma("unroll") for (int k = 0; k < 2; ++k) dst[n][k] = *(const PG8_LAS bf16x8*)(lds + PG8_SB(b, h) + boff + n * 2048 + k * 1024); } while (0)
; #define PG8_MMA(ai, bj, At, Bt) do { __builtin_amdgcn_s_setprio(1); _Pragma("unroll") for (int m = 0; m < 4; ++m) _Pragma("unroll") for (int n = 0; n < 2; ++n) _Pragma("unroll") for (int k = 0; k < 2; ++k) \
;         acc[ai][bj][m][n] = __builtin_amdgcn_mfma_f32_16x16x32_bf16(Bt[n][k], At[m][k], acc[ai][bj][m][n], 0, 0, 0); __builtin_amdgcn_s_setprio(0); } while (0)
; #define PG8_WAIT_V(n) asm volatile("s_waitcnt vmcnt(" #n ")" ::: "memory")
; #define PG8_WAIT_L(n) asm volatile("s_waitcnt lgkmcnt(" #n ")" ::: "memory")
; #define PG8_BAR __builtin_amdgcn_s_barrier()
; #define PG8_SCHED __builtin_amdgcn_sched_barrier(0)
; template <class Epi, class Sched>
; __device__ __forceinline__ void gemm_phase(int wid_s, PG8_LAS unsigned char* lds, const Gemm g, const Sched& S, const Epi& E) {
;     ...
;             PG8_WAIT_V(8); PG8_WAIT_L(0); PG8_BAR; PG8_MMA(1, 0, At, B0); PG8_MMA(1, 1, At, B1); PG8_BAR; PG8_SCHED;
;             PG8_LDB(B0, 1, 0); PG8_LDB(B1, 1, 1); PG8_SCHED; PG8_LDA(At, 1, 0); PG8_STAGE(PG8_SA(0, 1), a2 + hstepA, voffA);
;             PG8_WAIT_V(8); PG8_WAIT_L(0); PG8_BAR; PG8_MMA(0, 0, At, B0); PG8_MMA(0, 1, At, B1); PG8_BAR; PG8_SCHED;
	s_setprio 1
	s_waitcnt lgkmcnt(0)
	v_mfma_f32_16x16x32_bf16 v[60:63], v[158:161], v[212:215], v[60:63]
	v_mfma_f32_16x16x32_bf16 v[56:59], v[188:191], v[212:215], v[56:59]
	v_mfma_f32_16x16x32_bf16 v[44:47], v[158:161], v[220:223], v[44:47]
	v_mfma_f32_16x16x32_bf16 v[40:43], v[188:191], v[220:223], v[40:43]
	v_mfma_f32_16x16x32_bf16 v[28:31], v[158:161], v[228:231], v[28:31]
	v_mfma_f32_16x16x32_bf16 v[24:27], v[188:191], v[228:231], v[24:27]
	v_mfma_f32_16x16x32_bf16 v[12:15], v[158:161], v[236:239], v[12:15]
	v_mfma_f32_16x16x32_bf16 v[8:11], v[188:191], v[236:239], v[8:11]
	v_mfma_f32_16x16x32_bf16 v[60:63], v[162:165], v[216:219], v[60:63]
	v_mfma_f32_16x16x32_bf16 v[56:59], v[192:195], v[216:219], v[56:59]
	v_mfma_f32_16x16x32_bf16 v[44:47], v[162:165], v[224:227], v[44:47]
	v_mfma_f32_16x16x32_bf16 v[40:43], v[192:195], v[224:227], v[40:43]
	v_mfma_f32_16x16x32_bf16 v[28:31], v[162:165], v[232:235], v[28:31]
	v_mfma_f32_16x16x32_bf16 v[24:27], v[192:195], v[232:235], v[24:27]
	v_mfma_f32_16x16x32_bf16 v[12:15], v[162:165], v[240:243], v[12:15]
	v_mfma_f32_16x16x32_bf16 v[8:11], v[192:195], v[240:243], v[8:11]
	s_setprio 0
	s_setprio 1
	v_mfma_f32_16x16x32_bf16 v[52:55], v[196:199], v[212:215], v[52:55]
	v_mfma_f32_16x16x32_bf16 v[48:51], v[204:207], v[212:215], v[48:51]
	v_mfma_f32_16x16x32_bf16 v[36:39], v[196:199], v[220:223], v[36:39]
	v_mfma_f32_16x16x32_bf16 v[32:35], v[204:207], v[220:223], v[32:35]
	v_mfma_f32_16x16x32_bf16 v[20:23], v[196:199], v[228:231], v[20:23]
	v_mfma_f32_16x16x32_bf16 v[16:19], v[204:207], v[228:231], v[16:19]
	v_mfma_f32_16x16x32_bf16 v[4:7], v[196:199], v[236:239], v[4:7]
	v_mfma_f32_16x16x32_bf16 v[0:3], v[204:207], v[236:239], v[0:3]
	v_mfma_f32_16x16x32_bf16 v[52:55], v[200:203], v[216:219], v[52:55]
	v_mfma_f32_16x16x32_bf16 v[48:51], v[208:211], v[216:219], v[48:51]
	v_mfma_f32_16x16x32_bf16 v[36:39], v[200:203], v[224:227], v[36:39]
	v_mfma_f32_16x16x32_bf16 v[32:35], v[208:211], v[224:227], v[32:35]
	v_mfma_f32_16x16x32_bf16 v[20:23], v[200:203], v[232:235], v[20:23]
	v_mfma_f32_16x16x32_bf16 v[16:19], v[208:211], v[232:235], v[16:19]
	v_mfma_f32_16x16x32_bf16 v[4:7], v[200:203], v[240:243], v[4:7]
	v_mfma_f32_16x16x32_bf16 v[0:3], v[208:211], v[240:243], v[0:3]
	s_setprio 0
	s_barrier
	s_add_i32 s56, 0, 0x18000
	v_add_u32_e32 v140, s56, v154
	s_add_i32 s57, 0, 0x1c000
	ds_read_b128 v[158:161], v140
	ds_read_b128 v[162:165], v140 offset:1024
	ds_read_b128 v[188:191], v140 offset:2048
	ds_read_b128 v[192:195], v140 offset:3072
	v_add_u32_e32 v140, s57, v154
	ds_read_b128 v[196:199], v140
	ds_read_b128 v[200:203], v140 offset:1024
	ds_read_b128 v[204:207], v140 offset:2048
	ds_read_b128 v[208:211], v140 offset:3072
	s_add_u32 s28, s28, s6
	s_addc_u32 s29, s29, s7
	s_mov_b32 m0, s39
	v_lshl_add_u64 v[250:251], s[28:29], 0, v[132:133]
	ds_read_b128 v[212:215], v156 offset:32768
	ds_read_b128 v[216:219], v156 offset:33792
	ds_read_b128 v[220:223], v156 offset:34816
	ds_read_b128 v[224:227], v156 offset:35840
	ds_read_b128 v[228:231], v156 offset:36864
	ds_read_b128 v[232:235], v156 offset:37888
	ds_read_b128 v[236:239], v156 offset:38912
	ds_read_b128 v[240:243], v156 offset:39936
	global_load_lds_dwordx4 v[250:251], off
	v_lshl_add_u64 v[250:251], s[28:29], 0, v[130:131]
	s_mov_b32 m0, s40
	s_nop 0
	global_load_lds_dwordx4 v[250:251], off
	s_waitcnt vmcnt(8)
	s_waitcnt lgkmcnt(0)
	s_barrier
	s_setprio 1
	s_waitcnt lgkmcnt(0)
	v_mfma_f32_16x16x32_bf16 v[124:127], v[158:161], v[212:215], v[124:127]
	v_mfma_f32_16x16x32_bf16 v[120:123], v[188:191], v[212:215], v[120:123]
	v_mfma_f32_16x16x32_bf16 v[108:111], v[158:161], v[220:223], v[108:111]
	v_mfma_f32_16x16x32_bf16 v[104:107], v[188:191], v[220:223], v[104:107]
	v_mfma_f32_16x16x32_bf16 v[92:95], v[158:161], v[228:231], v[92:95]
	v_mfma_f32_16x16x32_bf16 v[88:91], v[188:191], v[228:231], v[88:91]
	v_mfma_f32_16x16x32_bf16 v[76:79], v[158:161], v[236:239], v[76:79]
	v_mfma_f32_16x16x32_bf16 v[72:75], v[188:191], v[236:239], v[72:75]
	v_mfma_f32_16x16x32_bf16 v[124:127], v[162:165], v[216:219], v[124:127]
	v_mfma_f32_16x16x32_bf16 v[120:123], v[192:195], v[216:219], v[120:123]
	v_mfma_f32_16x16x32_bf16 v[108:111], v[162:165], v[224:227], v[108:111]
	v_mfma_f32_16x16x32_bf16 v[104:107], v[192:195], v[224:227], v[104:107]
	v_mfma_f32_16x16x32_bf16 v[92:95], v[162:165], v[232:235], v[92:95]
	v_mfma_f32_16x16x32_bf16 v[88:91], v[192:195], v[232:235], v[88:91]
	v_mfma_f32_16x16x32_bf16 v[76:79], v[162:165], v[240:243], v[76:79]
	v_mfma_f32_16x16x32_bf16 v[72:75], v[192:195], v[240:243], v[72:75]
	s_setprio 0
	s_setprio 1
	v_mfma_f32_16x16x32_bf16 v[116:119], v[196:199], v[212:215], v[116:119]
	v_mfma_f32_16x16x32_bf16 v[112:115], v[204:207], v[212:215], v[112:115]
	v_mfma_f32_16x16x32_bf16 v[100:103], v[196:199], v[220:223], v[100:103]
	v_mfma_f32_16x16x32_bf16 v[96:99], v[204:207], v[220:223], v[96:99]
	v_mfma_f32_16x16x32_bf16 v[84:87], v[196:199], v[228:231], v[84:87]
	v_mfma_f32_16x16x32_bf16 v[80:83], v[204:207], v[228:231], v[80:83]
	v_mfma_f32_16x16x32_bf16 v[68:71], v[196:199], v[236:239], v[68:71]
	v_mfma_f32_16x16x32_bf16 v[64:67], v[204:207], v[236:239], v[64:67]
	v_mfma_f32_16x16x32_bf16 v[116:119], v[200:203], v[216:219], v[116:119]
	v_mfma_f32_16x16x32_bf16 v[112:115], v[208:211], v[216:219], v[112:115]
	v_mfma_f32_16x16x32_bf16 v[100:103], v[200:203], v[224:227], v[100:103]
	v_mfma_f32_16x16x32_bf16 v[96:99], v[208:211], v[224:227], v[96:99]
	v_mfma_f32_16x16x32_bf16 v[84:87], v[200:203], v[232:235], v[84:87]
	v_mfma_f32_16x16x32_bf16 v[80:83], v[208:211], v[232:235], v[80:83]
	v_mfma_f32_16x16x32_bf16 v[68:71], v[200:203], v[240:243], v[68:71]
	v_mfma_f32_16x16x32_bf16 v[64:67], v[208:211], v[240:243], v[64:67]
	s_setprio 0
	s_barrier
; #define PG8_STAGE(bufoff, gbase, voff) do { _Pragma("unroll") for (int _i = 0; _i < 2; ++_i) \
;         __builtin_amdgcn_global_load_lds((const unsigned*)((const char*)(gbase) + (voff)[_i]), (PG8_LAS unsigned*)(lds + (bufoff) + ldsw + _i * 8192), 16, 0, 0); } while (0)
; #define PG8_LDA(dst, b, h) do { _Pragma("unroll") for (int m = 0; m < 4; ++m) _Pragma("unroll") for (int k = 0; k < 2; ++k) dst[m][k] = *(const PG8_LAS bf16x8*)(lds + PG8_SA(b, h) + aoff + m * 2048 + k * 1024); } while (0)
; #define PG8_MMA(ai, bj, At, Bt) do { __builtin_amdgcn_s_setprio(1); _Pragma("unroll") for (int m = 0; m < 4; ++m) _Pragma("unroll") for (int n = 0; n < 2; ++n) _Pragma("unroll") for (int k = 0; k < 2; ++k) \
;         acc[ai][bj][m][n] = __builtin_amdgcn_mfma_f32_16x16x32_bf16(Bt[n][k], At[m][k], acc[ai][bj][m][n], 0, 0, 0); __builtin_amdgcn_s_setprio(0); } while (0)
; #define PG8_WAIT_V(n) asm volatile("s_waitcnt vmcnt(" #n ")" ::: "memory")
; #define PG8_WAIT_L(n) asm volatile("s_waitcnt lgkmcnt(" #n ")" ::: "memory")
; #define PG8_BAR __builtin_amdgcn_s_barrier()
; #define PG8_SCHED __builtin_amdgcn_sched_barrier(0)
; template <class Epi, class Sched>
; __device__ __forceinline__ void gemm_phase(int wid_s, PG8_LAS unsigned char* lds, const Gemm g, const Sched& S, const Epi& E) {
;     ...
;         for (int t = 0; t < nt; t += 2) {
;             const bool last = (t == nt - 2);
;             const char* a1 = cA + (size_t)(t + 1) * kstep;
;             const char* a2 = last ? nA : cA + (size_t)(t + 2) * kstep; const char* b2 = last ? nB : cB + (size_t)(t + 2) * kstep;
;             const char* a3 = a2 + kstep; const char* b3 = b2 + kstep;
;     ...
;             PG8_LDA(At, 1, 1); PG8_STAGE(PG8_SB(1, 0), b3, voffB); PG8_STAGE(PG8_SB(1, 1), b3 + hstepB, voffB); PG8_STAGE(PG8_SA(1, 0), a3, voffA);
;             PG8_WAIT_V(8); PG8_WAIT_L(0); PG8_BAR; PG8_MMA(1, 0, At, B0); PG8_MMA(1, 1, At, B1); PG8_BAR; PG8_SCHED;
	s_add_i32 s28, s56, s34
	v_lshl_add_u64 v[138:139], v[138:139], 0, s[96:97]
	s_mov_b32 m0, s28
	ds_read_b128 v[212:215], v156 offset:49152
	ds_read_b128 v[216:219], v156 offset:50176
	ds_read_b128 v[220:223], v156 offset:51200
	ds_read_b128 v[224:227], v156 offset:52224
	ds_read_b128 v[228:231], v156 offset:53248
	ds_read_b128 v[232:235], v156 offset:54272
	ds_read_b128 v[236:239], v156 offset:55296
	ds_read_b128 v[240:243], v156 offset:56320
	global_load_lds_dwordx4 v[138:139], off
	v_lshl_add_u64 v[138:139], v[142:143], 0, s[96:97]
	s_add_i32 m0, s28, 0x2000
	s_add_i32 s28, s57, s34
	global_load_lds_dwordx4 v[138:139], off
	v_lshl_add_u64 v[138:139], v[166:167], 0, s[96:97]
	s_mov_b32 m0, s28
	s_nop 0
	global_load_lds_dwordx4 v[138:139], off
	v_lshl_add_u64 v[138:139], v[244:245], 0, s[96:97]
	s_add_i32 m0, s28, 0x2000
	s_nop 0
	global_load_lds_dwordx4 v[138:139], off
	v_lshl_add_u64 v[138:139], v[246:247], 0, s[96:97]
	s_mov_b32 m0, s41
	s_nop 0
	global_load_lds_dwordx4 v[138:139], off
	v_lshl_add_u64 v[138:139], v[248:249], 0, s[96:97]
	s_mov_b32 m0, s44
	s_nop 0
	global_load_lds_dwordx4 v[138:139], off
	s_waitcnt vmcnt(8)
	s_waitcnt lgkmcnt(0)
	s_barrier
	s_setprio 1
	s_waitcnt lgkmcnt(0)
	v_mfma_f32_16x16x32_bf16 v[60:63], v[158:161], v[212:215], v[60:63]
	v_mfma_f32_16x16x32_bf16 v[56:59], v[188:191], v[212:215], v[56:59]
	v_mfma_f32_16x16x32_bf16 v[44:47], v[158:161], v[220:223], v[44:47]
	v_mfma_f32_16x16x32_bf16 v[40:43], v[188:191], v[220:223], v[40:43]
	v_mfma_f32_16x16x32_bf16 v[28:31], v[158:161], v[228:231], v[28:31]
	v_mfma_f32_16x16x32_bf16 v[24:27], v[188:191], v[228:231], v[24:27]
	v_mfma_f32_16x16x32_bf16 v[12:15], v[158:161], v[236:239], v[12:15]
	v_mfma_f32_16x16x32_bf16 v[8:11], v[188:191], v[236:239], v[8:11]
	v_mfma_f32_16x16x32_bf16 v[60:63], v[162:165], v[216:219], v[60:63]
	v_mfma_f32_16x16x32_bf16 v[56:59], v[192:195], v[216:219], v[56:59]
	v_mfma_f32_16x16x32_bf16 v[44:47], v[162:165], v[224:227], v[44:47]
	v_mfma_f32_16x16x32_bf16 v[40:43], v[192:195], v[224:227], v[40:43]
	v_mfma_f32_16x16x32_bf16 v[28:31], v[162:165], v[232:235], v[28:31]
	v_mfma_f32_16x16x32_bf16 v[24:27], v[192:195], v[232:235], v[24:27]
	v_mfma_f32_16x16x32_bf16 v[12:15], v[162:165], v[240:243], v[12:15]
	v_mfma_f32_16x16x32_bf16 v[8:11], v[192:195], v[240:243], v[8:11]
	s_setprio 0
	s_setprio 1
	v_mfma_f32_16x16x32_bf16 v[52:55], v[196:199], v[212:215], v[52:55]
	s_add_u32 s33, s33, 0x100
	s_addc_u32 s50, s50, 0
	v_mfma_f32_16x16x32_bf16 v[48:51], v[204:207], v[212:215], v[48:51]
	s_add_u32 s26, s26, 0x100
	s_addc_u32 s27, s27, 0
	v_mfma_f32_16x16x32_bf16 v[36:39], v[196:199], v[220:223], v[36:39]
	s_cmp_ge_i32 s51, s45
	s_mov_b32 s28, s51
	s_cbranch_scc1 .Lmy_kx11
	v_mfma_f32_16x16x32_bf16 v[32:35], v[204:207], v[220:223], v[32:35]
	s_add_i32 s51, s28, 2
	v_mfma_f32_16x16x32_bf16 v[20:23], v[196:199], v[228:231], v[20:23]
	s_add_u32 s56, s26, 0x80
	v_mfma_f32_16x16x32_bf16 v[16:19], v[204:207], v[228:231], v[16:19]
	s_addc_u32 s29, s27, 0
	v_mfma_f32_16x16x32_bf16 v[4:7], v[196:199], v[236:239], v[4:7]
	s_add_i32 s92, 0, 0x10000
	v_mfma_f32_16x16x32_bf16 v[0:3], v[204:207], v[236:239], v[0:3]
	s_cmp_eq_u32 s46, s28
	v_mfma_f32_16x16x32_bf16 v[52:55], v[200:203], v[216:219], v[52:55]
	s_cselect_b32 s29, s5, s29
	v_mfma_f32_16x16x32_bf16 v[48:51], v[208:211], v[216:219], v[48:51]
	s_cselect_b32 s28, s4, s56
	v_mfma_f32_16x16x32_bf16 v[36:39], v[200:203], v[224:227], v[36:39]
	v_add_u32_e32 v138, s92, v154
	v_mfma_f32_16x16x32_bf16 v[32:35], v[208:211], v[224:227], v[32:35]
	s_cselect_b32 s57, s25, s50
	v_mfma_f32_16x16x32_bf16 v[20:23], v[200:203], v[232:235], v[20:23]
	s_cselect_b32 s56, s24, s33
	v_mfma_f32_16x16x32_bf16 v[16:19], v[208:211], v[232:235], v[16:19]
	s_add_i32 s94, 0, 0x14000
	v_mfma_f32_16x16x32_bf16 v[4:7], v[200:203], v[240:243], v[4:7]
	v_mfma_f32_16x16x32_bf16 v[0:3], v[208:211], v[240:243], v[0:3]
	s_setprio 0
	s_barrier
	s_branch .Lmy_kh11
.Lmy_kx11:
	v_mfma_f32_16x16x32_bf16 v[32:35], v[204:207], v[220:223], v[32:35]
	v_mfma_f32_16x16x32_bf16 v[20:23], v[196:199], v[228:231], v[20:23]
	v_mfma_f32_16x16x32_bf16 v[16:19], v[204:207], v[228:231], v[16:19]
	v_mfma_f32_16x16x32_bf16 v[4:7], v[196:199], v[236:239], v[4:7]
	v_mfma_f32_16x16x32_bf16 v[0:3], v[204:207], v[236:239], v[0:3]
	v_mfma_f32_16x16x32_bf16 v[52:55], v[200:203], v[216:219], v[52:55]
	v_mfma_f32_16x16x32_bf16 v[48:51], v[208:211], v[216:219], v[48:51]
	v_mfma_f32_16x16x32_bf16 v[36:39], v[200:203], v[224:227], v[36:39]
	v_mfma_f32_16x16x32_bf16 v[32:35], v[208:211], v[224:227], v[32:35]
	v_mfma_f32_16x16x32_bf16 v[20:23], v[200:203], v[232:235], v[20:23]
	v_mfma_f32_16x16x32_bf16 v[16:19], v[208:211], v[232:235], v[16:19]
	v_mfma_f32_16x16x32_bf16 v[4:7], v[200:203], v[240:243], v[4:7]
	v_mfma_f32_16x16x32_bf16 v[0:3], v[208:211], v[240:243], v[0:3]
	s_setprio 0
	s_barrier
	v_readlane_b32 s92, v254, 54
	v_readlane_b32 s94, v254, 55
	s_movk_i32 s51, 0x200
	s_movk_i32 s33, 0x300
	s_mov_b32 s50, s95

; #define PG8_STAGE(bufoff, gbase, voff) do { _Pragma("unroll") for (int _i = 0; _i < 2; ++_i) \
;         __builtin_amdgcn_global_load_lds((const unsigned*)((const char*)(gbase) + (voff)[_i]), (PG8_LAS unsigned*)(lds + (bufoff) + ldsw + _i * 8192), 16, 0, 0); } while (0)
; #define PG8_LDA(dst, b, h) do { _Pragma("unroll") for (int m = 0; m < 4; ++m) _Pragma("unroll") for (int k = 0; k < 2; ++k) dst[m][k] = *(const PG8_LAS bf16x8*)(lds + PG8_SA(b, h) + aoff + m * 2048 + k * 1024); } while (0)
; #define PG8_LDB(dst, b, h) do { _Pragma("unroll") for (int n = 0; n < 2; ++n) _Pragma("unroll") for (int k = 0; k < 2; ++k) dst[n][k] = *(const PG8_LAS bf16x8*)(lds + PG8_SB(b, h) + boff + n * 2048 + k * 1024); } while (0)
; #define PG8_MMA(ai, bj, At, Bt) do { __builtin_amdgcn_s_setprio(1); _Pragma("unroll") for (int m = 0; m < 4; ++m) _Pragma("unroll") for (int n = 0; n < 2; ++n) _Pragma("unroll") for (int k = 0; k < 2; ++k) \
;         acc[ai][bj][m][n] = __builtin_amdgcn_mfma_f32_16x16x32_bf16(Bt[n][k], At[m][k], acc[ai][bj][m][n], 0, 0, 0); __builtin_amdgcn_s_setprio(0); } while (0)
; #define PG8_WAIT_V(n) asm volatile("s_waitcnt vmcnt(" #n ")" ::: "memory")
; #define PG8_WAIT_L(n) asm volatile("s_waitcnt lgkmcnt(" #n ")" ::: "memory")
; #define PG8_BAR __builtin_amdgcn_s_barrier()
; #define PG8_SCHED __builtin_amdgcn_sched_barrier(0)
; template <class Epi, class Sched>
; __device__ __forceinline__ void gemm_phase(int wid_s, PG8_LAS unsigned char* lds, const Gemm g, const Sched& S, const Epi& E) {
;     ...
;             PG8_LDB(B0, 0, 0); PG8_LDB(B1, 0, 1); PG8_SCHED; PG8_LDA(At, 0, 0); PG8_STAGE(PG8_SA(1, 1), a1 + hstepA, voffA);
;             PG8_WAIT_V(8); PG8_WAIT_L(0); PG8_BAR; PG8_MMA(0, 0, At, B0); PG8_MMA(0, 1, At, B1); PG8_BAR; PG8_SCHED;
;             PG8_LDA(At, 0, 1); PG8_STAGE(PG8_SB(0, 0), b2, voffB); PG8_STAGE(PG8_SB(0, 1), b2 + hstepB, voffB); PG8_STAGE(PG8_SA(0, 0), a2, voffA);
.Lmy_kh12:
	ds_read_b128 v[138:141], v142
	ds_read_b128 v[162:165], v142 offset:1024
	ds_read_b128 v[186:189], v142 offset:2048
	ds_read_b128 v[190:193], v142 offset:3072
	v_add_u32_e32 v142, s47, v159
	ds_read_b128 v[194:197], v142
	ds_read_b128 v[198:201], v142 offset:1024
	ds_read_b128 v[202:205], v142 offset:2048
	ds_read_b128 v[206:209], v142 offset:3072
	v_lshl_add_u64 v[142:143], s[4:5], 0, v[136:137]
	s_add_i32 m0, s92, 0xc000
	ds_read_b128 v[210:213], v161
	ds_read_b128 v[214:217], v161 offset:1024
	ds_read_b128 v[218:221], v161 offset:2048
	ds_read_b128 v[222:225], v161 offset:3072
	ds_read_b128 v[226:229], v161 offset:4096
	ds_read_b128 v[230:233], v161 offset:5120
	ds_read_b128 v[234:237], v161 offset:6144
	ds_read_b128 v[238:241], v161 offset:7168
	global_load_lds_dwordx4 v[142:143], off
	v_lshl_add_u64 v[142:143], s[4:5], 0, v[134:135]
	s_add_i32 m0, s92, 0xe000
	s_nop 0
	global_load_lds_dwordx4 v[142:143], off
	s_waitcnt vmcnt(8)
	s_waitcnt lgkmcnt(0)
	s_barrier
	s_setprio 1
	s_waitcnt lgkmcnt(0)
	v_mfma_f32_16x16x32_bf16 v[124:127], v[138:141], v[210:213], v[124:127]
	v_mfma_f32_16x16x32_bf16 v[120:123], v[186:189], v[210:213], v[120:123]
	v_mfma_f32_16x16x32_bf16 v[108:111], v[138:141], v[218:221], v[108:111]
	v_mfma_f32_16x16x32_bf16 v[104:107], v[186:189], v[218:221], v[104:107]
	v_mfma_f32_16x16x32_bf16 v[92:95], v[138:141], v[226:229], v[92:95]
	v_mfma_f32_16x16x32_bf16 v[88:91], v[186:189], v[226:229], v[88:91]
	v_mfma_f32_16x16x32_bf16 v[76:79], v[138:141], v[234:237], v[76:79]
	v_mfma_f32_16x16x32_bf16 v[72:75], v[186:189], v[234:237], v[72:75]
	v_mfma_f32_16x16x32_bf16 v[124:127], v[162:165], v[214:217], v[124:127]
	v_mfma_f32_16x16x32_bf16 v[120:123], v[190:193], v[214:217], v[120:123]
	v_mfma_f32_16x16x32_bf16 v[108:111], v[162:165], v[222:225], v[108:111]
	v_mfma_f32_16x16x32_bf16 v[104:107], v[190:193], v[222:225], v[104:107]
	v_mfma_f32_16x16x32_bf16 v[92:95], v[162:165], v[230:233], v[92:95]
	v_mfma_f32_16x16x32_bf16 v[88:91], v[190:193], v[230:233], v[88:91]
	v_mfma_f32_16x16x32_bf16 v[76:79], v[162:165], v[238:241], v[76:79]
	v_mfma_f32_16x16x32_bf16 v[72:75], v[190:193], v[238:241], v[72:75]
	s_setprio 0
	s_setprio 1
	v_mfma_f32_16x16x32_bf16 v[116:119], v[194:197], v[210:213], v[116:119]
	v_mfma_f32_16x16x32_bf16 v[112:115], v[202:205], v[210:213], v[112:115]
	v_mfma_f32_16x16x32_bf16 v[100:103], v[194:197], v[218:221], v[100:103]
	v_mfma_f32_16x16x32_bf16 v[96:99], v[202:205], v[218:221], v[96:99]
	v_mfma_f32_16x16x32_bf16 v[84:87], v[194:197], v[226:229], v[84:87]
	v_mfma_f32_16x16x32_bf16 v[80:83], v[202:205], v[226:229], v[80:83]
	v_mfma_f32_16x16x32_bf16 v[68:71], v[194:197], v[234:237], v[68:71]
	v_mfma_f32_16x16x32_bf16 v[64:67], v[202:205], v[234:237], v[64:67]
	v_mfma_f32_16x16x32_bf16 v[116:119], v[198:201], v[214:217], v[116:119]
	v_mfma_f32_16x16x32_bf16 v[112:115], v[206:209], v[214:217], v[112:115]
	v_mfma_f32_16x16x32_bf16 v[100:103], v[198:201], v[222:225], v[100:103]
	v_mfma_f32_16x16x32_bf16 v[96:99], v[206:209], v[222:225], v[96:99]
	v_mfma_f32_16x16x32_bf16 v[84:87], v[198:201], v[230:233], v[84:87]
	v_mfma_f32_16x16x32_bf16 v[80:83], v[206:209], v[230:233], v[80:83]
	v_mfma_f32_16x16x32_bf16 v[68:71], v[198:201], v[238:241], v[68:71]
	v_mfma_f32_16x16x32_bf16 v[64:67], v[206:209], v[238:241], v[64:67]
	s_setprio 0
	s_barrier
	s_add_i32 s53, s53, s55
	v_lshl_add_u64 v[142:143], s[50:51], 0, v[144:145]
	s_mov_b32 m0, s53
	ds_read_b128 v[210:213], v161 offset:16384
	ds_read_b128 v[214:217], v161 offset:17408
	ds_read_b128 v[218:221], v161 offset:18432
	ds_read_b128 v[222:225], v161 offset:19456
	ds_read_b128 v[226:229], v161 offset:20480
	ds_read_b128 v[230:233], v161 offset:21504
	ds_read_b128 v[234:237], v161 offset:22528
	ds_read_b128 v[238:241], v161 offset:23552
	global_load_lds_dwordx4 v[142:143], off
	s_add_i32 m0, s53, 0x2000
	v_lshl_add_u64 v[154:155], s[50:51], 0, v[132:133]
	s_add_u32 s50, s50, s14
	s_addc_u32 s51, s51, s15
	s_add_i32 s47, s47, s55
	global_load_lds_dwordx4 v[154:155], off
	v_lshl_add_u64 v[166:167], s[50:51], 0, v[144:145]
	s_mov_b32 m0, s47
	v_lshl_add_u64 v[242:243], s[50:51], 0, v[132:133]
	global_load_lds_dwordx4 v[166:167], off
	s_add_i32 m0, s47, 0x2000
	v_lshl_add_u64 v[244:245], s[6:7], 0, v[128:129]
	global_load_lds_dwordx4 v[242:243], off
	s_mov_b32 m0, s92
	v_lshl_add_u64 v[246:247], s[6:7], 0, v[130:131]
	global_load_lds_dwordx4 v[244:245], off
	s_mov_b32 m0, s94
	s_nop 0
	global_load_lds_dwordx4 v[246:247], off
	s_waitcnt vmcnt(8)
	s_waitcnt lgkmcnt(0)
	s_barrier
; #define PG8_STAGE(bufoff, gbase, voff) do { _Pragma("unroll") for (int _i = 0; _i < 2; ++_i) \
;         __builtin_amdgcn_global_load_lds((const unsigned*)((const char*)(gbase) + (voff)[_i]), (PG8_LAS unsigned*)(lds + (bufoff) + ldsw + _i * 8192), 16, 0, 0); } while (0)
; #define PG8_LDA(dst, b, h) do { _Pragma("unroll") for (int m = 0; m < 4; ++m) _Pragma("unroll") for (int k = 0; k < 2; ++k) dst[m][k] = *(const PG8_LAS bf16x8*)(lds + PG8_SA(b, h) + aoff + m * 2048 + k * 1024); } while (0)
; #define PG8_LDB(dst, b, h) do { _Pragma("unroll") for (int n = 0; n < 2; ++n) _Pragma("unroll") for (int k = 0; k < 2; ++k) dst[n][k] = *(const PG8_LAS bf16x8*)(lds + PG8_SB(b, h) + boff + n * 2048 + k * 1024); } while (0)
; #define PG8_MMA(ai, bj, At, Bt) do { __builtin_amdgcn_s_setprio(1); _Pragma("unroll") for (int m = 0; m < 4; ++m) _Pragma("unroll") for (int n = 0; n < 2; ++n) _Pragma("unroll") for (int k = 0; k < 2; ++k) \
;         acc[ai][bj][m][n] = __builtin_amdgcn_mfma_f32_16x16x32_bf16(Bt[n][k], At[m][k], acc[ai][bj][m][n], 0, 0, 0); __builtin_amdgcn_s_setprio(0); } while (0)
; #define PG8_WAIT_V(n) asm volatile("s_waitcnt vmcnt(" #n ")" ::: "memory")
; #define PG8_WAIT_L(n) asm volatile("s_waitcnt lgkmcnt(" #n ")" ::: "memory")
; #define PG8_BAR __builtin_amdgcn_s_barrier()
; #define PG8_SCHED __builtin_amdgcn_sched_barrier(0)
; template <class Epi, class Sched>
; __device__ __forceinline__ void gemm_phase(int wid_s, PG8_LAS unsigned char* lds, const Gemm g, const Sched& S, const Epi& E) {
;     ...
;             PG8_WAIT_V(8); PG8_WAIT_L(0); PG8_BAR; PG8_MMA(1, 0, At, B0); PG8_MMA(1, 1, At, B1); PG8_BAR; PG8_SCHED;
;             PG8_LDB(B0, 1, 0); PG8_LDB(B1, 1, 1); PG8_SCHED; PG8_LDA(At, 1, 0); PG8_STAGE(PG8_SA(0, 1), a2 + hstepA, voffA);
;             PG8_WAIT_V(8); PG8_WAIT_L(0); PG8_BAR; PG8_MMA(0, 0, At, B0); PG8_MMA(0, 1, At, B1); PG8_BAR; PG8_SCHED;
	s_setprio 1
	s_waitcnt lgkmcnt(0)
	v_mfma_f32_16x16x32_bf16 v[60:63], v[138:141], v[210:213], v[60:63]
	v_mfma_f32_16x16x32_bf16 v[56:59], v[186:189], v[210:213], v[56:59]
	v_mfma_f32_16x16x32_bf16 v[44:47], v[138:141], v[218:221], v[44:47]
	v_mfma_f32_16x16x32_bf16 v[40:43], v[186:189], v[218:221], v[40:43]
	v_mfma_f32_16x16x32_bf16 v[28:31], v[138:141], v[226:229], v[28:31]
	v_mfma_f32_16x16x32_bf16 v[24:27], v[186:189], v[226:229], v[24:27]
	v_mfma_f32_16x16x32_bf16 v[12:15], v[138:141], v[234:237], v[12:15]
	v_mfma_f32_16x16x32_bf16 v[8:11], v[186:189], v[234:237], v[8:11]
	v_mfma_f32_16x16x32_bf16 v[60:63], v[162:165], v[214:217], v[60:63]
	v_mfma_f32_16x16x32_bf16 v[56:59], v[190:193], v[214:217], v[56:59]
	v_mfma_f32_16x16x32_bf16 v[44:47], v[162:165], v[222:225], v[44:47]
	v_mfma_f32_16x16x32_bf16 v[40:43], v[190:193], v[222:225], v[40:43]
	v_mfma_f32_16x16x32_bf16 v[28:31], v[162:165], v[230:233], v[28:31]
	v_mfma_f32_16x16x32_bf16 v[24:27], v[190:193], v[230:233], v[24:27]
	v_mfma_f32_16x16x32_bf16 v[12:15], v[162:165], v[238:241], v[12:15]
	v_mfma_f32_16x16x32_bf16 v[8:11], v[190:193], v[238:241], v[8:11]
	s_setprio 0
	s_setprio 1
	v_mfma_f32_16x16x32_bf16 v[52:55], v[194:197], v[210:213], v[52:55]
	v_mfma_f32_16x16x32_bf16 v[48:51], v[202:205], v[210:213], v[48:51]
	v_mfma_f32_16x16x32_bf16 v[36:39], v[194:197], v[218:221], v[36:39]
	v_mfma_f32_16x16x32_bf16 v[32:35], v[202:205], v[218:221], v[32:35]
	v_mfma_f32_16x16x32_bf16 v[20:23], v[194:197], v[226:229], v[20:23]
	v_mfma_f32_16x16x32_bf16 v[16:19], v[202:205], v[226:229], v[16:19]
	v_mfma_f32_16x16x32_bf16 v[4:7], v[194:197], v[234:237], v[4:7]
	v_mfma_f32_16x16x32_bf16 v[0:3], v[202:205], v[234:237], v[0:3]
	v_mfma_f32_16x16x32_bf16 v[52:55], v[198:201], v[214:217], v[52:55]
	v_mfma_f32_16x16x32_bf16 v[48:51], v[206:209], v[214:217], v[48:51]
	v_mfma_f32_16x16x32_bf16 v[36:39], v[198:201], v[222:225], v[36:39]
	v_mfma_f32_16x16x32_bf16 v[32:35], v[206:209], v[222:225], v[32:35]
	v_mfma_f32_16x16x32_bf16 v[20:23], v[198:201], v[230:233], v[20:23]
	v_mfma_f32_16x16x32_bf16 v[16:19], v[206:209], v[230:233], v[16:19]
	v_mfma_f32_16x16x32_bf16 v[4:7], v[198:201], v[238:241], v[4:7]
	v_mfma_f32_16x16x32_bf16 v[0:3], v[206:209], v[238:241], v[0:3]
	s_setprio 0
	s_barrier
	s_add_i32 s47, 0, 0x18000
	v_add_u32_e32 v185, s47, v159
	s_add_i32 s50, 0, 0x1c000
	ds_read_b128 v[138:141], v185
	ds_read_b128 v[162:165], v185 offset:1024
	ds_read_b128 v[186:189], v185 offset:2048
	ds_read_b128 v[190:193], v185 offset:3072
	v_add_u32_e32 v185, s50, v159
	ds_read_b128 v[194:197], v185
	ds_read_b128 v[198:201], v185 offset:1024
	ds_read_b128 v[202:205], v185 offset:2048
	ds_read_b128 v[206:209], v185 offset:3072
	s_add_u32 s6, s6, s12
	s_addc_u32 s7, s7, s13
	s_mov_b32 m0, s95
	v_lshl_add_u64 v[248:249], s[6:7], 0, v[128:129]
	ds_read_b128 v[210:213], v161 offset:32768
	ds_read_b128 v[214:217], v161 offset:33792
	ds_read_b128 v[218:221], v161 offset:34816
	ds_read_b128 v[222:225], v161 offset:35840
	ds_read_b128 v[226:229], v161 offset:36864
	ds_read_b128 v[230:233], v161 offset:37888
	ds_read_b128 v[234:237], v161 offset:38912
	ds_read_b128 v[238:241], v161 offset:39936
	global_load_lds_dwordx4 v[248:249], off
	v_lshl_add_u64 v[248:249], s[6:7], 0, v[130:131]
	s_mov_b32 m0, s8
	s_nop 0
	global_load_lds_dwordx4 v[248:249], off
	s_waitcnt vmcnt(8)
	s_waitcnt lgkmcnt(0)
	s_barrier
	s_setprio 1
	s_waitcnt lgkmcnt(0)
	v_mfma_f32_16x16x32_bf16 v[124:127], v[138:141], v[210:213], v[124:127]
	v_mfma_f32_16x16x32_bf16 v[120:123], v[186:189], v[210:213], v[120:123]
	v_mfma_f32_16x16x32_bf16 v[108:111], v[138:141], v[218:221], v[108:111]
	v_mfma_f32_16x16x32_bf16 v[104:107], v[186:189], v[218:221], v[104:107]
	v_mfma_f32_16x16x32_bf16 v[92:95], v[138:141], v[226:229], v[92:95]
	v_mfma_f32_16x16x32_bf16 v[88:91], v[186:189], v[226:229], v[88:91]
	v_mfma_f32_16x16x32_bf16 v[76:79], v[138:141], v[234:237], v[76:79]
	v_mfma_f32_16x16x32_bf16 v[72:75], v[186:189], v[234:237], v[72:75]
	v_mfma_f32_16x16x32_bf16 v[124:127], v[162:165], v[214:217], v[124:127]
	v_mfma_f32_16x16x32_bf16 v[120:123], v[190:193], v[214:217], v[120:123]
	v_mfma_f32_16x16x32_bf16 v[108:111], v[162:165], v[222:225], v[108:111]
	v_mfma_f32_16x16x32_bf16 v[104:107], v[190:193], v[222:225], v[104:107]
	v_mfma_f32_16x16x32_bf16 v[92:95], v[162:165], v[230:233], v[92:95]
	v_mfma_f32_16x16x32_bf16 v[88:91], v[190:193], v[230:233], v[88:91]
	v_mfma_f32_16x16x32_bf16 v[76:79], v[162:165], v[238:241], v[76:79]
	v_mfma_f32_16x16x32_bf16 v[72:75], v[190:193], v[238:241], v[72:75]
	s_setprio 0
	s_setprio 1
	v_mfma_f32_16x16x32_bf16 v[116:119], v[194:197], v[210:213], v[116:119]
	v_mfma_f32_16x16x32_bf16 v[112:115], v[202:205], v[210:213], v[112:115]
	v_mfma_f32_16x16x32_bf16 v[100:103], v[194:197], v[218:221], v[100:103]
	v_mfma_f32_16x16x32_bf16 v[96:99], v[202:205], v[218:221], v[96:99]
	v_mfma_f32_16x16x32_bf16 v[84:87], v[194:197], v[226:229], v[84:87]
	v_mfma_f32_16x16x32_bf16 v[80:83], v[202:205], v[226:229], v[80:83]
	v_mfma_f32_16x16x32_bf16 v[68:71], v[194:197], v[234:237], v[68:71]
	v_mfma_f32_16x16x32_bf16 v[64:67], v[202:205], v[234:237], v[64:67]
	v_mfma_f32_16x16x32_bf16 v[116:119], v[198:201], v[214:217], v[116:119]
	v_mfma_f32_16x16x32_bf16 v[112:115], v[206:209], v[214:217], v[112:115]
	v_mfma_f32_16x16x32_bf16 v[100:103], v[198:201], v[222:225], v[100:103]
	v_mfma_f32_16x16x32_bf16 v[96:99], v[206:209], v[222:225], v[96:99]
	v_mfma_f32_16x16x32_bf16 v[84:87], v[198:201], v[230:233], v[84:87]
	v_mfma_f32_16x16x32_bf16 v[80:83], v[206:209], v[230:233], v[80:83]
	v_mfma_f32_16x16x32_bf16 v[68:71], v[198:201], v[238:241], v[68:71]
	v_mfma_f32_16x16x32_bf16 v[64:67], v[206:209], v[238:241], v[64:67]
	s_setprio 0
	s_barrier
; #define PG8_STAGE(bufoff, gbase, voff) do { _Pragma("unroll") for (int _i = 0; _i < 2; ++_i) \
;         __builtin_amdgcn_global_load_lds((const unsigned*)((const char*)(gbase) + (voff)[_i]), (PG8_LAS unsigned*)(lds + (bufoff) + ldsw + _i * 8192), 16, 0, 0); } while (0)
; #define PG8_LDA(dst, b, h) do { _Pragma("unroll") for (int m = 0; m < 4; ++m) _Pragma("unroll") for (int k = 0; k < 2; ++k) dst[m][k] = *(const PG8_LAS bf16x8*)(lds + PG8_SA(b, h) + aoff + m * 2048 + k * 1024); } while (0)
; #define PG8_MMA(ai, bj, At, Bt) do { __builtin_amdgcn_s_setprio(1); _Pragma("unroll") for (int m = 0; m < 4; ++m) _Pragma("unroll") for (int n = 0; n < 2; ++n) _Pragma("unroll") for (int k = 0; k < 2; ++k) \
;         acc[ai][bj][m][n] = __builtin_amdgcn_mfma_f32_16x16x32_bf16(Bt[n][k], At[m][k], acc[ai][bj][m][n], 0, 0, 0); __builtin_amdgcn_s_setprio(0); } while (0)
; #define PG8_WAIT_V(n) asm volatile("s_waitcnt vmcnt(" #n ")" ::: "memory")
; #define PG8_WAIT_L(n) asm volatile("s_waitcnt lgkmcnt(" #n ")" ::: "memory")
; #define PG8_BAR __builtin_amdgcn_s_barrier()
; #define PG8_SCHED __builtin_amdgcn_sched_barrier(0)
; template <class Epi, class Sched>
; __device__ __forceinline__ void gemm_phase(int wid_s, PG8_LAS unsigned char* lds, const Gemm g, const Sched& S, const Epi& E) {
;     ...
;         for (int t = 0; t < nt; t += 2) {
;             const bool last = (t == nt - 2);
;             const char* a1 = cA + (size_t)(t + 1) * kstep;
;             const char* a2 = last ? nA : cA + (size_t)(t + 2) * kstep; const char* b2 = last ? nB : cB + (size_t)(t + 2) * kstep;
;             const char* a3 = a2 + kstep; const char* b3 = b2 + kstep;
;     ...
;             PG8_LDA(At, 1, 1); PG8_STAGE(PG8_SB(1, 0), b3, voffB); PG8_STAGE(PG8_SB(1, 1), b3 + hstepB, voffB); PG8_STAGE(PG8_SA(1, 0), a3, voffA);
;             PG8_WAIT_V(8); PG8_WAIT_L(0); PG8_BAR; PG8_MMA(1, 0, At, B0); PG8_MMA(1, 1, At, B1); PG8_BAR; PG8_SCHED;
	s_add_i32 s6, s47, s55
	v_lshl_add_u64 v[142:143], v[142:143], 0, s[96:97]
	s_mov_b32 m0, s6
	ds_read_b128 v[210:213], v161 offset:49152
	ds_read_b128 v[214:217], v161 offset:50176
	ds_read_b128 v[218:221], v161 offset:51200
	ds_read_b128 v[222:225], v161 offset:52224
	ds_read_b128 v[226:229], v161 offset:53248
	ds_read_b128 v[230:233], v161 offset:54272
	ds_read_b128 v[234:237], v161 offset:55296
	ds_read_b128 v[238:241], v161 offset:56320
	global_load_lds_dwordx4 v[142:143], off
	v_lshl_add_u64 v[142:143], v[154:155], 0, s[96:97]
	s_add_i32 m0, s6, 0x2000
	s_add_i32 s6, s50, s55
	global_load_lds_dwordx4 v[142:143], off
	v_lshl_add_u64 v[142:143], v[166:167], 0, s[96:97]
	s_mov_b32 m0, s6
	s_nop 0
	global_load_lds_dwordx4 v[142:143], off
	v_lshl_add_u64 v[142:143], v[242:243], 0, s[96:97]
	s_add_i32 m0, s6, 0x2000
	s_nop 0
	global_load_lds_dwordx4 v[142:143], off
	v_lshl_add_u64 v[142:143], v[244:245], 0, s[96:97]
	s_mov_b32 m0, s9
	s_nop 0
	global_load_lds_dwordx4 v[142:143], off
	v_lshl_add_u64 v[142:143], v[246:247], 0, s[96:97]
	s_mov_b32 m0, s0
	s_nop 0
	global_load_lds_dwordx4 v[142:143], off
	s_waitcnt vmcnt(8)
	s_waitcnt lgkmcnt(0)
	s_barrier
	s_setprio 1
	s_waitcnt lgkmcnt(0)
	v_mfma_f32_16x16x32_bf16 v[60:63], v[138:141], v[210:213], v[60:63]
	v_mfma_f32_16x16x32_bf16 v[56:59], v[186:189], v[210:213], v[56:59]
	v_mfma_f32_16x16x32_bf16 v[44:47], v[138:141], v[218:221], v[44:47]
	v_mfma_f32_16x16x32_bf16 v[40:43], v[186:189], v[218:221], v[40:43]
	v_mfma_f32_16x16x32_bf16 v[28:31], v[138:141], v[226:229], v[28:31]
	v_mfma_f32_16x16x32_bf16 v[24:27], v[186:189], v[226:229], v[24:27]
	v_mfma_f32_16x16x32_bf16 v[12:15], v[138:141], v[234:237], v[12:15]
	v_mfma_f32_16x16x32_bf16 v[8:11], v[186:189], v[234:237], v[8:11]
	v_mfma_f32_16x16x32_bf16 v[60:63], v[162:165], v[214:217], v[60:63]
	v_mfma_f32_16x16x32_bf16 v[56:59], v[190:193], v[214:217], v[56:59]
	v_mfma_f32_16x16x32_bf16 v[44:47], v[162:165], v[222:225], v[44:47]
	v_mfma_f32_16x16x32_bf16 v[40:43], v[190:193], v[222:225], v[40:43]
	v_mfma_f32_16x16x32_bf16 v[28:31], v[162:165], v[230:233], v[28:31]
	v_mfma_f32_16x16x32_bf16 v[24:27], v[190:193], v[230:233], v[24:27]
	v_mfma_f32_16x16x32_bf16 v[12:15], v[162:165], v[238:241], v[12:15]
	v_mfma_f32_16x16x32_bf16 v[8:11], v[190:193], v[238:241], v[8:11]
	s_setprio 0
	s_setprio 1
	v_mfma_f32_16x16x32_bf16 v[52:55], v[194:197], v[210:213], v[52:55]
	s_add_u32 s33, s33, 0x100
	s_addc_u32 s49, s49, 0
	v_mfma_f32_16x16x32_bf16 v[48:51], v[202:205], v[210:213], v[48:51]
	s_add_u32 s4, s4, 0x100
	s_addc_u32 s5, s5, 0
	v_mfma_f32_16x16x32_bf16 v[36:39], v[194:197], v[218:221], v[36:39]
	s_cmp_ge_i32 s46, s22
	s_mov_b32 s6, s46
	s_cbranch_scc1 .Lmy_kx12
	v_mfma_f32_16x16x32_bf16 v[32:35], v[202:205], v[218:221], v[32:35]
	s_add_i32 s46, s6, 2
	v_mfma_f32_16x16x32_bf16 v[20:23], v[194:197], v[226:229], v[20:23]
	s_add_u32 s47, s4, 0x80
	v_mfma_f32_16x16x32_bf16 v[16:19], v[202:205], v[226:229], v[16:19]
	s_addc_u32 s7, s5, 0
	v_mfma_f32_16x16x32_bf16 v[4:7], v[194:197], v[234:237], v[4:7]
	s_add_i32 s53, 0, 0x10000
	v_mfma_f32_16x16x32_bf16 v[0:3], v[202:205], v[234:237], v[0:3]
	s_cmp_eq_u32 s23, s6
	v_mfma_f32_16x16x32_bf16 v[52:55], v[198:201], v[214:217], v[52:55]
	s_cselect_b32 s7, s31, s7
	v_mfma_f32_16x16x32_bf16 v[48:51], v[206:209], v[214:217], v[48:51]
	s_cselect_b32 s6, s30, s47
	v_mfma_f32_16x16x32_bf16 v[36:39], v[198:201], v[222:225], v[36:39]
	v_add_u32_e32 v142, s53, v159
	v_mfma_f32_16x16x32_bf16 v[32:35], v[206:209], v[222:225], v[32:35]
	s_cselect_b32 s51, s35, s49
	v_mfma_f32_16x16x32_bf16 v[20:23], v[198:201], v[230:233], v[20:23]
	s_cselect_b32 s50, s34, s33
	v_mfma_f32_16x16x32_bf16 v[16:19], v[206:209], v[230:233], v[16:19]
	s_add_i32 s47, 0, 0x14000
	v_mfma_f32_16x16x32_bf16 v[4:7], v[198:201], v[238:241], v[4:7]
	v_mfma_f32_16x16x32_bf16 v[0:3], v[206:209], v[238:241], v[0:3]
	s_setprio 0
	s_barrier
	s_branch .Lmy_kh12
.Lmy_kx12:
	v_mfma_f32_16x16x32_bf16 v[32:35], v[202:205], v[218:221], v[32:35]
	v_mfma_f32_16x16x32_bf16 v[20:23], v[194:197], v[226:229], v[20:23]
	v_mfma_f32_16x16x32_bf16 v[16:19], v[202:205], v[226:229], v[16:19]
	v_mfma_f32_16x16x32_bf16 v[4:7], v[194:197], v[234:237], v[4:7]
	v_mfma_f32_16x16x32_bf16 v[0:3], v[202:205], v[234:237], v[0:3]
	v_mfma_f32_16x16x32_bf16 v[52:55], v[198:201], v[214:217], v[52:55]
	v_mfma_f32_16x16x32_bf16 v[48:51], v[206:209], v[214:217], v[48:51]
	v_mfma_f32_16x16x32_bf16 v[36:39], v[198:201], v[222:225], v[36:39]
	v_mfma_f32_16x16x32_bf16 v[32:35], v[206:209], v[222:225], v[32:35]
	v_mfma_f32_16x16x32_bf16 v[20:23], v[198:201], v[230:233], v[20:23]
	v_mfma_f32_16x16x32_bf16 v[16:19], v[206:209], v[230:233], v[16:19]
	v_mfma_f32_16x16x32_bf16 v[4:7], v[198:201], v[238:241], v[4:7]
	v_mfma_f32_16x16x32_bf16 v[0:3], v[206:209], v[238:241], v[0:3]
	s_setprio 0
	s_barrier
	s_movk_i32 s51, 0x200
	s_movk_i32 s33, 0x300
